# sel: score keys kept as raw f32 bit patterns (f2key conversion dropped from the transposes: -208 VALU per unit) and the radix descent done on sign-magnitude (sign plane inverted, remaining planes inve
# speedup vs baseline: 1.0060x; 1.0036x over previous
.LBB0_826:
	s_lshl_b32 s6, s12, 14
	v_and_b32_e32 v99, 63, v106
	s_add_i32 s6, s6, 0
	s_cmpk_lt_u32 s19, 0x101
	v_lshl_add_u32 v190, v99, 2, s6
	s_waitcnt lgkmcnt(0)
	s_barrier
	s_cbranch_scc1 .LBB0_830
	s_waitcnt vmcnt(12)
	ds_read2st64_b32 v[62:63], v190 offset1:1
	ds_read2st64_b32 v[60:61], v190 offset0:2 offset1:3
	ds_read2st64_b32 v[58:59], v190 offset0:4 offset1:5
	ds_read2st64_b32 v[56:57], v190 offset0:6 offset1:7
	s_waitcnt vmcnt(0)
	ds_read2st64_b32 v[54:55], v190 offset0:8 offset1:9
	ds_read2st64_b32 v[52:53], v190 offset0:10 offset1:11
	ds_read2st64_b32 v[50:51], v190 offset0:12 offset1:13
	ds_read2st64_b32 v[48:49], v190 offset0:14 offset1:15
	ds_read2st64_b32 v[46:47], v190 offset0:16 offset1:17
	ds_read2st64_b32 v[44:45], v190 offset0:18 offset1:19
	ds_read2st64_b32 v[42:43], v190 offset0:20 offset1:21
	ds_read2st64_b32 v[40:41], v190 offset0:22 offset1:23
	ds_read2st64_b32 v[38:39], v190 offset0:24 offset1:25
	ds_read2st64_b32 v[36:37], v190 offset0:26 offset1:27
	ds_read2st64_b32 v[34:35], v190 offset0:28 offset1:29
	ds_read2st64_b32 v[32:33], v190 offset0:30 offset1:31
	v_mov_b32_e32 v186, 0
	s_cmpk_lt_u32 s19, 0x801
	v_mov_b32_e32 v185, 0
	v_mov_b32_e32 v183, 0
	v_mov_b32_e32 v161, 0
	v_mov_b32_e32 v159, 0
	v_mov_b32_e32 v157, 0
	v_mov_b32_e32 v155, 0
	v_mov_b32_e32 v153, 0
	v_mov_b32_e32 v151, 0
	v_mov_b32_e32 v149, 0
	v_mov_b32_e32 v147, 0
	v_mov_b32_e32 v145, 0
	v_mov_b32_e32 v143, 0
	v_mov_b32_e32 v141, 0
	v_mov_b32_e32 v139, 0
	v_mov_b32_e32 v137, 0
	v_mov_b32_e32 v135, 0
	v_mov_b32_e32 v133, 0
	v_mov_b32_e32 v131, 0
	v_mov_b32_e32 v129, 0
	v_mov_b32_e32 v127, 0
	v_mov_b32_e32 v125, 0
	v_mov_b32_e32 v123, 0
	v_mov_b32_e32 v121, 0
	v_mov_b32_e32 v119, 0
	v_mov_b32_e32 v117, 0
	v_mov_b32_e32 v115, 0
	v_mov_b32_e32 v113, 0
	v_mov_b32_e32 v111, 0
	v_mov_b32_e32 v109, 0
	v_mov_b32_e32 v107, 0
	v_mov_b32_e32 v106, 0
	s_cbranch_scc1 .LBB0_829
	ds_read2st64_b32 v[64:65], v190 offset0:32 offset1:33
	ds_read2st64_b32 v[66:67], v190 offset0:34 offset1:35
	ds_read2st64_b32 v[68:69], v190 offset0:36 offset1:37
	ds_read2st64_b32 v[70:71], v190 offset0:38 offset1:39
	s_waitcnt lgkmcnt(3)
	v_mov_b32_e32 v72, v64
	s_waitcnt lgkmcnt(2)
	v_mov_b32_e32 v74, v66
	v_mov_b32_e32 v75, v67
	s_waitcnt lgkmcnt(1)
	v_mov_b32_e32 v76, v68
	v_mov_b32_e32 v77, v69
	s_waitcnt lgkmcnt(0)
	v_mov_b32_e32 v73, v65
	v_mov_b32_e32 v78, v70
	ds_read2st64_b32 v[64:65], v190 offset0:40 offset1:41
	v_mov_b32_e32 v79, v71
	ds_read2st64_b32 v[66:67], v190 offset0:42 offset1:43
	ds_read2st64_b32 v[68:69], v190 offset0:44 offset1:45
	ds_read2st64_b32 v[70:71], v190 offset0:46 offset1:47
	s_waitcnt lgkmcnt(3)
	v_mov_b32_e32 v80, v64
	v_mov_b32_e32 v81, v65
	s_waitcnt lgkmcnt(2)
	v_mov_b32_e32 v82, v66
	v_mov_b32_e32 v83, v67
	s_waitcnt lgkmcnt(1)
	v_mov_b32_e32 v84, v68
	v_mov_b32_e32 v85, v69
	s_waitcnt lgkmcnt(0)
	v_mov_b32_e32 v86, v70
	ds_read2st64_b32 v[64:65], v190 offset0:48 offset1:49
	v_mov_b32_e32 v87, v71
	ds_read2st64_b32 v[66:67], v190 offset0:50 offset1:51
	ds_read2st64_b32 v[68:69], v190 offset0:52 offset1:53
	ds_read2st64_b32 v[70:71], v190 offset0:54 offset1:55
	s_waitcnt lgkmcnt(3)
	v_mov_b32_e32 v88, v64
	v_mov_b32_e32 v89, v65
	s_waitcnt lgkmcnt(2)
	v_mov_b32_e32 v90, v66
	v_mov_b32_e32 v91, v67
	s_waitcnt lgkmcnt(1)
	v_mov_b32_e32 v92, v68
	v_mov_b32_e32 v93, v69
	s_waitcnt lgkmcnt(0)
	v_mov_b32_e32 v94, v70
	ds_read2st64_b32 v[64:65], v190 offset0:56 offset1:57
	v_mov_b32_e32 v95, v71
	ds_read2st64_b32 v[66:67], v190 offset0:58 offset1:59
	ds_read2st64_b32 v[68:69], v190 offset0:60 offset1:61
	ds_read2st64_b32 v[70:71], v190 offset0:62 offset1:63
	v_perm_b32 v103, v89, v73, s37
	s_waitcnt lgkmcnt(3)
	s_waitcnt lgkmcnt(2)
	s_waitcnt lgkmcnt(1)
	s_waitcnt lgkmcnt(0)
	v_perm_b32 v73, v89, v73, s36
	v_perm_b32 v89, v90, v74, s37
	v_perm_b32 v74, v90, v74, s36
	v_perm_b32 v90, v91, v75, s37
	v_perm_b32 v75, v91, v75, s36
	v_perm_b32 v91, v92, v76, s37
	v_perm_b32 v106, v65, v81, s37
	v_perm_b32 v65, v65, v81, s36
	v_perm_b32 v81, v66, v82, s37
	v_perm_b32 v66, v66, v82, s36
	v_perm_b32 v82, v67, v83, s37
	v_perm_b32 v67, v67, v83, s36
	v_perm_b32 v83, v68, v84, s37
	v_perm_b32 v102, v88, v72, s36
	v_perm_b32 v76, v92, v76, s36
	v_perm_b32 v92, v93, v77, s37
	v_perm_b32 v77, v93, v77, s36
	v_perm_b32 v93, v94, v78, s37
	v_perm_b32 v78, v94, v78, s36
	v_perm_b32 v94, v95, v79, s37
	v_perm_b32 v79, v95, v79, s36
	v_perm_b32 v95, v64, v80, s36
	v_perm_b32 v68, v68, v84, s36
	v_perm_b32 v84, v69, v85, s37
	v_perm_b32 v69, v69, v85, s36
	v_perm_b32 v85, v70, v86, s37
	v_perm_b32 v70, v70, v86, s36
	v_perm_b32 v86, v71, v87, s37
	v_perm_b32 v71, v71, v87, s36
	v_perm_b32 v64, v64, v80, s37
	v_perm_b32 v72, v88, v72, s37
	v_perm_b32 v88, v81, v89, s38
	v_perm_b32 v81, v81, v89, s39
	v_perm_b32 v89, v82, v90, s38
	v_perm_b32 v82, v82, v90, s39
	v_perm_b32 v90, v83, v91, s38
	v_perm_b32 v80, v64, v72, s38
	v_perm_b32 v83, v83, v91, s39
	v_perm_b32 v91, v84, v92, s38
	v_perm_b32 v84, v84, v92, s39
	v_perm_b32 v92, v85, v93, s38
	v_perm_b32 v85, v85, v93, s39
	v_perm_b32 v93, v86, v94, s38
	v_perm_b32 v86, v86, v94, s39
	v_perm_b32 v94, v95, v102, s38
	v_perm_b32 v95, v95, v102, s39
	v_perm_b32 v102, v65, v73, s38
	v_perm_b32 v65, v65, v73, s39
	v_perm_b32 v73, v66, v74, s38
	v_perm_b32 v66, v66, v74, s39
	v_perm_b32 v74, v67, v75, s38
	v_perm_b32 v67, v67, v75, s39
	v_perm_b32 v75, v68, v76, s38
	v_perm_b32 v68, v68, v76, s39
	v_perm_b32 v76, v69, v77, s38
	v_perm_b32 v69, v69, v77, s39
	v_perm_b32 v77, v70, v78, s38
	v_perm_b32 v70, v70, v78, s39
	v_perm_b32 v78, v71, v79, s38
	v_perm_b32 v71, v71, v79, s39
	v_lshlrev_b32_e32 v79, 4, v90
	v_bfi_b32 v79, s44, v79, v80
	v_lshrrev_b32_e32 v80, 4, v80
	v_perm_b32 v64, v64, v72, s39
	v_perm_b32 v72, v106, v103, s38
	v_bfi_b32 v80, s44, v90, v80
	v_lshlrev_b32_e32 v90, 4, v91
	v_bfi_b32 v90, s44, v90, v72
	v_lshrrev_b32_e32 v72, 4, v72
	v_bfi_b32 v72, s44, v91, v72
	v_lshlrev_b32_e32 v91, 4, v92
	v_bfi_b32 v91, s44, v91, v88
	v_lshrrev_b32_e32 v88, 4, v88
	v_bfi_b32 v88, s44, v92, v88
	v_lshlrev_b32_e32 v92, 4, v93
	v_bfi_b32 v92, s44, v92, v89
	v_lshrrev_b32_e32 v89, 4, v89
	v_bfi_b32 v89, s44, v93, v89
	v_lshlrev_b32_e32 v93, 4, v83
	v_bfi_b32 v93, s44, v93, v64
	v_lshrrev_b32_e32 v64, 4, v64
	v_perm_b32 v87, v106, v103, s39
	v_bfi_b32 v64, s44, v83, v64
	v_lshlrev_b32_e32 v83, 4, v84
	v_bfi_b32 v83, s44, v83, v87
	v_lshrrev_b32_e32 v87, 4, v87
	v_bfi_b32 v84, s44, v84, v87
	v_lshlrev_b32_e32 v87, 4, v85
	v_bfi_b32 v87, s44, v87, v81
	v_lshrrev_b32_e32 v81, 4, v81
	v_bfi_b32 v81, s44, v85, v81
	v_lshlrev_b32_e32 v85, 4, v86
	v_bfi_b32 v85, s44, v85, v82
	v_lshrrev_b32_e32 v82, 4, v82
	v_bfi_b32 v82, s44, v86, v82
	v_lshlrev_b32_e32 v86, 4, v75
	v_bfi_b32 v86, s44, v86, v94
	v_lshrrev_b32_e32 v94, 4, v94
	v_bfi_b32 v75, s44, v75, v94
	v_lshlrev_b32_e32 v94, 4, v76
	v_bfi_b32 v94, s44, v94, v102
	v_lshrrev_b32_e32 v102, 4, v102
	v_bfi_b32 v76, s44, v76, v102
	v_lshlrev_b32_e32 v102, 4, v77
	v_bfi_b32 v102, s44, v102, v73
	v_lshrrev_b32_e32 v73, 4, v73
	v_bfi_b32 v73, s44, v77, v73
	v_lshlrev_b32_e32 v77, 4, v78
	v_bfi_b32 v77, s44, v77, v74
	v_lshrrev_b32_e32 v74, 4, v74
	v_bfi_b32 v74, s44, v78, v74
	v_lshlrev_b32_e32 v78, 4, v68
	v_bfi_b32 v78, s44, v78, v95
	v_lshrrev_b32_e32 v95, 4, v95
	v_bfi_b32 v68, s44, v68, v95
	v_lshlrev_b32_e32 v95, 4, v69
	v_bfi_b32 v95, s44, v95, v65
	v_lshrrev_b32_e32 v65, 4, v65
	v_bfi_b32 v65, s44, v69, v65
	v_lshlrev_b32_e32 v69, 4, v70
	v_bfi_b32 v69, s44, v69, v66
	v_lshrrev_b32_e32 v66, 4, v66
	v_bfi_b32 v66, s44, v70, v66
	v_lshlrev_b32_e32 v70, 4, v71
	v_bfi_b32 v70, s44, v70, v67
	v_lshrrev_b32_e32 v67, 4, v67
	v_bfi_b32 v67, s44, v71, v67
	v_lshlrev_b32_e32 v71, 2, v91
	v_bfi_b32 v71, s45, v71, v79
	v_lshrrev_b32_e32 v79, 2, v79
	v_bfi_b32 v79, s45, v91, v79
	v_lshlrev_b32_e32 v91, 2, v92
	v_bfi_b32 v91, s45, v91, v90
	v_lshrrev_b32_e32 v90, 2, v90
	v_bfi_b32 v90, s45, v92, v90
	v_lshlrev_b32_e32 v92, 2, v88
	v_bfi_b32 v92, s45, v92, v80
	v_lshrrev_b32_e32 v80, 2, v80
	v_bfi_b32 v80, s45, v88, v80
	v_lshlrev_b32_e32 v88, 2, v89
	v_bfi_b32 v88, s45, v88, v72
	v_lshrrev_b32_e32 v72, 2, v72
	v_bfi_b32 v72, s45, v89, v72
	v_lshlrev_b32_e32 v89, 2, v87
	v_bfi_b32 v89, s45, v89, v93
	v_lshrrev_b32_e32 v93, 2, v93
	v_bfi_b32 v87, s45, v87, v93
	v_lshlrev_b32_e32 v93, 2, v85
	v_bfi_b32 v93, s45, v93, v83
	v_lshrrev_b32_e32 v83, 2, v83
	v_bfi_b32 v83, s45, v85, v83
	v_lshlrev_b32_e32 v85, 2, v81
	v_bfi_b32 v85, s45, v85, v64
	v_lshrrev_b32_e32 v64, 2, v64
	v_bfi_b32 v64, s45, v81, v64
	v_lshlrev_b32_e32 v81, 2, v82
	v_bfi_b32 v81, s45, v81, v84
	v_lshrrev_b32_e32 v84, 2, v84
	v_bfi_b32 v82, s45, v82, v84
	v_lshlrev_b32_e32 v84, 2, v102
	v_bfi_b32 v84, s45, v84, v86
	v_lshrrev_b32_e32 v86, 2, v86
	v_bfi_b32 v86, s45, v102, v86
	v_lshlrev_b32_e32 v102, 2, v77
	v_bfi_b32 v102, s45, v102, v94
	v_lshrrev_b32_e32 v94, 2, v94
	v_bfi_b32 v77, s45, v77, v94
	v_lshlrev_b32_e32 v94, 2, v73
	v_bfi_b32 v94, s45, v94, v75
	v_lshrrev_b32_e32 v75, 2, v75
	v_bfi_b32 v73, s45, v73, v75
	v_lshlrev_b32_e32 v75, 2, v74
	v_bfi_b32 v75, s45, v75, v76
	v_lshrrev_b32_e32 v76, 2, v76
	v_bfi_b32 v74, s45, v74, v76
	v_lshlrev_b32_e32 v76, 2, v69
	v_bfi_b32 v76, s45, v76, v78
	v_lshrrev_b32_e32 v78, 2, v78
	v_bfi_b32 v69, s45, v69, v78
	v_lshlrev_b32_e32 v78, 2, v70
	v_bfi_b32 v78, s45, v78, v95
	v_lshrrev_b32_e32 v95, 2, v95
	v_bfi_b32 v70, s45, v70, v95
	v_lshlrev_b32_e32 v95, 2, v66
	v_bfi_b32 v95, s45, v95, v68
	v_lshrrev_b32_e32 v68, 2, v68
	v_bfi_b32 v66, s45, v66, v68
	v_lshlrev_b32_e32 v68, 2, v67
	v_bfi_b32 v68, s45, v68, v65
	v_lshrrev_b32_e32 v65, 2, v65
	v_bfi_b32 v65, s45, v67, v65
	v_lshlrev_b32_e32 v67, 1, v91
	v_bfi_b32 v106, s46, v67, v71
	v_lshrrev_b32_e32 v67, 1, v71
	v_bfi_b32 v107, s47, v67, v91
	v_lshlrev_b32_e32 v67, 1, v90
	v_bfi_b32 v109, s46, v67, v79
	v_lshrrev_b32_e32 v67, 1, v79
	v_bfi_b32 v111, s47, v67, v90
	v_lshlrev_b32_e32 v67, 1, v88
	v_bfi_b32 v113, s46, v67, v92
	v_lshrrev_b32_e32 v67, 1, v92
	v_bfi_b32 v115, s47, v67, v88
	v_lshlrev_b32_e32 v67, 1, v72
	v_bfi_b32 v117, s46, v67, v80
	v_lshrrev_b32_e32 v67, 1, v80
	v_bfi_b32 v119, s47, v67, v72
	v_lshlrev_b32_e32 v67, 1, v93
	v_bfi_b32 v121, s46, v67, v89
	v_lshrrev_b32_e32 v67, 1, v89
	v_bfi_b32 v123, s47, v67, v93
	v_lshlrev_b32_e32 v67, 1, v83
	v_bfi_b32 v125, s46, v67, v87
	v_lshrrev_b32_e32 v67, 1, v87
	v_bfi_b32 v127, s47, v67, v83
	v_lshlrev_b32_e32 v67, 1, v81
	v_bfi_b32 v129, s46, v67, v85
	v_lshrrev_b32_e32 v67, 1, v85
	v_bfi_b32 v131, s47, v67, v81
	v_lshlrev_b32_e32 v67, 1, v82
	v_bfi_b32 v133, s46, v67, v64
	v_lshrrev_b32_e32 v64, 1, v64
	v_bfi_b32 v135, s47, v64, v82
	v_lshlrev_b32_e32 v64, 1, v102
	v_bfi_b32 v137, s46, v64, v84
	v_lshrrev_b32_e32 v64, 1, v84
	v_bfi_b32 v139, s47, v64, v102
	v_lshlrev_b32_e32 v64, 1, v77
	v_bfi_b32 v141, s46, v64, v86
	v_lshrrev_b32_e32 v64, 1, v86
	v_bfi_b32 v143, s47, v64, v77
	v_lshlrev_b32_e32 v64, 1, v75
	v_bfi_b32 v145, s46, v64, v94
	v_lshrrev_b32_e32 v64, 1, v94
	v_bfi_b32 v147, s47, v64, v75
	v_lshlrev_b32_e32 v64, 1, v74
	v_bfi_b32 v149, s46, v64, v73
	v_lshrrev_b32_e32 v64, 1, v73
	v_bfi_b32 v151, s47, v64, v74
	v_lshlrev_b32_e32 v64, 1, v78
	v_bfi_b32 v153, s46, v64, v76
	v_lshrrev_b32_e32 v64, 1, v76
	v_bfi_b32 v155, s47, v64, v78
	v_lshlrev_b32_e32 v64, 1, v70
	v_bfi_b32 v157, s46, v64, v69
	v_lshrrev_b32_e32 v64, 1, v69
	v_bfi_b32 v159, s47, v64, v70
	v_lshlrev_b32_e32 v64, 1, v68
	v_bfi_b32 v161, s46, v64, v95
	v_lshrrev_b32_e32 v64, 1, v95
	v_bfi_b32 v183, s47, v64, v68
	v_lshlrev_b32_e32 v64, 1, v65
	v_bfi_b32 v185, s46, v64, v66
	v_lshrrev_b32_e32 v64, 1, v66
	v_bfi_b32 v186, s47, v64, v65
.LBB0_829:
	s_waitcnt lgkmcnt(14)
	s_waitcnt lgkmcnt(13)
	s_waitcnt lgkmcnt(12)
	s_waitcnt lgkmcnt(11)
	s_waitcnt lgkmcnt(10)
	s_waitcnt lgkmcnt(9)
	s_waitcnt lgkmcnt(8)
	s_waitcnt lgkmcnt(7)
	s_waitcnt lgkmcnt(6)
	s_waitcnt lgkmcnt(5)
	s_waitcnt lgkmcnt(4)
	s_waitcnt lgkmcnt(3)
	s_waitcnt lgkmcnt(2)
	s_waitcnt lgkmcnt(1)
	s_waitcnt lgkmcnt(0)
	v_perm_b32 v65, v47, v63, s37
	v_perm_b32 v47, v47, v63, s36
	v_perm_b32 v63, v44, v60, s37
	v_perm_b32 v44, v44, v60, s36
	v_perm_b32 v60, v45, v61, s37
	v_perm_b32 v45, v45, v61, s36
	v_perm_b32 v61, v42, v58, s37
	v_perm_b32 v66, v39, v55, s37
	v_perm_b32 v39, v39, v55, s36
	v_perm_b32 v55, v36, v52, s37
	v_perm_b32 v36, v36, v52, s36
	v_perm_b32 v52, v37, v53, s37
	v_perm_b32 v37, v37, v53, s36
	v_perm_b32 v53, v34, v50, s37
	v_perm_b32 v64, v46, v62, s36
	v_perm_b32 v42, v42, v58, s36
	v_perm_b32 v58, v43, v59, s37
	v_perm_b32 v43, v43, v59, s36
	v_perm_b32 v59, v40, v56, s37
	v_perm_b32 v40, v40, v56, s36
	v_perm_b32 v56, v41, v57, s37
	v_perm_b32 v41, v41, v57, s36
	v_perm_b32 v57, v38, v54, s36
	v_perm_b32 v34, v34, v50, s36
	v_perm_b32 v50, v35, v51, s37
	v_perm_b32 v35, v35, v51, s36
	v_perm_b32 v51, v32, v48, s37
	v_perm_b32 v32, v32, v48, s36
	v_perm_b32 v48, v33, v49, s37
	v_perm_b32 v33, v33, v49, s36
	v_perm_b32 v38, v38, v54, s37
	v_perm_b32 v46, v46, v62, s37
	v_perm_b32 v62, v55, v63, s38
	v_perm_b32 v55, v55, v63, s39
	v_perm_b32 v63, v52, v60, s38
	v_perm_b32 v52, v52, v60, s39
	v_perm_b32 v60, v53, v61, s38
	v_perm_b32 v49, v38, v46, s38
	v_perm_b32 v53, v53, v61, s39
	v_perm_b32 v61, v50, v58, s38
	v_perm_b32 v50, v50, v58, s39
	v_perm_b32 v58, v51, v59, s38
	v_perm_b32 v51, v51, v59, s39
	v_perm_b32 v59, v48, v56, s38
	v_perm_b32 v48, v48, v56, s39
	v_perm_b32 v56, v57, v64, s38
	v_perm_b32 v57, v57, v64, s39
	v_perm_b32 v64, v39, v47, s38
	v_perm_b32 v39, v39, v47, s39
	v_perm_b32 v47, v36, v44, s38
	v_perm_b32 v36, v36, v44, s39
	v_perm_b32 v44, v37, v45, s38
	v_perm_b32 v37, v37, v45, s39
	v_perm_b32 v45, v34, v42, s38
	v_perm_b32 v34, v34, v42, s39
	v_perm_b32 v42, v35, v43, s38
	v_perm_b32 v35, v35, v43, s39
	v_perm_b32 v43, v32, v40, s38
	v_perm_b32 v32, v32, v40, s39
	v_perm_b32 v40, v33, v41, s38
	v_perm_b32 v33, v33, v41, s39
	v_lshlrev_b32_e32 v41, 4, v60
	v_bfi_b32 v41, s44, v41, v49
	v_lshrrev_b32_e32 v49, 4, v49
	v_perm_b32 v38, v38, v46, s39
	v_perm_b32 v46, v66, v65, s38
	v_bfi_b32 v49, s44, v60, v49
	v_lshlrev_b32_e32 v60, 4, v61
	v_bfi_b32 v60, s44, v60, v46
	v_lshrrev_b32_e32 v46, 4, v46
	v_bfi_b32 v46, s44, v61, v46
	v_lshlrev_b32_e32 v61, 4, v58
	v_bfi_b32 v61, s44, v61, v62
	v_lshrrev_b32_e32 v62, 4, v62
	v_bfi_b32 v58, s44, v58, v62
	v_lshlrev_b32_e32 v62, 4, v59
	v_bfi_b32 v62, s44, v62, v63
	v_lshrrev_b32_e32 v63, 4, v63
	v_bfi_b32 v59, s44, v59, v63
	v_lshlrev_b32_e32 v63, 4, v53
	v_bfi_b32 v63, s44, v63, v38
	v_lshrrev_b32_e32 v38, 4, v38
	v_perm_b32 v54, v66, v65, s39
	v_bfi_b32 v38, s44, v53, v38
	v_lshlrev_b32_e32 v53, 4, v50
	v_bfi_b32 v53, s44, v53, v54
	v_lshrrev_b32_e32 v54, 4, v54
	v_bfi_b32 v50, s44, v50, v54
	v_lshlrev_b32_e32 v54, 4, v51
	v_bfi_b32 v54, s44, v54, v55
	v_lshrrev_b32_e32 v55, 4, v55
	v_bfi_b32 v51, s44, v51, v55
	v_lshlrev_b32_e32 v55, 4, v48
	v_bfi_b32 v55, s44, v55, v52
	v_lshrrev_b32_e32 v52, 4, v52
	v_bfi_b32 v48, s44, v48, v52
	v_lshlrev_b32_e32 v52, 4, v45
	v_bfi_b32 v52, s44, v52, v56
	v_lshrrev_b32_e32 v56, 4, v56
	v_bfi_b32 v45, s44, v45, v56
	v_lshlrev_b32_e32 v56, 4, v42
	v_bfi_b32 v56, s44, v56, v64
	v_lshrrev_b32_e32 v64, 4, v64
	v_bfi_b32 v42, s44, v42, v64
	v_lshlrev_b32_e32 v64, 4, v43
	v_bfi_b32 v64, s44, v64, v47
	v_lshrrev_b32_e32 v47, 4, v47
	v_bfi_b32 v43, s44, v43, v47
	v_lshlrev_b32_e32 v47, 4, v40
	v_bfi_b32 v47, s44, v47, v44
	v_lshrrev_b32_e32 v44, 4, v44
	v_bfi_b32 v40, s44, v40, v44
	v_lshlrev_b32_e32 v44, 4, v34
	v_bfi_b32 v44, s44, v44, v57
	v_lshrrev_b32_e32 v57, 4, v57
	v_bfi_b32 v34, s44, v34, v57
	v_lshlrev_b32_e32 v57, 4, v35
	v_bfi_b32 v57, s44, v57, v39
	v_lshrrev_b32_e32 v39, 4, v39
	v_bfi_b32 v35, s44, v35, v39
	v_lshlrev_b32_e32 v39, 4, v32
	v_bfi_b32 v39, s44, v39, v36
	v_lshrrev_b32_e32 v36, 4, v36
	v_bfi_b32 v32, s44, v32, v36
	v_lshlrev_b32_e32 v36, 4, v33
	v_bfi_b32 v36, s44, v36, v37
	v_lshrrev_b32_e32 v37, 4, v37
	v_bfi_b32 v33, s44, v33, v37
	v_lshlrev_b32_e32 v37, 2, v61
	v_bfi_b32 v37, s45, v37, v41
	v_lshrrev_b32_e32 v41, 2, v41
	v_bfi_b32 v41, s45, v61, v41
	v_lshlrev_b32_e32 v61, 2, v62
	v_bfi_b32 v61, s45, v61, v60
	v_lshrrev_b32_e32 v60, 2, v60
	v_bfi_b32 v60, s45, v62, v60
	v_lshlrev_b32_e32 v62, 2, v58
	v_bfi_b32 v62, s45, v62, v49
	v_lshrrev_b32_e32 v49, 2, v49
	v_bfi_b32 v49, s45, v58, v49
	v_lshlrev_b32_e32 v58, 2, v59
	v_bfi_b32 v58, s45, v58, v46
	v_lshrrev_b32_e32 v46, 2, v46
	v_bfi_b32 v46, s45, v59, v46
	v_lshlrev_b32_e32 v59, 2, v54
	v_bfi_b32 v59, s45, v59, v63
	v_lshrrev_b32_e32 v63, 2, v63
	v_bfi_b32 v54, s45, v54, v63
	v_lshlrev_b32_e32 v63, 2, v55
	v_bfi_b32 v63, s45, v63, v53
	v_lshrrev_b32_e32 v53, 2, v53
	v_bfi_b32 v53, s45, v55, v53
	v_lshlrev_b32_e32 v55, 2, v51
	v_bfi_b32 v55, s45, v55, v38
	v_lshrrev_b32_e32 v38, 2, v38
	v_bfi_b32 v38, s45, v51, v38
	v_lshlrev_b32_e32 v51, 2, v48
	v_bfi_b32 v51, s45, v51, v50
	v_lshrrev_b32_e32 v50, 2, v50
	v_bfi_b32 v48, s45, v48, v50
	v_lshlrev_b32_e32 v50, 2, v64
	v_bfi_b32 v50, s45, v50, v52
	v_lshrrev_b32_e32 v52, 2, v52
	v_bfi_b32 v52, s45, v64, v52
	v_lshlrev_b32_e32 v64, 2, v47
	v_bfi_b32 v64, s45, v64, v56
	v_lshrrev_b32_e32 v56, 2, v56
	v_bfi_b32 v47, s45, v47, v56
	v_lshlrev_b32_e32 v56, 2, v43
	v_bfi_b32 v56, s45, v56, v45
	v_lshrrev_b32_e32 v45, 2, v45
	v_bfi_b32 v43, s45, v43, v45
	v_lshlrev_b32_e32 v45, 2, v40
	v_bfi_b32 v45, s45, v45, v42
	v_lshrrev_b32_e32 v42, 2, v42
	v_bfi_b32 v40, s45, v40, v42
	v_lshlrev_b32_e32 v42, 2, v39
	v_bfi_b32 v42, s45, v42, v44
	v_lshrrev_b32_e32 v44, 2, v44
	v_bfi_b32 v39, s45, v39, v44
	v_lshlrev_b32_e32 v44, 2, v36
	v_bfi_b32 v44, s45, v44, v57
	v_lshrrev_b32_e32 v57, 2, v57
	v_bfi_b32 v36, s45, v36, v57
	v_lshlrev_b32_e32 v57, 2, v32
	v_bfi_b32 v57, s45, v57, v34
	v_lshrrev_b32_e32 v34, 2, v34
	v_bfi_b32 v32, s45, v32, v34
	v_lshlrev_b32_e32 v34, 2, v33
	v_bfi_b32 v34, s45, v34, v35
	v_lshrrev_b32_e32 v35, 2, v35
	v_bfi_b32 v33, s45, v33, v35
	v_lshlrev_b32_e32 v35, 1, v61
	v_bfi_b32 v108, s46, v35, v37
	v_lshrrev_b32_e32 v35, 1, v37
	v_bfi_b32 v110, s47, v35, v61
	v_lshlrev_b32_e32 v35, 1, v60
	v_bfi_b32 v112, s46, v35, v41
	v_lshrrev_b32_e32 v35, 1, v41
	v_bfi_b32 v114, s47, v35, v60
	v_lshlrev_b32_e32 v35, 1, v58
	v_bfi_b32 v116, s46, v35, v62
	v_lshrrev_b32_e32 v35, 1, v62
	v_bfi_b32 v118, s47, v35, v58
	v_lshlrev_b32_e32 v35, 1, v46
	v_bfi_b32 v120, s46, v35, v49
	v_lshrrev_b32_e32 v35, 1, v49
	v_bfi_b32 v122, s47, v35, v46
	v_lshlrev_b32_e32 v35, 1, v63
	v_bfi_b32 v124, s46, v35, v59
	v_lshrrev_b32_e32 v35, 1, v59
	v_bfi_b32 v126, s47, v35, v63
	v_lshlrev_b32_e32 v35, 1, v53
	v_bfi_b32 v128, s46, v35, v54
	v_lshrrev_b32_e32 v35, 1, v54
	v_bfi_b32 v130, s47, v35, v53
	v_lshlrev_b32_e32 v35, 1, v51
	v_bfi_b32 v132, s46, v35, v55
	v_lshrrev_b32_e32 v35, 1, v55
	v_bfi_b32 v134, s47, v35, v51
	v_lshlrev_b32_e32 v35, 1, v48
	v_bfi_b32 v136, s46, v35, v38
	v_lshrrev_b32_e32 v35, 1, v38
	v_bfi_b32 v138, s47, v35, v48
	v_lshlrev_b32_e32 v35, 1, v64
	v_bfi_b32 v140, s46, v35, v50
	v_lshrrev_b32_e32 v35, 1, v50
	v_bfi_b32 v142, s47, v35, v64
	v_lshlrev_b32_e32 v35, 1, v47
	v_bfi_b32 v144, s46, v35, v52
	v_lshrrev_b32_e32 v35, 1, v52
	v_bfi_b32 v146, s47, v35, v47
	v_lshlrev_b32_e32 v35, 1, v45
	v_bfi_b32 v148, s46, v35, v56
	v_lshrrev_b32_e32 v35, 1, v56
	v_bfi_b32 v150, s47, v35, v45
	v_lshlrev_b32_e32 v35, 1, v40
	v_bfi_b32 v152, s46, v35, v43
	v_lshrrev_b32_e32 v35, 1, v43
	v_bfi_b32 v154, s47, v35, v40
	v_lshlrev_b32_e32 v35, 1, v44
	v_bfi_b32 v156, s46, v35, v42
	v_lshrrev_b32_e32 v35, 1, v42
	v_bfi_b32 v158, s47, v35, v44
	v_lshlrev_b32_e32 v35, 1, v36
	v_bfi_b32 v160, s46, v35, v39
	v_lshrrev_b32_e32 v35, 1, v39
	v_bfi_b32 v181, s47, v35, v36
	v_lshlrev_b32_e32 v35, 1, v34
	v_bfi_b32 v184, s46, v35, v57
	v_lshrrev_b32_e32 v35, 1, v57
	v_bfi_b32 v187, s47, v35, v34
	v_lshlrev_b32_e32 v34, 1, v33
	v_bfi_b32 v188, s46, v34, v32
	v_lshrrev_b32_e32 v32, 1, v32
	v_bfi_b32 v189, s47, v32, v33

.LBB0_840:
	s_waitcnt lgkmcnt(0)
	s_barrier
	ds_read2st64_b32 v[30:31], v190 offset1:1
	ds_read2st64_b32 v[28:29], v190 offset0:2 offset1:3
	ds_read2st64_b32 v[26:27], v190 offset0:4 offset1:5
	ds_read2st64_b32 v[24:25], v190 offset0:6 offset1:7
	ds_read2st64_b32 v[22:23], v190 offset0:8 offset1:9
	ds_read2st64_b32 v[20:21], v190 offset0:10 offset1:11
	ds_read2st64_b32 v[18:19], v190 offset0:12 offset1:13
	ds_read2st64_b32 v[16:17], v190 offset0:14 offset1:15
	ds_read2st64_b32 v[14:15], v190 offset0:16 offset1:17
	ds_read2st64_b32 v[12:13], v190 offset0:18 offset1:19
	ds_read2st64_b32 v[10:11], v190 offset0:20 offset1:21
	ds_read2st64_b32 v[8:9], v190 offset0:22 offset1:23
	ds_read2st64_b32 v[6:7], v190 offset0:24 offset1:25
	ds_read2st64_b32 v[4:5], v190 offset0:26 offset1:27
	ds_read2st64_b32 v[2:3], v190 offset0:28 offset1:29
	ds_read2st64_b32 v[0:1], v190 offset0:30 offset1:31
	s_waitcnt vmcnt(4)
	v_mov_b32_e32 v44, 0
	s_cmpk_lt_u32 s19, 0x1801
	v_mov_b32_e32 v43, 0
	v_mov_b32_e32 v41, 0
	v_mov_b32_e32 v39, 0
	v_mov_b32_e32 v37, 0
	v_mov_b32_e32 v35, 0
	v_mov_b32_e32 v33, 0
	v_mov_b32_e32 v32, 0
	v_mov_b32_e32 v46, 0
	s_waitcnt vmcnt(1)
	v_mov_b32_e32 v48, 0
	v_mov_b32_e32 v50, 0
	s_waitcnt vmcnt(0)
	v_mov_b32_e32 v52, 0
	v_mov_b32_e32 v54, 0
	v_mov_b32_e32 v56, 0
	v_mov_b32_e32 v58, 0
	v_mov_b32_e32 v60, 0
	v_mov_b32_e32 v62, 0
	v_mov_b32_e32 v64, 0
	v_mov_b32_e32 v66, 0
	v_mov_b32_e32 v68, 0
	v_mov_b32_e32 v70, 0
	v_mov_b32_e32 v72, 0
	v_mov_b32_e32 v74, 0
	v_mov_b32_e32 v76, 0
	v_mov_b32_e32 v78, 0
	v_mov_b32_e32 v80, 0
	v_mov_b32_e32 v82, 0
	v_mov_b32_e32 v84, 0
	v_mov_b32_e32 v86, 0
	v_mov_b32_e32 v88, 0
	v_mov_b32_e32 v90, 0
	v_mov_b32_e32 v92, 0
	s_cbranch_scc1 .LBB0_842
	ds_read2st64_b32 v[32:33], v190 offset0:32 offset1:33
	ds_read2st64_b32 v[34:35], v190 offset0:34 offset1:35
	ds_read2st64_b32 v[36:37], v190 offset0:36 offset1:37
	ds_read2st64_b32 v[38:39], v190 offset0:38 offset1:39
	s_waitcnt lgkmcnt(3)
	v_mov_b32_e32 v40, v32
	s_waitcnt lgkmcnt(2)
	v_mov_b32_e32 v42, v34
	v_mov_b32_e32 v43, v35
	s_waitcnt lgkmcnt(1)
	v_mov_b32_e32 v44, v36
	v_mov_b32_e32 v45, v37
	s_waitcnt lgkmcnt(0)
	v_mov_b32_e32 v41, v33
	v_mov_b32_e32 v46, v38
	ds_read2st64_b32 v[32:33], v190 offset0:40 offset1:41
	v_mov_b32_e32 v47, v39
	ds_read2st64_b32 v[34:35], v190 offset0:42 offset1:43
	ds_read2st64_b32 v[36:37], v190 offset0:44 offset1:45
	ds_read2st64_b32 v[38:39], v190 offset0:46 offset1:47
	s_waitcnt lgkmcnt(3)
	v_mov_b32_e32 v48, v32
	v_mov_b32_e32 v49, v33
	s_waitcnt lgkmcnt(2)
	v_mov_b32_e32 v50, v34
	v_mov_b32_e32 v51, v35
	s_waitcnt lgkmcnt(1)
	v_mov_b32_e32 v52, v36
	v_mov_b32_e32 v53, v37
	s_waitcnt lgkmcnt(0)
	v_mov_b32_e32 v54, v38
	ds_read2st64_b32 v[32:33], v190 offset0:48 offset1:49
	v_mov_b32_e32 v55, v39
	ds_read2st64_b32 v[34:35], v190 offset0:50 offset1:51
	ds_read2st64_b32 v[36:37], v190 offset0:52 offset1:53
	ds_read2st64_b32 v[38:39], v190 offset0:54 offset1:55
	s_waitcnt lgkmcnt(3)
	v_mov_b32_e32 v56, v32
	v_mov_b32_e32 v57, v33
	s_waitcnt lgkmcnt(2)
	v_mov_b32_e32 v58, v34
	v_mov_b32_e32 v59, v35
	s_waitcnt lgkmcnt(1)
	v_mov_b32_e32 v60, v36
	v_mov_b32_e32 v61, v37
	s_waitcnt lgkmcnt(0)
	v_mov_b32_e32 v62, v38
	ds_read2st64_b32 v[32:33], v190 offset0:56 offset1:57
	v_mov_b32_e32 v63, v39
	ds_read2st64_b32 v[34:35], v190 offset0:58 offset1:59
	ds_read2st64_b32 v[36:37], v190 offset0:60 offset1:61
	ds_read2st64_b32 v[38:39], v190 offset0:62 offset1:63
	v_perm_b32 v65, v57, v41, s37
	s_waitcnt lgkmcnt(3)
	s_waitcnt lgkmcnt(2)
	s_waitcnt lgkmcnt(1)
	s_waitcnt lgkmcnt(0)
	v_perm_b32 v41, v57, v41, s36
	v_perm_b32 v57, v58, v42, s37
	v_perm_b32 v42, v58, v42, s36
	v_perm_b32 v58, v59, v43, s37
	v_perm_b32 v43, v59, v43, s36
	v_perm_b32 v59, v60, v44, s37
	v_perm_b32 v66, v33, v49, s37
	v_perm_b32 v33, v33, v49, s36
	v_perm_b32 v49, v34, v50, s37
	v_perm_b32 v34, v34, v50, s36
	v_perm_b32 v50, v35, v51, s37
	v_perm_b32 v35, v35, v51, s36
	v_perm_b32 v51, v36, v52, s37
	v_perm_b32 v64, v56, v40, s36
	v_perm_b32 v44, v60, v44, s36
	v_perm_b32 v60, v61, v45, s37
	v_perm_b32 v45, v61, v45, s36
	v_perm_b32 v61, v62, v46, s37
	v_perm_b32 v46, v62, v46, s36
	v_perm_b32 v62, v63, v47, s37
	v_perm_b32 v47, v63, v47, s36
	v_perm_b32 v63, v32, v48, s36
	v_perm_b32 v36, v36, v52, s36
	v_perm_b32 v52, v37, v53, s37
	v_perm_b32 v37, v37, v53, s36
	v_perm_b32 v53, v38, v54, s37
	v_perm_b32 v38, v38, v54, s36
	v_perm_b32 v54, v39, v55, s37
	v_perm_b32 v39, v39, v55, s36
	v_perm_b32 v32, v32, v48, s37
	v_perm_b32 v40, v56, v40, s37
	v_perm_b32 v56, v49, v57, s38
	v_perm_b32 v49, v49, v57, s39
	v_perm_b32 v57, v50, v58, s38
	v_perm_b32 v50, v50, v58, s39
	v_perm_b32 v58, v51, v59, s38
	v_perm_b32 v48, v32, v40, s38
	v_perm_b32 v51, v51, v59, s39
	v_perm_b32 v59, v52, v60, s38
	v_perm_b32 v52, v52, v60, s39
	v_perm_b32 v60, v53, v61, s38
	v_perm_b32 v53, v53, v61, s39
	v_perm_b32 v61, v54, v62, s38
	v_perm_b32 v54, v54, v62, s39
	v_perm_b32 v62, v63, v64, s38
	v_perm_b32 v63, v63, v64, s39
	v_perm_b32 v64, v33, v41, s38
	v_perm_b32 v33, v33, v41, s39
	v_perm_b32 v41, v34, v42, s38
	v_perm_b32 v34, v34, v42, s39
	v_perm_b32 v42, v35, v43, s38
	v_perm_b32 v35, v35, v43, s39
	v_perm_b32 v43, v36, v44, s38
	v_perm_b32 v36, v36, v44, s39
	v_perm_b32 v44, v37, v45, s38
	v_perm_b32 v37, v37, v45, s39
	v_perm_b32 v45, v38, v46, s38
	v_perm_b32 v38, v38, v46, s39
	v_perm_b32 v46, v39, v47, s38
	v_perm_b32 v39, v39, v47, s39
	v_lshlrev_b32_e32 v47, 4, v58
	v_bfi_b32 v47, s44, v47, v48
	v_lshrrev_b32_e32 v48, 4, v48
	v_perm_b32 v32, v32, v40, s39
	v_perm_b32 v40, v66, v65, s38
	v_bfi_b32 v48, s44, v58, v48
	v_lshlrev_b32_e32 v58, 4, v59
	v_bfi_b32 v58, s44, v58, v40
	v_lshrrev_b32_e32 v40, 4, v40
	v_bfi_b32 v40, s44, v59, v40
	v_lshlrev_b32_e32 v59, 4, v60
	v_bfi_b32 v59, s44, v59, v56
	v_lshrrev_b32_e32 v56, 4, v56
	v_bfi_b32 v56, s44, v60, v56
	v_lshlrev_b32_e32 v60, 4, v61
	v_bfi_b32 v60, s44, v60, v57
	v_lshrrev_b32_e32 v57, 4, v57
	v_bfi_b32 v57, s44, v61, v57
	v_lshlrev_b32_e32 v61, 4, v51
	v_bfi_b32 v61, s44, v61, v32
	v_lshrrev_b32_e32 v32, 4, v32
	v_perm_b32 v55, v66, v65, s39
	v_bfi_b32 v32, s44, v51, v32
	v_lshlrev_b32_e32 v51, 4, v52
	v_bfi_b32 v51, s44, v51, v55
	v_lshrrev_b32_e32 v55, 4, v55
	v_bfi_b32 v52, s44, v52, v55
	v_lshlrev_b32_e32 v55, 4, v53
	v_bfi_b32 v55, s44, v55, v49
	v_lshrrev_b32_e32 v49, 4, v49
	v_bfi_b32 v49, s44, v53, v49
	v_lshlrev_b32_e32 v53, 4, v54
	v_bfi_b32 v53, s44, v53, v50
	v_lshrrev_b32_e32 v50, 4, v50
	v_bfi_b32 v50, s44, v54, v50
	v_lshlrev_b32_e32 v54, 4, v43
	v_bfi_b32 v54, s44, v54, v62
	v_lshrrev_b32_e32 v62, 4, v62
	v_bfi_b32 v43, s44, v43, v62
	v_lshlrev_b32_e32 v62, 4, v44
	v_bfi_b32 v62, s44, v62, v64
	v_lshrrev_b32_e32 v64, 4, v64
	v_bfi_b32 v44, s44, v44, v64
	v_lshlrev_b32_e32 v64, 4, v45
	v_bfi_b32 v64, s44, v64, v41
	v_lshrrev_b32_e32 v41, 4, v41
	v_bfi_b32 v41, s44, v45, v41
	v_lshlrev_b32_e32 v45, 4, v46
	v_bfi_b32 v45, s44, v45, v42
	v_lshrrev_b32_e32 v42, 4, v42
	v_bfi_b32 v42, s44, v46, v42
	v_lshlrev_b32_e32 v46, 4, v36
	v_bfi_b32 v46, s44, v46, v63
	v_lshrrev_b32_e32 v63, 4, v63
	v_bfi_b32 v36, s44, v36, v63
	v_lshlrev_b32_e32 v63, 4, v37
	v_bfi_b32 v63, s44, v63, v33
	v_lshrrev_b32_e32 v33, 4, v33
	v_bfi_b32 v33, s44, v37, v33
	v_lshlrev_b32_e32 v37, 4, v38
	v_bfi_b32 v37, s44, v37, v34
	v_lshrrev_b32_e32 v34, 4, v34
	v_bfi_b32 v34, s44, v38, v34
	v_lshlrev_b32_e32 v38, 4, v39
	v_bfi_b32 v38, s44, v38, v35
	v_lshrrev_b32_e32 v35, 4, v35
	v_bfi_b32 v35, s44, v39, v35
	v_lshlrev_b32_e32 v39, 2, v59
	v_bfi_b32 v39, s45, v39, v47
	v_lshrrev_b32_e32 v47, 2, v47
	v_bfi_b32 v47, s45, v59, v47
	v_lshlrev_b32_e32 v59, 2, v60
	v_bfi_b32 v59, s45, v59, v58
	v_lshrrev_b32_e32 v58, 2, v58
	v_bfi_b32 v58, s45, v60, v58
	v_lshlrev_b32_e32 v60, 2, v56
	v_bfi_b32 v60, s45, v60, v48
	v_lshrrev_b32_e32 v48, 2, v48
	v_bfi_b32 v48, s45, v56, v48
	v_lshlrev_b32_e32 v56, 2, v57
	v_bfi_b32 v56, s45, v56, v40
	v_lshrrev_b32_e32 v40, 2, v40
	v_bfi_b32 v40, s45, v57, v40
	v_lshlrev_b32_e32 v57, 2, v55
	v_bfi_b32 v57, s45, v57, v61
	v_lshrrev_b32_e32 v61, 2, v61
	v_bfi_b32 v55, s45, v55, v61
	v_lshlrev_b32_e32 v61, 2, v53
	v_bfi_b32 v61, s45, v61, v51
	v_lshrrev_b32_e32 v51, 2, v51
	v_bfi_b32 v51, s45, v53, v51
	v_lshlrev_b32_e32 v53, 2, v49
	v_bfi_b32 v53, s45, v53, v32
	v_lshrrev_b32_e32 v32, 2, v32
	v_bfi_b32 v49, s45, v49, v32
	v_lshlrev_b32_e32 v32, 2, v50
	v_bfi_b32 v65, s45, v32, v52
	v_lshrrev_b32_e32 v32, 2, v52
	v_bfi_b32 v66, s45, v50, v32
	v_lshlrev_b32_e32 v32, 2, v64
	v_bfi_b32 v67, s45, v32, v54
	v_lshrrev_b32_e32 v32, 2, v54
	v_bfi_b32 v68, s45, v64, v32
	v_lshlrev_b32_e32 v32, 2, v45
	v_bfi_b32 v64, s45, v32, v62
	v_lshrrev_b32_e32 v32, 2, v62
	v_bfi_b32 v45, s45, v45, v32
	v_lshlrev_b32_e32 v32, 2, v41
	v_bfi_b32 v69, s45, v32, v43
	v_lshrrev_b32_e32 v32, 2, v43
	v_bfi_b32 v71, s45, v41, v32
	v_lshlrev_b32_e32 v32, 2, v42
	v_bfi_b32 v72, s45, v32, v44
	v_lshrrev_b32_e32 v32, 2, v44
	v_bfi_b32 v42, s45, v42, v32
	v_lshlrev_b32_e32 v32, 2, v37
	v_bfi_b32 v73, s45, v32, v46
	v_lshrrev_b32_e32 v32, 2, v46
	v_bfi_b32 v75, s45, v37, v32
	v_lshlrev_b32_e32 v32, 2, v38
	v_lshrrev_b32_e32 v44, 1, v48
	v_bfi_b32 v77, s45, v32, v63
	v_lshrrev_b32_e32 v32, 2, v63
	v_lshlrev_b32_e32 v43, 1, v40
	v_bfi_b32 v44, s47, v44, v40
	v_lshlrev_b32_e32 v40, 1, v61
	v_bfi_b32 v38, s45, v38, v32
	v_lshlrev_b32_e32 v32, 2, v34
	v_bfi_b32 v46, s46, v40, v57
	v_lshrrev_b32_e32 v40, 1, v57
	v_bfi_b32 v63, s45, v32, v36
	v_lshrrev_b32_e32 v32, 2, v36
	v_bfi_b32 v43, s46, v43, v48
	v_bfi_b32 v48, s47, v40, v61
	v_lshlrev_b32_e32 v40, 1, v51
	v_bfi_b32 v34, s45, v34, v32
	v_lshlrev_b32_e32 v32, 2, v35
	v_bfi_b32 v50, s46, v40, v55
	v_lshrrev_b32_e32 v40, 1, v55
	v_bfi_b32 v36, s45, v32, v33
	v_lshrrev_b32_e32 v32, 2, v33
	v_bfi_b32 v52, s47, v40, v51
	v_lshlrev_b32_e32 v40, 1, v65
	v_bfi_b32 v79, s45, v35, v32
	v_lshlrev_b32_e32 v32, 1, v59
	v_lshrrev_b32_e32 v41, 1, v60
	v_bfi_b32 v54, s46, v40, v53
	v_lshrrev_b32_e32 v40, 1, v53
	v_bfi_b32 v32, s46, v32, v39
	v_lshrrev_b32_e32 v33, 1, v39
	v_lshrrev_b32_e32 v37, 1, v47
	v_lshlrev_b32_e32 v39, 1, v56
	v_bfi_b32 v41, s47, v41, v56
	v_bfi_b32 v56, s47, v40, v65
	v_lshlrev_b32_e32 v40, 1, v66
	v_lshlrev_b32_e32 v35, 1, v58
	v_bfi_b32 v37, s47, v37, v58
	v_bfi_b32 v58, s46, v40, v49
	v_lshrrev_b32_e32 v40, 1, v49
	v_bfi_b32 v39, s46, v39, v60
	v_bfi_b32 v60, s47, v40, v66
	v_lshlrev_b32_e32 v40, 1, v64
	v_bfi_b32 v62, s46, v40, v67
	v_lshrrev_b32_e32 v40, 1, v67
	v_bfi_b32 v64, s47, v40, v64
	v_lshlrev_b32_e32 v40, 1, v45
	v_bfi_b32 v66, s46, v40, v68
	v_lshrrev_b32_e32 v40, 1, v68
	v_bfi_b32 v68, s47, v40, v45
	v_lshlrev_b32_e32 v40, 1, v72
	v_bfi_b32 v70, s46, v40, v69
	v_lshrrev_b32_e32 v40, 1, v69
	v_bfi_b32 v72, s47, v40, v72
	v_lshlrev_b32_e32 v40, 1, v42
	v_bfi_b32 v74, s46, v40, v71
	v_lshrrev_b32_e32 v40, 1, v71
	v_bfi_b32 v76, s47, v40, v42
	v_lshlrev_b32_e32 v40, 1, v77
	v_bfi_b32 v78, s46, v40, v73
	v_lshrrev_b32_e32 v40, 1, v73
	v_bfi_b32 v80, s47, v40, v77
	v_lshlrev_b32_e32 v40, 1, v38
	v_bfi_b32 v82, s46, v40, v75
	v_lshrrev_b32_e32 v40, 1, v75
	v_bfi_b32 v84, s47, v40, v38
	v_lshlrev_b32_e32 v38, 1, v36
	v_bfi_b32 v86, s46, v38, v63
	v_lshrrev_b32_e32 v38, 1, v63
	v_bfi_b32 v88, s47, v38, v36
	v_lshlrev_b32_e32 v36, 1, v79
	v_bfi_b32 v90, s46, v36, v34
	v_lshrrev_b32_e32 v34, 1, v34
	v_bfi_b32 v33, s47, v33, v59
	v_bfi_b32 v35, s46, v35, v47
	v_bfi_b32 v92, s47, v34, v79
.LBB0_842:
	s_waitcnt lgkmcnt(14)
	s_waitcnt lgkmcnt(13)
	s_waitcnt lgkmcnt(12)
	s_waitcnt lgkmcnt(11)
	s_waitcnt lgkmcnt(10)
	s_waitcnt lgkmcnt(9)
	s_waitcnt lgkmcnt(8)
	s_waitcnt lgkmcnt(7)
	s_waitcnt lgkmcnt(6)
	s_waitcnt lgkmcnt(5)
	s_waitcnt lgkmcnt(4)
	s_waitcnt lgkmcnt(3)
	s_waitcnt lgkmcnt(2)
	s_waitcnt lgkmcnt(1)
	s_waitcnt lgkmcnt(0)
	v_perm_b32 v36, v15, v31, s37
	v_perm_b32 v15, v15, v31, s36
	v_perm_b32 v31, v12, v28, s37
	v_perm_b32 v12, v12, v28, s36
	v_perm_b32 v28, v13, v29, s37
	v_perm_b32 v13, v13, v29, s36
	v_perm_b32 v29, v10, v26, s37
	v_perm_b32 v38, v7, v23, s37
	v_perm_b32 v7, v7, v23, s36
	v_perm_b32 v23, v4, v20, s37
	v_perm_b32 v4, v4, v20, s36
	v_perm_b32 v20, v5, v21, s37
	v_perm_b32 v5, v5, v21, s36
	v_perm_b32 v21, v2, v18, s37
	v_perm_b32 v34, v14, v30, s36
	v_perm_b32 v10, v10, v26, s36
	v_perm_b32 v26, v11, v27, s37
	v_perm_b32 v11, v11, v27, s36
	v_perm_b32 v27, v8, v24, s37
	v_perm_b32 v8, v8, v24, s36
	v_perm_b32 v24, v9, v25, s37
	v_perm_b32 v9, v9, v25, s36
	v_perm_b32 v25, v6, v22, s36
	v_perm_b32 v2, v2, v18, s36
	v_perm_b32 v18, v3, v19, s37
	v_perm_b32 v3, v3, v19, s36
	v_perm_b32 v19, v0, v16, s37
	v_perm_b32 v0, v0, v16, s36
	v_perm_b32 v16, v1, v17, s37
	v_perm_b32 v1, v1, v17, s36
	v_perm_b32 v6, v6, v22, s37
	v_perm_b32 v14, v14, v30, s37
	v_perm_b32 v30, v23, v31, s38
	v_perm_b32 v23, v23, v31, s39
	v_perm_b32 v31, v20, v28, s38
	v_perm_b32 v20, v20, v28, s39
	v_perm_b32 v28, v21, v29, s38
	v_perm_b32 v17, v6, v14, s38
	v_perm_b32 v21, v21, v29, s39
	v_perm_b32 v29, v18, v26, s38
	v_perm_b32 v18, v18, v26, s39
	v_perm_b32 v26, v19, v27, s38
	v_perm_b32 v19, v19, v27, s39
	v_perm_b32 v27, v16, v24, s38
	v_perm_b32 v16, v16, v24, s39
	v_perm_b32 v24, v25, v34, s38
	v_perm_b32 v25, v25, v34, s39
	v_perm_b32 v34, v7, v15, s38
	v_perm_b32 v7, v7, v15, s39
	v_perm_b32 v15, v4, v12, s38
	v_perm_b32 v4, v4, v12, s39
	v_perm_b32 v12, v5, v13, s38
	v_perm_b32 v5, v5, v13, s39
	v_perm_b32 v13, v2, v10, s38
	v_perm_b32 v2, v2, v10, s39
	v_perm_b32 v10, v3, v11, s38
	v_perm_b32 v3, v3, v11, s39
	v_perm_b32 v11, v0, v8, s38
	v_perm_b32 v0, v0, v8, s39
	v_perm_b32 v8, v1, v9, s38
	v_perm_b32 v1, v1, v9, s39
	v_lshlrev_b32_e32 v9, 4, v28
	v_bfi_b32 v9, s44, v9, v17
	v_lshrrev_b32_e32 v17, 4, v17
	v_perm_b32 v6, v6, v14, s39
	v_perm_b32 v14, v38, v36, s38
	v_bfi_b32 v17, s44, v28, v17
	v_lshlrev_b32_e32 v28, 4, v29
	v_bfi_b32 v28, s44, v28, v14
	v_lshrrev_b32_e32 v14, 4, v14
	v_bfi_b32 v14, s44, v29, v14
	v_lshlrev_b32_e32 v29, 4, v26
	v_bfi_b32 v29, s44, v29, v30
	v_lshrrev_b32_e32 v30, 4, v30
	v_bfi_b32 v26, s44, v26, v30
	v_lshlrev_b32_e32 v30, 4, v27
	v_bfi_b32 v30, s44, v30, v31
	v_lshrrev_b32_e32 v31, 4, v31
	v_bfi_b32 v27, s44, v27, v31
	v_lshlrev_b32_e32 v31, 4, v21
	v_bfi_b32 v31, s44, v31, v6
	v_lshrrev_b32_e32 v6, 4, v6
	v_perm_b32 v22, v38, v36, s39
	v_bfi_b32 v6, s44, v21, v6
	v_lshlrev_b32_e32 v21, 4, v18
	v_bfi_b32 v21, s44, v21, v22
	v_lshrrev_b32_e32 v22, 4, v22
	v_bfi_b32 v18, s44, v18, v22
	v_lshlrev_b32_e32 v22, 4, v19
	v_bfi_b32 v22, s44, v22, v23
	v_lshrrev_b32_e32 v23, 4, v23
	v_bfi_b32 v19, s44, v19, v23
	v_lshlrev_b32_e32 v23, 4, v16
	v_bfi_b32 v23, s44, v23, v20
	v_lshrrev_b32_e32 v20, 4, v20
	v_bfi_b32 v16, s44, v16, v20
	v_lshlrev_b32_e32 v20, 4, v13
	v_bfi_b32 v20, s44, v20, v24
	v_lshrrev_b32_e32 v24, 4, v24
	v_bfi_b32 v13, s44, v13, v24
	v_lshlrev_b32_e32 v24, 4, v10
	v_bfi_b32 v24, s44, v24, v34
	v_lshrrev_b32_e32 v34, 4, v34
	v_bfi_b32 v10, s44, v10, v34
	v_lshlrev_b32_e32 v34, 4, v11
	v_bfi_b32 v34, s44, v34, v15
	v_lshrrev_b32_e32 v15, 4, v15
	v_bfi_b32 v11, s44, v11, v15
	v_lshlrev_b32_e32 v15, 4, v8
	v_bfi_b32 v15, s44, v15, v12
	v_lshrrev_b32_e32 v12, 4, v12
	v_bfi_b32 v8, s44, v8, v12
	v_lshlrev_b32_e32 v12, 4, v2
	v_bfi_b32 v12, s44, v12, v25
	v_lshrrev_b32_e32 v25, 4, v25
	v_bfi_b32 v2, s44, v2, v25
	v_lshlrev_b32_e32 v25, 4, v3
	v_bfi_b32 v25, s44, v25, v7
	v_lshrrev_b32_e32 v7, 4, v7
	v_bfi_b32 v3, s44, v3, v7
	v_lshlrev_b32_e32 v7, 4, v0
	v_bfi_b32 v7, s44, v7, v4
	v_lshrrev_b32_e32 v4, 4, v4
	v_bfi_b32 v0, s44, v0, v4
	v_lshlrev_b32_e32 v4, 4, v1
	v_bfi_b32 v4, s44, v4, v5
	v_lshrrev_b32_e32 v5, 4, v5
	v_bfi_b32 v1, s44, v1, v5
	v_lshlrev_b32_e32 v5, 2, v29
	v_bfi_b32 v5, s45, v5, v9
	v_lshrrev_b32_e32 v9, 2, v9
	v_bfi_b32 v9, s45, v29, v9
	v_lshlrev_b32_e32 v29, 2, v30
	v_bfi_b32 v29, s45, v29, v28
	v_lshrrev_b32_e32 v28, 2, v28
	v_bfi_b32 v28, s45, v30, v28
	v_lshlrev_b32_e32 v30, 2, v26
	v_bfi_b32 v30, s45, v30, v17
	v_lshrrev_b32_e32 v17, 2, v17
	v_bfi_b32 v17, s45, v26, v17
	v_lshlrev_b32_e32 v26, 2, v27
	v_bfi_b32 v26, s45, v26, v14
	v_lshrrev_b32_e32 v14, 2, v14
	v_bfi_b32 v14, s45, v27, v14
	v_lshlrev_b32_e32 v27, 2, v22
	v_bfi_b32 v27, s45, v27, v31
	v_lshrrev_b32_e32 v31, 2, v31
	v_bfi_b32 v22, s45, v22, v31
	v_lshlrev_b32_e32 v31, 2, v23
	v_bfi_b32 v31, s45, v31, v21
	v_lshrrev_b32_e32 v21, 2, v21
	v_bfi_b32 v21, s45, v23, v21
	v_lshlrev_b32_e32 v23, 2, v19
	v_bfi_b32 v23, s45, v23, v6
	v_lshrrev_b32_e32 v6, 2, v6
	v_bfi_b32 v6, s45, v19, v6
	v_lshlrev_b32_e32 v19, 2, v16
	v_bfi_b32 v19, s45, v19, v18
	v_lshrrev_b32_e32 v18, 2, v18
	v_bfi_b32 v16, s45, v16, v18
	v_lshlrev_b32_e32 v18, 2, v34
	v_bfi_b32 v18, s45, v18, v20
	v_lshrrev_b32_e32 v20, 2, v20
	v_bfi_b32 v20, s45, v34, v20
	v_lshlrev_b32_e32 v34, 2, v15
	v_bfi_b32 v69, s45, v34, v24
	v_lshrrev_b32_e32 v24, 2, v24
	v_bfi_b32 v15, s45, v15, v24
	v_lshlrev_b32_e32 v24, 2, v11
	v_bfi_b32 v24, s45, v24, v13
	v_lshrrev_b32_e32 v13, 2, v13
	v_bfi_b32 v11, s45, v11, v13
	v_lshlrev_b32_e32 v13, 2, v8
	v_bfi_b32 v13, s45, v13, v10
	v_lshrrev_b32_e32 v10, 2, v10
	v_bfi_b32 v8, s45, v8, v10
	v_lshlrev_b32_e32 v10, 2, v7
	v_bfi_b32 v10, s45, v10, v12
	v_lshrrev_b32_e32 v12, 2, v12
	v_bfi_b32 v7, s45, v7, v12
	v_lshlrev_b32_e32 v12, 2, v4
	v_bfi_b32 v12, s45, v12, v25
	v_lshrrev_b32_e32 v25, 2, v25
	v_bfi_b32 v4, s45, v4, v25
	v_lshlrev_b32_e32 v25, 2, v0
	v_bfi_b32 v25, s45, v25, v2
	v_lshrrev_b32_e32 v2, 2, v2
	v_bfi_b32 v0, s45, v0, v2
	v_lshlrev_b32_e32 v2, 2, v1
	v_bfi_b32 v2, s45, v2, v3
	v_lshrrev_b32_e32 v3, 2, v3
	v_bfi_b32 v1, s45, v1, v3
	v_lshlrev_b32_e32 v3, 1, v29
	v_bfi_b32 v34, s46, v3, v5
	v_lshrrev_b32_e32 v3, 1, v5
	v_bfi_b32 v36, s47, v3, v29
	v_lshlrev_b32_e32 v3, 1, v28
	v_bfi_b32 v38, s46, v3, v9
	v_lshrrev_b32_e32 v3, 1, v9
	v_bfi_b32 v40, s47, v3, v28
	v_lshlrev_b32_e32 v3, 1, v26
	v_bfi_b32 v42, s46, v3, v30
	v_lshrrev_b32_e32 v3, 1, v30
	v_bfi_b32 v45, s47, v3, v26
	v_lshlrev_b32_e32 v3, 1, v14
	v_bfi_b32 v47, s46, v3, v17
	v_lshrrev_b32_e32 v3, 1, v17
	v_bfi_b32 v49, s47, v3, v14
	v_lshlrev_b32_e32 v3, 1, v31
	v_bfi_b32 v51, s46, v3, v27
	v_lshrrev_b32_e32 v3, 1, v27
	v_bfi_b32 v53, s47, v3, v31
	v_lshlrev_b32_e32 v3, 1, v21
	v_bfi_b32 v55, s46, v3, v22
	v_lshrrev_b32_e32 v3, 1, v22
	v_bfi_b32 v57, s47, v3, v21
	v_lshlrev_b32_e32 v3, 1, v19
	v_bfi_b32 v59, s46, v3, v23
	v_lshrrev_b32_e32 v3, 1, v23
	v_bfi_b32 v61, s47, v3, v19
	v_lshlrev_b32_e32 v3, 1, v16
	v_bfi_b32 v63, s46, v3, v6
	v_lshrrev_b32_e32 v3, 1, v6
	v_bfi_b32 v65, s47, v3, v16
	v_lshlrev_b32_e32 v3, 1, v69
	v_bfi_b32 v67, s46, v3, v18
	v_lshrrev_b32_e32 v3, 1, v18
	v_bfi_b32 v69, s47, v3, v69
	v_lshlrev_b32_e32 v3, 1, v15
	v_bfi_b32 v71, s46, v3, v20
	v_lshrrev_b32_e32 v3, 1, v20
	v_bfi_b32 v73, s47, v3, v15
	v_lshlrev_b32_e32 v3, 1, v13
	v_bfi_b32 v75, s46, v3, v24
	v_lshrrev_b32_e32 v3, 1, v24
	v_bfi_b32 v77, s47, v3, v13
	v_lshlrev_b32_e32 v3, 1, v8
	v_bfi_b32 v79, s46, v3, v11
	v_lshrrev_b32_e32 v3, 1, v11
	v_bfi_b32 v81, s47, v3, v8
	v_lshlrev_b32_e32 v3, 1, v12
	v_bfi_b32 v83, s46, v3, v10
	v_lshrrev_b32_e32 v3, 1, v10
	v_bfi_b32 v85, s47, v3, v12
	v_lshlrev_b32_e32 v3, 1, v4
	v_bfi_b32 v87, s46, v3, v7
	v_lshrrev_b32_e32 v3, 1, v7
	v_bfi_b32 v89, s47, v3, v4
	v_lshlrev_b32_e32 v3, 1, v2
	v_bfi_b32 v91, s46, v3, v25
	v_lshrrev_b32_e32 v3, 1, v25
	v_bfi_b32 v93, s47, v3, v2
	v_lshlrev_b32_e32 v2, 1, v1
	v_bfi_b32 v94, s46, v2, v0
	v_lshrrev_b32_e32 v0, 1, v0
	v_bfi_b32 v95, s47, v0, v1
.LBB0_843:
	s_lshl_b32 s6, s12, 10
	s_add_i32 s40, s6, 0
	s_add_i32 s40, s40, 0x20000
	s_add_i32 s41, s41, s12
	s_cmpk_gt_i32 s19, 0x100
	s_mov_b64 s[6:7], -1
	s_cbranch_scc0 .LBB0_1135
	v_xad_u32 v0, v99, 63, s19
	v_lshrrev_b32_e32 v1, 6, v0
	v_lshlrev_b32_e64 v2, v1, -1
	v_not_b32_e32 v2, v2
	v_cmp_gt_u32_e32 vcc, s49, v0
	v_subrev_u32_e32 v8, 32, v1
	v_lshlrev_b32_e64 v8, v8, -1
	v_cndmask_b32_e32 v7, -1, v2, vcc
	v_not_b32_e32 v8, v8
	v_cmp_lt_u32_e32 vcc, s50, v0
	v_subrev_u32_e32 v9, 64, v1
	v_lshlrev_b32_e64 v9, v9, -1
	v_cndmask_b32_e32 v8, 0, v8, vcc
	v_cmp_gt_u32_e32 vcc, s27, v0
	v_not_b32_e32 v9, v9
	v_add_u32_e32 v1, 0xffffffa0, v1
	v_cndmask_b32_e32 v6, -1, v8, vcc
	v_cmp_lt_u32_e32 vcc, s51, v0
	v_lshlrev_b32_e64 v1, v1, -1
	v_not_b32_e32 v1, v1
	v_cndmask_b32_e32 v9, 0, v9, vcc
	v_cmp_gt_u32_e32 vcc, s52, v0
	s_mov_b32 s57, 0
	v_mov_b32_e32 v3, 0
	v_cndmask_b32_e32 v5, -1, v9, vcc
	v_cmp_lt_u32_e32 vcc, s53, v0
	v_mov_b32_e32 v2, 0
	s_nop 0
	v_cndmask_b32_e32 v1, 0, v1, vcc
	v_cmp_gt_u32_e32 vcc, s48, v0
	v_mov_b32_e32 v0, 0
	s_nop 0
	v_cndmask_b32_e32 v4, -1, v1, vcc
	v_mov_b32_e32 v1, 0
	s_cmpk_gt_u32 s19, 0x1800
	s_cbranch_scc1 .Lrdx_w4
	s_cmpk_gt_u32 s19, 0x1000
	s_cbranch_scc1 .Lrdx_w3
	s_cmpk_gt_u32 s19, 0x800
	s_cbranch_scc1 .Lrdx_w2
	v_mov_b32_e32 v9, 0
	v_mov_b32_e32 v10, 0
	v_mov_b32_e32 v11, 0
	s_mov_b32 s58, -1
	v_bitop3_b32 v8, v7, v189, s58 bitop3:0x60
	v_bcnt_u32_b32 v12, v8, 0
	s_nop 1
	v_add_u32_dpp v12, v12, v12 row_ror:8 row_mask:0xf bank_mask:0xf bound_ctrl:1
	s_nop 1
	v_add_u32_dpp v12, v12, v12 row_ror:4 row_mask:0xf bank_mask:0xf bound_ctrl:1
	s_nop 1
	v_add_u32_dpp v12, v12, v12 row_ror:2 row_mask:0xf bank_mask:0xf bound_ctrl:1
	s_nop 1
	v_add_u32_dpp v12, v12, v12 row_ror:1 row_mask:0xf bank_mask:0xf bound_ctrl:1
	s_nop 0
	v_readlane_b32 s6, v12, 0
	v_readlane_b32 s7, v12, 16
	v_readlane_b32 s8, v12, 32
	v_readlane_b32 s9, v12, 48
	s_add_i32 s6, s6, s7
	s_add_i32 s8, s8, s9
	s_add_i32 s6, s6, s57
	s_add_i32 s8, s6, s8
	s_cmpk_eq_i32 s8, 0x100
	s_cbranch_scc1 .Lrdx_eq
	s_cmpk_lt_i32 s8, 0x100
	s_cselect_b32 s6, -1, 0
	s_cselect_b32 s57, s8, s57
	s_xor_b32 s59, s58, s6
	v_bitop3_b32 v7, v7, v189, s59 bitop3:0x60
	s_mov_b32 s58, s6
	v_bitop3_b32 v3, v3, v8, s6 bitop3:0xf8
	v_bitop3_b32 v8, v7, v188, s58 bitop3:0x60
	v_bcnt_u32_b32 v12, v8, 0
	s_nop 1
	v_add_u32_dpp v12, v12, v12 row_ror:8 row_mask:0xf bank_mask:0xf bound_ctrl:1
	s_nop 1
	v_add_u32_dpp v12, v12, v12 row_ror:4 row_mask:0xf bank_mask:0xf bound_ctrl:1
	s_nop 1
	v_add_u32_dpp v12, v12, v12 row_ror:2 row_mask:0xf bank_mask:0xf bound_ctrl:1
	s_nop 1
	v_add_u32_dpp v12, v12, v12 row_ror:1 row_mask:0xf bank_mask:0xf bound_ctrl:1
	s_nop 0
	v_readlane_b32 s6, v12, 0
	v_readlane_b32 s7, v12, 16
	v_readlane_b32 s8, v12, 32
	v_readlane_b32 s9, v12, 48
	s_add_i32 s6, s6, s7
	s_add_i32 s8, s8, s9
	s_add_i32 s6, s6, s57
	s_add_i32 s8, s6, s8
	s_cmpk_eq_i32 s8, 0x100
	s_cbranch_scc1 .Lrdx_eq
	s_cmpk_lt_i32 s8, 0x100
	s_cselect_b32 s6, -1, 0
	s_cselect_b32 s57, s8, s57
	s_xor_b32 s59, s58, s6
	v_bitop3_b32 v7, v7, v188, s59 bitop3:0x60
	v_bitop3_b32 v3, v3, v8, s6 bitop3:0xf8
	v_bitop3_b32 v8, v7, v187, s58 bitop3:0x60
	v_bcnt_u32_b32 v12, v8, 0
	s_nop 1
	v_add_u32_dpp v12, v12, v12 row_ror:8 row_mask:0xf bank_mask:0xf bound_ctrl:1
	s_nop 1
	v_add_u32_dpp v12, v12, v12 row_ror:4 row_mask:0xf bank_mask:0xf bound_ctrl:1
	s_nop 1
	v_add_u32_dpp v12, v12, v12 row_ror:2 row_mask:0xf bank_mask:0xf bound_ctrl:1
	s_nop 1
	v_add_u32_dpp v12, v12, v12 row_ror:1 row_mask:0xf bank_mask:0xf bound_ctrl:1
	s_nop 0
	v_readlane_b32 s6, v12, 0
	v_readlane_b32 s7, v12, 16
	v_readlane_b32 s8, v12, 32
	v_readlane_b32 s9, v12, 48
	s_add_i32 s6, s6, s7
	s_add_i32 s8, s8, s9
	s_add_i32 s6, s6, s57
	s_add_i32 s8, s6, s8
	s_cmpk_eq_i32 s8, 0x100
	s_cbranch_scc1 .Lrdx_eq
	s_cmpk_lt_i32 s8, 0x100
	s_cselect_b32 s6, -1, 0
	s_cselect_b32 s57, s8, s57
	s_xor_b32 s59, s58, s6
	v_bitop3_b32 v7, v7, v187, s59 bitop3:0x60
	v_bitop3_b32 v3, v3, v8, s6 bitop3:0xf8
	v_bitop3_b32 v8, v7, v184, s58 bitop3:0x60
	v_bcnt_u32_b32 v12, v8, 0
	s_nop 1
	v_add_u32_dpp v12, v12, v12 row_ror:8 row_mask:0xf bank_mask:0xf bound_ctrl:1
	s_nop 1
	v_add_u32_dpp v12, v12, v12 row_ror:4 row_mask:0xf bank_mask:0xf bound_ctrl:1
	s_nop 1
	v_add_u32_dpp v12, v12, v12 row_ror:2 row_mask:0xf bank_mask:0xf bound_ctrl:1
	s_nop 1
	v_add_u32_dpp v12, v12, v12 row_ror:1 row_mask:0xf bank_mask:0xf bound_ctrl:1
	s_nop 0
	v_readlane_b32 s6, v12, 0
	v_readlane_b32 s7, v12, 16
	v_readlane_b32 s8, v12, 32
	v_readlane_b32 s9, v12, 48
	s_add_i32 s6, s6, s7
	s_add_i32 s8, s8, s9
	s_add_i32 s6, s6, s57
	s_add_i32 s8, s6, s8
	s_cmpk_eq_i32 s8, 0x100
	s_cbranch_scc1 .Lrdx_eq
	s_cmpk_lt_i32 s8, 0x100
	s_cselect_b32 s6, -1, 0
	s_cselect_b32 s57, s8, s57
	s_xor_b32 s59, s58, s6
	v_bitop3_b32 v7, v7, v184, s59 bitop3:0x60
	v_bitop3_b32 v3, v3, v8, s6 bitop3:0xf8
	v_bitop3_b32 v8, v7, v181, s58 bitop3:0x60
	v_bcnt_u32_b32 v12, v8, 0
	s_nop 1
	v_add_u32_dpp v12, v12, v12 row_ror:8 row_mask:0xf bank_mask:0xf bound_ctrl:1
	s_nop 1
	v_add_u32_dpp v12, v12, v12 row_ror:4 row_mask:0xf bank_mask:0xf bound_ctrl:1
	s_nop 1
	v_add_u32_dpp v12, v12, v12 row_ror:2 row_mask:0xf bank_mask:0xf bound_ctrl:1
	s_nop 1
	v_add_u32_dpp v12, v12, v12 row_ror:1 row_mask:0xf bank_mask:0xf bound_ctrl:1
	s_nop 0
	v_readlane_b32 s6, v12, 0
	v_readlane_b32 s7, v12, 16
	v_readlane_b32 s8, v12, 32
	v_readlane_b32 s9, v12, 48
	s_add_i32 s6, s6, s7
	s_add_i32 s8, s8, s9
	s_add_i32 s6, s6, s57
	s_add_i32 s8, s6, s8
	s_cmpk_eq_i32 s8, 0x100
	s_cbranch_scc1 .Lrdx_eq
	s_cmpk_lt_i32 s8, 0x100
	s_cselect_b32 s6, -1, 0
	s_cselect_b32 s57, s8, s57
	s_xor_b32 s59, s58, s6
	v_bitop3_b32 v7, v7, v181, s59 bitop3:0x60
	v_bitop3_b32 v3, v3, v8, s6 bitop3:0xf8
	v_bitop3_b32 v8, v7, v160, s58 bitop3:0x60
	v_bcnt_u32_b32 v12, v8, 0
	s_nop 1
	v_add_u32_dpp v12, v12, v12 row_ror:8 row_mask:0xf bank_mask:0xf bound_ctrl:1
	s_nop 1
	v_add_u32_dpp v12, v12, v12 row_ror:4 row_mask:0xf bank_mask:0xf bound_ctrl:1
	s_nop 1
	v_add_u32_dpp v12, v12, v12 row_ror:2 row_mask:0xf bank_mask:0xf bound_ctrl:1
	s_nop 1
	v_add_u32_dpp v12, v12, v12 row_ror:1 row_mask:0xf bank_mask:0xf bound_ctrl:1
	s_nop 0
	v_readlane_b32 s6, v12, 0
	v_readlane_b32 s7, v12, 16
	v_readlane_b32 s8, v12, 32
	v_readlane_b32 s9, v12, 48
	s_add_i32 s6, s6, s7
	s_add_i32 s8, s8, s9
	s_add_i32 s6, s6, s57
	s_add_i32 s8, s6, s8
	s_cmpk_eq_i32 s8, 0x100
	s_cbranch_scc1 .Lrdx_eq
	s_cmpk_lt_i32 s8, 0x100
	s_cselect_b32 s6, -1, 0
	s_cselect_b32 s57, s8, s57
	s_xor_b32 s59, s58, s6
	v_bitop3_b32 v7, v7, v160, s59 bitop3:0x60
	v_bitop3_b32 v3, v3, v8, s6 bitop3:0xf8
	v_bitop3_b32 v8, v7, v158, s58 bitop3:0x60
	v_bcnt_u32_b32 v12, v8, 0
	s_nop 1
	v_add_u32_dpp v12, v12, v12 row_ror:8 row_mask:0xf bank_mask:0xf bound_ctrl:1
	s_nop 1
	v_add_u32_dpp v12, v12, v12 row_ror:4 row_mask:0xf bank_mask:0xf bound_ctrl:1
	s_nop 1
	v_add_u32_dpp v12, v12, v12 row_ror:2 row_mask:0xf bank_mask:0xf bound_ctrl:1
	s_nop 1
	v_add_u32_dpp v12, v12, v12 row_ror:1 row_mask:0xf bank_mask:0xf bound_ctrl:1
	s_nop 0
	v_readlane_b32 s6, v12, 0
	v_readlane_b32 s7, v12, 16
	v_readlane_b32 s8, v12, 32
	v_readlane_b32 s9, v12, 48
	s_add_i32 s6, s6, s7
	s_add_i32 s8, s8, s9
	s_add_i32 s6, s6, s57
	s_add_i32 s8, s6, s8
	s_cmpk_eq_i32 s8, 0x100
	s_cbranch_scc1 .Lrdx_eq
	s_cmpk_lt_i32 s8, 0x100
	s_cselect_b32 s6, -1, 0
	s_cselect_b32 s57, s8, s57
	s_xor_b32 s59, s58, s6
	v_bitop3_b32 v7, v7, v158, s59 bitop3:0x60
	v_bitop3_b32 v3, v3, v8, s6 bitop3:0xf8
	v_bitop3_b32 v8, v7, v156, s58 bitop3:0x60
	v_bcnt_u32_b32 v12, v8, 0
	s_nop 1
	v_add_u32_dpp v12, v12, v12 row_ror:8 row_mask:0xf bank_mask:0xf bound_ctrl:1
	s_nop 1
	v_add_u32_dpp v12, v12, v12 row_ror:4 row_mask:0xf bank_mask:0xf bound_ctrl:1
	s_nop 1
	v_add_u32_dpp v12, v12, v12 row_ror:2 row_mask:0xf bank_mask:0xf bound_ctrl:1
	s_nop 1
	v_add_u32_dpp v12, v12, v12 row_ror:1 row_mask:0xf bank_mask:0xf bound_ctrl:1
	s_nop 0
	v_readlane_b32 s6, v12, 0
	v_readlane_b32 s7, v12, 16
	v_readlane_b32 s8, v12, 32
	v_readlane_b32 s9, v12, 48
	s_add_i32 s6, s6, s7
	s_add_i32 s8, s8, s9
	s_add_i32 s6, s6, s57
	s_add_i32 s8, s6, s8
	s_cmpk_eq_i32 s8, 0x100
	s_cbranch_scc1 .Lrdx_eq
	s_cmpk_lt_i32 s8, 0x100
	s_cselect_b32 s6, -1, 0
	s_cselect_b32 s57, s8, s57
	s_xor_b32 s59, s58, s6
	v_bitop3_b32 v7, v7, v156, s59 bitop3:0x60
	v_bitop3_b32 v3, v3, v8, s6 bitop3:0xf8
	v_bitop3_b32 v8, v7, v154, s58 bitop3:0x60
	v_bcnt_u32_b32 v12, v8, 0
	s_nop 1
	v_add_u32_dpp v12, v12, v12 row_ror:8 row_mask:0xf bank_mask:0xf bound_ctrl:1
	s_nop 1
	v_add_u32_dpp v12, v12, v12 row_ror:4 row_mask:0xf bank_mask:0xf bound_ctrl:1
	s_nop 1
	v_add_u32_dpp v12, v12, v12 row_ror:2 row_mask:0xf bank_mask:0xf bound_ctrl:1
	s_nop 1
	v_add_u32_dpp v12, v12, v12 row_ror:1 row_mask:0xf bank_mask:0xf bound_ctrl:1
	s_nop 0
	v_readlane_b32 s6, v12, 0
	v_readlane_b32 s7, v12, 16
	v_readlane_b32 s8, v12, 32
	v_readlane_b32 s9, v12, 48
	s_add_i32 s6, s6, s7
	s_add_i32 s8, s8, s9
	s_add_i32 s6, s6, s57
	s_add_i32 s8, s6, s8
	s_cmpk_eq_i32 s8, 0x100
	s_cbranch_scc1 .Lrdx_eq
	s_cmpk_lt_i32 s8, 0x100
	s_cselect_b32 s6, -1, 0
	s_cselect_b32 s57, s8, s57
	s_xor_b32 s59, s58, s6
	v_bitop3_b32 v7, v7, v154, s59 bitop3:0x60
	v_bitop3_b32 v3, v3, v8, s6 bitop3:0xf8
	v_bitop3_b32 v8, v7, v152, s58 bitop3:0x60
	v_bcnt_u32_b32 v12, v8, 0
	s_nop 1
	v_add_u32_dpp v12, v12, v12 row_ror:8 row_mask:0xf bank_mask:0xf bound_ctrl:1
	s_nop 1
	v_add_u32_dpp v12, v12, v12 row_ror:4 row_mask:0xf bank_mask:0xf bound_ctrl:1
	s_nop 1
	v_add_u32_dpp v12, v12, v12 row_ror:2 row_mask:0xf bank_mask:0xf bound_ctrl:1
	s_nop 1
	v_add_u32_dpp v12, v12, v12 row_ror:1 row_mask:0xf bank_mask:0xf bound_ctrl:1
	s_nop 0
	v_readlane_b32 s6, v12, 0
	v_readlane_b32 s7, v12, 16
	v_readlane_b32 s8, v12, 32
	v_readlane_b32 s9, v12, 48
	s_add_i32 s6, s6, s7
	s_add_i32 s8, s8, s9
	s_add_i32 s6, s6, s57
	s_add_i32 s8, s6, s8
	s_cmpk_eq_i32 s8, 0x100
	s_cbranch_scc1 .Lrdx_eq
	s_cmpk_lt_i32 s8, 0x100
	s_cselect_b32 s6, -1, 0
	s_cselect_b32 s57, s8, s57
	s_xor_b32 s59, s58, s6
	v_bitop3_b32 v7, v7, v152, s59 bitop3:0x60
	v_bitop3_b32 v3, v3, v8, s6 bitop3:0xf8
	v_bitop3_b32 v8, v7, v150, s58 bitop3:0x60
	v_bcnt_u32_b32 v12, v8, 0
	s_nop 1
	v_add_u32_dpp v12, v12, v12 row_ror:8 row_mask:0xf bank_mask:0xf bound_ctrl:1
	s_nop 1
	v_add_u32_dpp v12, v12, v12 row_ror:4 row_mask:0xf bank_mask:0xf bound_ctrl:1
	s_nop 1
	v_add_u32_dpp v12, v12, v12 row_ror:2 row_mask:0xf bank_mask:0xf bound_ctrl:1
	s_nop 1
	v_add_u32_dpp v12, v12, v12 row_ror:1 row_mask:0xf bank_mask:0xf bound_ctrl:1
	s_nop 0
	v_readlane_b32 s6, v12, 0
	v_readlane_b32 s7, v12, 16
	v_readlane_b32 s8, v12, 32
	v_readlane_b32 s9, v12, 48
	s_add_i32 s6, s6, s7
	s_add_i32 s8, s8, s9
	s_add_i32 s6, s6, s57
	s_add_i32 s8, s6, s8
	s_cmpk_eq_i32 s8, 0x100
	s_cbranch_scc1 .Lrdx_eq
	s_cmpk_lt_i32 s8, 0x100
	s_cselect_b32 s6, -1, 0
	s_cselect_b32 s57, s8, s57
	s_xor_b32 s59, s58, s6
	v_bitop3_b32 v7, v7, v150, s59 bitop3:0x60
	v_bitop3_b32 v3, v3, v8, s6 bitop3:0xf8
	v_bitop3_b32 v8, v7, v148, s58 bitop3:0x60
	v_bcnt_u32_b32 v12, v8, 0
	s_nop 1
	v_add_u32_dpp v12, v12, v12 row_ror:8 row_mask:0xf bank_mask:0xf bound_ctrl:1
	s_nop 1
	v_add_u32_dpp v12, v12, v12 row_ror:4 row_mask:0xf bank_mask:0xf bound_ctrl:1
	s_nop 1
	v_add_u32_dpp v12, v12, v12 row_ror:2 row_mask:0xf bank_mask:0xf bound_ctrl:1
	s_nop 1
	v_add_u32_dpp v12, v12, v12 row_ror:1 row_mask:0xf bank_mask:0xf bound_ctrl:1
	s_nop 0
	v_readlane_b32 s6, v12, 0
	v_readlane_b32 s7, v12, 16
	v_readlane_b32 s8, v12, 32
	v_readlane_b32 s9, v12, 48
	s_add_i32 s6, s6, s7
	s_add_i32 s8, s8, s9
	s_add_i32 s6, s6, s57
	s_add_i32 s8, s6, s8
	s_cmpk_eq_i32 s8, 0x100
	s_cbranch_scc1 .Lrdx_eq
	s_cmpk_lt_i32 s8, 0x100
	s_cselect_b32 s6, -1, 0
	s_cselect_b32 s57, s8, s57
	s_xor_b32 s59, s58, s6
	v_bitop3_b32 v7, v7, v148, s59 bitop3:0x60
	v_bitop3_b32 v3, v3, v8, s6 bitop3:0xf8
	v_bitop3_b32 v8, v7, v146, s58 bitop3:0x60
	v_bcnt_u32_b32 v12, v8, 0
	s_nop 1
	v_add_u32_dpp v12, v12, v12 row_ror:8 row_mask:0xf bank_mask:0xf bound_ctrl:1
	s_nop 1
	v_add_u32_dpp v12, v12, v12 row_ror:4 row_mask:0xf bank_mask:0xf bound_ctrl:1
	s_nop 1
	v_add_u32_dpp v12, v12, v12 row_ror:2 row_mask:0xf bank_mask:0xf bound_ctrl:1
	s_nop 1
	v_add_u32_dpp v12, v12, v12 row_ror:1 row_mask:0xf bank_mask:0xf bound_ctrl:1
	s_nop 0
	v_readlane_b32 s6, v12, 0
	v_readlane_b32 s7, v12, 16
	v_readlane_b32 s8, v12, 32
	v_readlane_b32 s9, v12, 48
	s_add_i32 s6, s6, s7
	s_add_i32 s8, s8, s9
	s_add_i32 s6, s6, s57
	s_add_i32 s8, s6, s8
	s_cmpk_eq_i32 s8, 0x100
	s_cbranch_scc1 .Lrdx_eq
	s_cmpk_lt_i32 s8, 0x100
	s_cselect_b32 s6, -1, 0
	s_cselect_b32 s57, s8, s57
	s_xor_b32 s59, s58, s6
	v_bitop3_b32 v7, v7, v146, s59 bitop3:0x60
	v_bitop3_b32 v3, v3, v8, s6 bitop3:0xf8
	v_bitop3_b32 v8, v7, v144, s58 bitop3:0x60
	v_bcnt_u32_b32 v12, v8, 0
	s_nop 1
	v_add_u32_dpp v12, v12, v12 row_ror:8 row_mask:0xf bank_mask:0xf bound_ctrl:1
	s_nop 1
	v_add_u32_dpp v12, v12, v12 row_ror:4 row_mask:0xf bank_mask:0xf bound_ctrl:1
	s_nop 1
	v_add_u32_dpp v12, v12, v12 row_ror:2 row_mask:0xf bank_mask:0xf bound_ctrl:1
	s_nop 1
	v_add_u32_dpp v12, v12, v12 row_ror:1 row_mask:0xf bank_mask:0xf bound_ctrl:1
	s_nop 0
	v_readlane_b32 s6, v12, 0
	v_readlane_b32 s7, v12, 16
	v_readlane_b32 s8, v12, 32
	v_readlane_b32 s9, v12, 48
	s_add_i32 s6, s6, s7
	s_add_i32 s8, s8, s9
	s_add_i32 s6, s6, s57
	s_add_i32 s8, s6, s8
	s_cmpk_eq_i32 s8, 0x100
	s_cbranch_scc1 .Lrdx_eq
	s_cmpk_lt_i32 s8, 0x100
	s_cselect_b32 s6, -1, 0
	s_cselect_b32 s57, s8, s57
	s_xor_b32 s59, s58, s6
	v_bitop3_b32 v7, v7, v144, s59 bitop3:0x60
	v_bitop3_b32 v3, v3, v8, s6 bitop3:0xf8
	v_bitop3_b32 v8, v7, v142, s58 bitop3:0x60
	v_bcnt_u32_b32 v12, v8, 0
	s_nop 1
	v_add_u32_dpp v12, v12, v12 row_ror:8 row_mask:0xf bank_mask:0xf bound_ctrl:1
	s_nop 1
	v_add_u32_dpp v12, v12, v12 row_ror:4 row_mask:0xf bank_mask:0xf bound_ctrl:1
	s_nop 1
	v_add_u32_dpp v12, v12, v12 row_ror:2 row_mask:0xf bank_mask:0xf bound_ctrl:1
	s_nop 1
	v_add_u32_dpp v12, v12, v12 row_ror:1 row_mask:0xf bank_mask:0xf bound_ctrl:1
	s_nop 0
	v_readlane_b32 s6, v12, 0
	v_readlane_b32 s7, v12, 16
	v_readlane_b32 s8, v12, 32
	v_readlane_b32 s9, v12, 48
	s_add_i32 s6, s6, s7
	s_add_i32 s8, s8, s9
	s_add_i32 s6, s6, s57
	s_add_i32 s8, s6, s8
	s_cmpk_eq_i32 s8, 0x100
	s_cbranch_scc1 .Lrdx_eq
	s_cmpk_lt_i32 s8, 0x100
	s_cselect_b32 s6, -1, 0
	s_cselect_b32 s57, s8, s57
	s_xor_b32 s59, s58, s6
	v_bitop3_b32 v7, v7, v142, s59 bitop3:0x60
	v_bitop3_b32 v3, v3, v8, s6 bitop3:0xf8
	v_bitop3_b32 v8, v7, v140, s58 bitop3:0x60
	v_bcnt_u32_b32 v12, v8, 0
	s_nop 1
	v_add_u32_dpp v12, v12, v12 row_ror:8 row_mask:0xf bank_mask:0xf bound_ctrl:1
	s_nop 1
	v_add_u32_dpp v12, v12, v12 row_ror:4 row_mask:0xf bank_mask:0xf bound_ctrl:1
	s_nop 1
	v_add_u32_dpp v12, v12, v12 row_ror:2 row_mask:0xf bank_mask:0xf bound_ctrl:1
	s_nop 1
	v_add_u32_dpp v12, v12, v12 row_ror:1 row_mask:0xf bank_mask:0xf bound_ctrl:1
	s_nop 0
	v_readlane_b32 s6, v12, 0
	v_readlane_b32 s7, v12, 16
	v_readlane_b32 s8, v12, 32
	v_readlane_b32 s9, v12, 48
	s_add_i32 s6, s6, s7
	s_add_i32 s8, s8, s9
	s_add_i32 s6, s6, s57
	s_add_i32 s8, s6, s8
	s_cmpk_eq_i32 s8, 0x100
	s_cbranch_scc1 .Lrdx_eq
	s_cmpk_lt_i32 s8, 0x100
	s_cselect_b32 s6, -1, 0
	s_cselect_b32 s57, s8, s57
	s_xor_b32 s59, s58, s6
	v_bitop3_b32 v7, v7, v140, s59 bitop3:0x60
	v_bitop3_b32 v3, v3, v8, s6 bitop3:0xf8
	v_bitop3_b32 v8, v7, v138, s58 bitop3:0x60
	v_bcnt_u32_b32 v12, v8, 0
	s_nop 1
	v_add_u32_dpp v12, v12, v12 row_ror:8 row_mask:0xf bank_mask:0xf bound_ctrl:1
	s_nop 1
	v_add_u32_dpp v12, v12, v12 row_ror:4 row_mask:0xf bank_mask:0xf bound_ctrl:1
	s_nop 1
	v_add_u32_dpp v12, v12, v12 row_ror:2 row_mask:0xf bank_mask:0xf bound_ctrl:1
	s_nop 1
	v_add_u32_dpp v12, v12, v12 row_ror:1 row_mask:0xf bank_mask:0xf bound_ctrl:1
	s_nop 0
	v_readlane_b32 s6, v12, 0
	v_readlane_b32 s7, v12, 16
	v_readlane_b32 s8, v12, 32
	v_readlane_b32 s9, v12, 48
	s_add_i32 s6, s6, s7
	s_add_i32 s8, s8, s9
	s_add_i32 s6, s6, s57
	s_add_i32 s8, s6, s8
	s_cmpk_eq_i32 s8, 0x100
	s_cbranch_scc1 .Lrdx_eq
	s_cmpk_lt_i32 s8, 0x100
	s_cselect_b32 s6, -1, 0
	s_cselect_b32 s57, s8, s57
	s_xor_b32 s59, s58, s6
	v_bitop3_b32 v7, v7, v138, s59 bitop3:0x60
	v_bitop3_b32 v3, v3, v8, s6 bitop3:0xf8
	v_bitop3_b32 v8, v7, v136, s58 bitop3:0x60
	v_bcnt_u32_b32 v12, v8, 0
	s_nop 1
	v_add_u32_dpp v12, v12, v12 row_ror:8 row_mask:0xf bank_mask:0xf bound_ctrl:1
	s_nop 1
	v_add_u32_dpp v12, v12, v12 row_ror:4 row_mask:0xf bank_mask:0xf bound_ctrl:1
	s_nop 1
	v_add_u32_dpp v12, v12, v12 row_ror:2 row_mask:0xf bank_mask:0xf bound_ctrl:1
	s_nop 1
	v_add_u32_dpp v12, v12, v12 row_ror:1 row_mask:0xf bank_mask:0xf bound_ctrl:1
	s_nop 0
	v_readlane_b32 s6, v12, 0
	v_readlane_b32 s7, v12, 16
	v_readlane_b32 s8, v12, 32
	v_readlane_b32 s9, v12, 48
	s_add_i32 s6, s6, s7
	s_add_i32 s8, s8, s9
	s_add_i32 s6, s6, s57
	s_add_i32 s8, s6, s8
	s_cmpk_eq_i32 s8, 0x100
	s_cbranch_scc1 .Lrdx_eq
	s_cmpk_lt_i32 s8, 0x100
	s_cselect_b32 s6, -1, 0
	s_cselect_b32 s57, s8, s57
	s_xor_b32 s59, s58, s6
	v_bitop3_b32 v7, v7, v136, s59 bitop3:0x60
	v_bitop3_b32 v3, v3, v8, s6 bitop3:0xf8
	v_bitop3_b32 v8, v7, v134, s58 bitop3:0x60
	v_bcnt_u32_b32 v12, v8, 0
	s_nop 1
	v_add_u32_dpp v12, v12, v12 row_ror:8 row_mask:0xf bank_mask:0xf bound_ctrl:1
	s_nop 1
	v_add_u32_dpp v12, v12, v12 row_ror:4 row_mask:0xf bank_mask:0xf bound_ctrl:1
	s_nop 1
	v_add_u32_dpp v12, v12, v12 row_ror:2 row_mask:0xf bank_mask:0xf bound_ctrl:1
	s_nop 1
	v_add_u32_dpp v12, v12, v12 row_ror:1 row_mask:0xf bank_mask:0xf bound_ctrl:1
	s_nop 0
	v_readlane_b32 s6, v12, 0
	v_readlane_b32 s7, v12, 16
	v_readlane_b32 s8, v12, 32
	v_readlane_b32 s9, v12, 48
	s_add_i32 s6, s6, s7
	s_add_i32 s8, s8, s9
	s_add_i32 s6, s6, s57
	s_add_i32 s8, s6, s8
	s_cmpk_eq_i32 s8, 0x100
	s_cbranch_scc1 .Lrdx_eq
	s_cmpk_lt_i32 s8, 0x100
	s_cselect_b32 s6, -1, 0
	s_cselect_b32 s57, s8, s57
	s_xor_b32 s59, s58, s6
	v_bitop3_b32 v7, v7, v134, s59 bitop3:0x60
	v_bitop3_b32 v3, v3, v8, s6 bitop3:0xf8
	v_bitop3_b32 v8, v7, v132, s58 bitop3:0x60
	v_bcnt_u32_b32 v12, v8, 0
	s_nop 1
	v_add_u32_dpp v12, v12, v12 row_ror:8 row_mask:0xf bank_mask:0xf bound_ctrl:1
	s_nop 1
	v_add_u32_dpp v12, v12, v12 row_ror:4 row_mask:0xf bank_mask:0xf bound_ctrl:1
	s_nop 1
	v_add_u32_dpp v12, v12, v12 row_ror:2 row_mask:0xf bank_mask:0xf bound_ctrl:1
	s_nop 1
	v_add_u32_dpp v12, v12, v12 row_ror:1 row_mask:0xf bank_mask:0xf bound_ctrl:1
	s_nop 0
	v_readlane_b32 s6, v12, 0
	v_readlane_b32 s7, v12, 16
	v_readlane_b32 s8, v12, 32
	v_readlane_b32 s9, v12, 48
	s_add_i32 s6, s6, s7
	s_add_i32 s8, s8, s9
	s_add_i32 s6, s6, s57
	s_add_i32 s8, s6, s8
	s_cmpk_eq_i32 s8, 0x100
	s_cbranch_scc1 .Lrdx_eq
	s_cmpk_lt_i32 s8, 0x100
	s_cselect_b32 s6, -1, 0
	s_cselect_b32 s57, s8, s57
	s_xor_b32 s59, s58, s6
	v_bitop3_b32 v7, v7, v132, s59 bitop3:0x60
	v_bitop3_b32 v3, v3, v8, s6 bitop3:0xf8
	v_bitop3_b32 v8, v7, v130, s58 bitop3:0x60
	v_bcnt_u32_b32 v12, v8, 0
	s_nop 1
	v_add_u32_dpp v12, v12, v12 row_ror:8 row_mask:0xf bank_mask:0xf bound_ctrl:1
	s_nop 1
	v_add_u32_dpp v12, v12, v12 row_ror:4 row_mask:0xf bank_mask:0xf bound_ctrl:1
	s_nop 1
	v_add_u32_dpp v12, v12, v12 row_ror:2 row_mask:0xf bank_mask:0xf bound_ctrl:1
	s_nop 1
	v_add_u32_dpp v12, v12, v12 row_ror:1 row_mask:0xf bank_mask:0xf bound_ctrl:1
	s_nop 0
	v_readlane_b32 s6, v12, 0
	v_readlane_b32 s7, v12, 16
	v_readlane_b32 s8, v12, 32
	v_readlane_b32 s9, v12, 48
	s_add_i32 s6, s6, s7
	s_add_i32 s8, s8, s9
	s_add_i32 s6, s6, s57
	s_add_i32 s8, s6, s8
	s_cmpk_eq_i32 s8, 0x100
	s_cbranch_scc1 .Lrdx_eq
	s_cmpk_lt_i32 s8, 0x100
	s_cselect_b32 s6, -1, 0
	s_cselect_b32 s57, s8, s57
	s_xor_b32 s59, s58, s6
	v_bitop3_b32 v7, v7, v130, s59 bitop3:0x60
	v_bitop3_b32 v3, v3, v8, s6 bitop3:0xf8
	v_bitop3_b32 v8, v7, v128, s58 bitop3:0x60
	v_bcnt_u32_b32 v12, v8, 0
	s_nop 1
	v_add_u32_dpp v12, v12, v12 row_ror:8 row_mask:0xf bank_mask:0xf bound_ctrl:1
	s_nop 1
	v_add_u32_dpp v12, v12, v12 row_ror:4 row_mask:0xf bank_mask:0xf bound_ctrl:1
	s_nop 1
	v_add_u32_dpp v12, v12, v12 row_ror:2 row_mask:0xf bank_mask:0xf bound_ctrl:1
	s_nop 1
	v_add_u32_dpp v12, v12, v12 row_ror:1 row_mask:0xf bank_mask:0xf bound_ctrl:1
	s_nop 0
	v_readlane_b32 s6, v12, 0
	v_readlane_b32 s7, v12, 16
	v_readlane_b32 s8, v12, 32
	v_readlane_b32 s9, v12, 48
	s_add_i32 s6, s6, s7
	s_add_i32 s8, s8, s9
	s_add_i32 s6, s6, s57
	s_add_i32 s8, s6, s8
	s_cmpk_eq_i32 s8, 0x100
	s_cbranch_scc1 .Lrdx_eq
	s_cmpk_lt_i32 s8, 0x100
	s_cselect_b32 s6, -1, 0
	s_cselect_b32 s57, s8, s57
	s_xor_b32 s59, s58, s6
	v_bitop3_b32 v7, v7, v128, s59 bitop3:0x60
	v_bitop3_b32 v3, v3, v8, s6 bitop3:0xf8
	v_bitop3_b32 v8, v7, v126, s58 bitop3:0x60
	v_bcnt_u32_b32 v12, v8, 0
	s_nop 1
	v_add_u32_dpp v12, v12, v12 row_ror:8 row_mask:0xf bank_mask:0xf bound_ctrl:1
	s_nop 1
	v_add_u32_dpp v12, v12, v12 row_ror:4 row_mask:0xf bank_mask:0xf bound_ctrl:1
	s_nop 1
	v_add_u32_dpp v12, v12, v12 row_ror:2 row_mask:0xf bank_mask:0xf bound_ctrl:1
	s_nop 1
	v_add_u32_dpp v12, v12, v12 row_ror:1 row_mask:0xf bank_mask:0xf bound_ctrl:1
	s_nop 0
	v_readlane_b32 s6, v12, 0
	v_readlane_b32 s7, v12, 16
	v_readlane_b32 s8, v12, 32
	v_readlane_b32 s9, v12, 48
	s_add_i32 s6, s6, s7
	s_add_i32 s8, s8, s9
	s_add_i32 s6, s6, s57
	s_add_i32 s8, s6, s8
	s_cmpk_eq_i32 s8, 0x100
	s_cbranch_scc1 .Lrdx_eq
	s_cmpk_lt_i32 s8, 0x100
	s_cselect_b32 s6, -1, 0
	s_cselect_b32 s57, s8, s57
	s_xor_b32 s59, s58, s6
	v_bitop3_b32 v7, v7, v126, s59 bitop3:0x60
	v_bitop3_b32 v3, v3, v8, s6 bitop3:0xf8
	v_bitop3_b32 v8, v7, v124, s58 bitop3:0x60
	v_bcnt_u32_b32 v12, v8, 0
	s_nop 1
	v_add_u32_dpp v12, v12, v12 row_ror:8 row_mask:0xf bank_mask:0xf bound_ctrl:1
	s_nop 1
	v_add_u32_dpp v12, v12, v12 row_ror:4 row_mask:0xf bank_mask:0xf bound_ctrl:1
	s_nop 1
	v_add_u32_dpp v12, v12, v12 row_ror:2 row_mask:0xf bank_mask:0xf bound_ctrl:1
	s_nop 1
	v_add_u32_dpp v12, v12, v12 row_ror:1 row_mask:0xf bank_mask:0xf bound_ctrl:1
	s_nop 0
	v_readlane_b32 s6, v12, 0
	v_readlane_b32 s7, v12, 16
	v_readlane_b32 s8, v12, 32
	v_readlane_b32 s9, v12, 48
	s_add_i32 s6, s6, s7
	s_add_i32 s8, s8, s9
	s_add_i32 s6, s6, s57
	s_add_i32 s8, s6, s8
	s_cmpk_eq_i32 s8, 0x100
	s_cbranch_scc1 .Lrdx_eq
	s_cmpk_lt_i32 s8, 0x100
	s_cselect_b32 s6, -1, 0
	s_cselect_b32 s57, s8, s57
	s_xor_b32 s59, s58, s6
	v_bitop3_b32 v7, v7, v124, s59 bitop3:0x60
	v_bitop3_b32 v3, v3, v8, s6 bitop3:0xf8
	v_bitop3_b32 v8, v7, v122, s58 bitop3:0x60
	v_bcnt_u32_b32 v12, v8, 0
	s_nop 1
	v_add_u32_dpp v12, v12, v12 row_ror:8 row_mask:0xf bank_mask:0xf bound_ctrl:1
	s_nop 1
	v_add_u32_dpp v12, v12, v12 row_ror:4 row_mask:0xf bank_mask:0xf bound_ctrl:1
	s_nop 1
	v_add_u32_dpp v12, v12, v12 row_ror:2 row_mask:0xf bank_mask:0xf bound_ctrl:1
	s_nop 1
	v_add_u32_dpp v12, v12, v12 row_ror:1 row_mask:0xf bank_mask:0xf bound_ctrl:1
	s_nop 0
	v_readlane_b32 s6, v12, 0
	v_readlane_b32 s7, v12, 16
	v_readlane_b32 s8, v12, 32
	v_readlane_b32 s9, v12, 48
	s_add_i32 s6, s6, s7
	s_add_i32 s8, s8, s9
	s_add_i32 s6, s6, s57
	s_add_i32 s8, s6, s8
	s_cmpk_eq_i32 s8, 0x100
	s_cbranch_scc1 .Lrdx_eq
	s_cmpk_lt_i32 s8, 0x100
	s_cselect_b32 s6, -1, 0
	s_cselect_b32 s57, s8, s57
	s_xor_b32 s59, s58, s6
	v_bitop3_b32 v7, v7, v122, s59 bitop3:0x60
	v_bitop3_b32 v3, v3, v8, s6 bitop3:0xf8
	v_bitop3_b32 v8, v7, v120, s58 bitop3:0x60
	v_bcnt_u32_b32 v12, v8, 0
	s_nop 1
	v_add_u32_dpp v12, v12, v12 row_ror:8 row_mask:0xf bank_mask:0xf bound_ctrl:1
	s_nop 1
	v_add_u32_dpp v12, v12, v12 row_ror:4 row_mask:0xf bank_mask:0xf bound_ctrl:1
	s_nop 1
	v_add_u32_dpp v12, v12, v12 row_ror:2 row_mask:0xf bank_mask:0xf bound_ctrl:1
	s_nop 1
	v_add_u32_dpp v12, v12, v12 row_ror:1 row_mask:0xf bank_mask:0xf bound_ctrl:1
	s_nop 0
	v_readlane_b32 s6, v12, 0
	v_readlane_b32 s7, v12, 16
	v_readlane_b32 s8, v12, 32
	v_readlane_b32 s9, v12, 48
	s_add_i32 s6, s6, s7
	s_add_i32 s8, s8, s9
	s_add_i32 s6, s6, s57
	s_add_i32 s8, s6, s8
	s_cmpk_eq_i32 s8, 0x100
	s_cbranch_scc1 .Lrdx_eq
	s_cmpk_lt_i32 s8, 0x100
	s_cselect_b32 s6, -1, 0
	s_cselect_b32 s57, s8, s57
	s_xor_b32 s59, s58, s6
	v_bitop3_b32 v7, v7, v120, s59 bitop3:0x60
	v_bitop3_b32 v3, v3, v8, s6 bitop3:0xf8
	v_bitop3_b32 v8, v7, v118, s58 bitop3:0x60
	v_bcnt_u32_b32 v12, v8, 0
	s_nop 1
	v_add_u32_dpp v12, v12, v12 row_ror:8 row_mask:0xf bank_mask:0xf bound_ctrl:1
	s_nop 1
	v_add_u32_dpp v12, v12, v12 row_ror:4 row_mask:0xf bank_mask:0xf bound_ctrl:1
	s_nop 1
	v_add_u32_dpp v12, v12, v12 row_ror:2 row_mask:0xf bank_mask:0xf bound_ctrl:1
	s_nop 1
	v_add_u32_dpp v12, v12, v12 row_ror:1 row_mask:0xf bank_mask:0xf bound_ctrl:1
	s_nop 0
	v_readlane_b32 s6, v12, 0
	v_readlane_b32 s7, v12, 16
	v_readlane_b32 s8, v12, 32
	v_readlane_b32 s9, v12, 48
	s_add_i32 s6, s6, s7
	s_add_i32 s8, s8, s9
	s_add_i32 s6, s6, s57
	s_add_i32 s8, s6, s8
	s_cmpk_eq_i32 s8, 0x100
	s_cbranch_scc1 .Lrdx_eq
	s_cmpk_lt_i32 s8, 0x100
	s_cselect_b32 s6, -1, 0
	s_cselect_b32 s57, s8, s57
	s_xor_b32 s59, s58, s6
	v_bitop3_b32 v7, v7, v118, s59 bitop3:0x60
	v_bitop3_b32 v3, v3, v8, s6 bitop3:0xf8
	v_bitop3_b32 v8, v7, v116, s58 bitop3:0x60
	v_bcnt_u32_b32 v12, v8, 0
	s_nop 1
	v_add_u32_dpp v12, v12, v12 row_ror:8 row_mask:0xf bank_mask:0xf bound_ctrl:1
	s_nop 1
	v_add_u32_dpp v12, v12, v12 row_ror:4 row_mask:0xf bank_mask:0xf bound_ctrl:1
	s_nop 1
	v_add_u32_dpp v12, v12, v12 row_ror:2 row_mask:0xf bank_mask:0xf bound_ctrl:1
	s_nop 1
	v_add_u32_dpp v12, v12, v12 row_ror:1 row_mask:0xf bank_mask:0xf bound_ctrl:1
	s_nop 0
	v_readlane_b32 s6, v12, 0
	v_readlane_b32 s7, v12, 16
	v_readlane_b32 s8, v12, 32
	v_readlane_b32 s9, v12, 48
	s_add_i32 s6, s6, s7
	s_add_i32 s8, s8, s9
	s_add_i32 s6, s6, s57
	s_add_i32 s8, s6, s8
	s_cmpk_eq_i32 s8, 0x100
	s_cbranch_scc1 .Lrdx_eq
	s_cmpk_lt_i32 s8, 0x100
	s_cselect_b32 s6, -1, 0
	s_cselect_b32 s57, s8, s57
	s_xor_b32 s59, s58, s6
	v_bitop3_b32 v7, v7, v116, s59 bitop3:0x60
	v_bitop3_b32 v3, v3, v8, s6 bitop3:0xf8
	v_bitop3_b32 v8, v7, v114, s58 bitop3:0x60
	v_bcnt_u32_b32 v12, v8, 0
	s_nop 1
	v_add_u32_dpp v12, v12, v12 row_ror:8 row_mask:0xf bank_mask:0xf bound_ctrl:1
	s_nop 1
	v_add_u32_dpp v12, v12, v12 row_ror:4 row_mask:0xf bank_mask:0xf bound_ctrl:1
	s_nop 1
	v_add_u32_dpp v12, v12, v12 row_ror:2 row_mask:0xf bank_mask:0xf bound_ctrl:1
	s_nop 1
	v_add_u32_dpp v12, v12, v12 row_ror:1 row_mask:0xf bank_mask:0xf bound_ctrl:1
	s_nop 0
	v_readlane_b32 s6, v12, 0
	v_readlane_b32 s7, v12, 16
	v_readlane_b32 s8, v12, 32
	v_readlane_b32 s9, v12, 48
	s_add_i32 s6, s6, s7
	s_add_i32 s8, s8, s9
	s_add_i32 s6, s6, s57
	s_add_i32 s8, s6, s8
	s_cmpk_eq_i32 s8, 0x100
	s_cbranch_scc1 .Lrdx_eq
	s_cmpk_lt_i32 s8, 0x100
	s_cselect_b32 s6, -1, 0
	s_cselect_b32 s57, s8, s57
	s_xor_b32 s59, s58, s6
	v_bitop3_b32 v7, v7, v114, s59 bitop3:0x60
	v_bitop3_b32 v3, v3, v8, s6 bitop3:0xf8
	v_bitop3_b32 v8, v7, v112, s58 bitop3:0x60
	v_bcnt_u32_b32 v12, v8, 0
	s_nop 1
	v_add_u32_dpp v12, v12, v12 row_ror:8 row_mask:0xf bank_mask:0xf bound_ctrl:1
	s_nop 1
	v_add_u32_dpp v12, v12, v12 row_ror:4 row_mask:0xf bank_mask:0xf bound_ctrl:1
	s_nop 1
	v_add_u32_dpp v12, v12, v12 row_ror:2 row_mask:0xf bank_mask:0xf bound_ctrl:1
	s_nop 1
	v_add_u32_dpp v12, v12, v12 row_ror:1 row_mask:0xf bank_mask:0xf bound_ctrl:1
	s_nop 0
	v_readlane_b32 s6, v12, 0
	v_readlane_b32 s7, v12, 16
	v_readlane_b32 s8, v12, 32
	v_readlane_b32 s9, v12, 48
	s_add_i32 s6, s6, s7
	s_add_i32 s8, s8, s9
	s_add_i32 s6, s6, s57
	s_add_i32 s8, s6, s8
	s_cmpk_eq_i32 s8, 0x100
	s_cbranch_scc1 .Lrdx_eq
	s_cmpk_lt_i32 s8, 0x100
	s_cselect_b32 s6, -1, 0
	s_cselect_b32 s57, s8, s57
	s_xor_b32 s59, s58, s6
	v_bitop3_b32 v7, v7, v112, s59 bitop3:0x60
	v_bitop3_b32 v3, v3, v8, s6 bitop3:0xf8
	v_bitop3_b32 v8, v7, v110, s58 bitop3:0x60
	v_bcnt_u32_b32 v12, v8, 0
	s_nop 1
	v_add_u32_dpp v12, v12, v12 row_ror:8 row_mask:0xf bank_mask:0xf bound_ctrl:1
	s_nop 1
	v_add_u32_dpp v12, v12, v12 row_ror:4 row_mask:0xf bank_mask:0xf bound_ctrl:1
	s_nop 1
	v_add_u32_dpp v12, v12, v12 row_ror:2 row_mask:0xf bank_mask:0xf bound_ctrl:1
	s_nop 1
	v_add_u32_dpp v12, v12, v12 row_ror:1 row_mask:0xf bank_mask:0xf bound_ctrl:1
	s_nop 0
	v_readlane_b32 s6, v12, 0
	v_readlane_b32 s7, v12, 16
	v_readlane_b32 s8, v12, 32
	v_readlane_b32 s9, v12, 48
	s_add_i32 s6, s6, s7
	s_add_i32 s8, s8, s9
	s_add_i32 s6, s6, s57
	s_add_i32 s8, s6, s8
	s_cmpk_eq_i32 s8, 0x100
	s_cbranch_scc1 .Lrdx_eq
	s_cmpk_lt_i32 s8, 0x100
	s_cselect_b32 s6, -1, 0
	s_cselect_b32 s57, s8, s57
	s_xor_b32 s59, s58, s6
	v_bitop3_b32 v7, v7, v110, s59 bitop3:0x60
	v_bitop3_b32 v3, v3, v8, s6 bitop3:0xf8
	v_bitop3_b32 v8, v7, v108, s58 bitop3:0x60
	v_bcnt_u32_b32 v12, v8, 0
	s_nop 1
	v_add_u32_dpp v12, v12, v12 row_ror:8 row_mask:0xf bank_mask:0xf bound_ctrl:1
	s_nop 1
	v_add_u32_dpp v12, v12, v12 row_ror:4 row_mask:0xf bank_mask:0xf bound_ctrl:1
	s_nop 1
	v_add_u32_dpp v12, v12, v12 row_ror:2 row_mask:0xf bank_mask:0xf bound_ctrl:1
	s_nop 1
	v_add_u32_dpp v12, v12, v12 row_ror:1 row_mask:0xf bank_mask:0xf bound_ctrl:1
	s_nop 0
	v_readlane_b32 s6, v12, 0
	v_readlane_b32 s7, v12, 16
	v_readlane_b32 s8, v12, 32
	v_readlane_b32 s9, v12, 48
	s_add_i32 s6, s6, s7
	s_add_i32 s8, s8, s9
	s_add_i32 s6, s6, s57
	s_add_i32 s8, s6, s8
	s_cmpk_eq_i32 s8, 0x100
	s_cbranch_scc1 .Lrdx_eq
	s_cmpk_lt_i32 s8, 0x100
	s_cselect_b32 s6, -1, 0
	s_cselect_b32 s57, s8, s57
	s_xor_b32 s59, s58, s6
	v_bitop3_b32 v7, v7, v108, s59 bitop3:0x60
	v_bitop3_b32 v3, v3, v8, s6 bitop3:0xf8
	s_branch .LBB0_1099
.Lrdx_w2:
	v_mov_b32_e32 v10, 0
	v_mov_b32_e32 v11, 0
	s_mov_b32 s58, -1
	v_bitop3_b32 v8, v7, v189, s58 bitop3:0x60
	v_bitop3_b32 v9, v6, v186, s58 bitop3:0x60
	v_bcnt_u32_b32 v12, v8, 0
	v_bcnt_u32_b32 v12, v9, v12
	s_nop 1
	v_add_u32_dpp v12, v12, v12 row_ror:8 row_mask:0xf bank_mask:0xf bound_ctrl:1
	s_nop 1
	v_add_u32_dpp v12, v12, v12 row_ror:4 row_mask:0xf bank_mask:0xf bound_ctrl:1
	s_nop 1
	v_add_u32_dpp v12, v12, v12 row_ror:2 row_mask:0xf bank_mask:0xf bound_ctrl:1
	s_nop 1
	v_add_u32_dpp v12, v12, v12 row_ror:1 row_mask:0xf bank_mask:0xf bound_ctrl:1
	s_nop 0
	v_readlane_b32 s6, v12, 0
	v_readlane_b32 s7, v12, 16
	v_readlane_b32 s8, v12, 32
	v_readlane_b32 s9, v12, 48
	s_add_i32 s6, s6, s7
	s_add_i32 s8, s8, s9
	s_add_i32 s6, s6, s57
	s_add_i32 s8, s6, s8
	s_cmpk_eq_i32 s8, 0x100
	s_cbranch_scc1 .Lrdx_eq
	s_cmpk_lt_i32 s8, 0x100
	s_cselect_b32 s6, -1, 0
	s_cselect_b32 s57, s8, s57
	s_xor_b32 s59, s58, s6
	v_bitop3_b32 v7, v7, v189, s59 bitop3:0x60
	v_bitop3_b32 v6, v6, v186, s59 bitop3:0x60
	s_mov_b32 s58, s6
	v_bitop3_b32 v3, v3, v8, s6 bitop3:0xf8
	v_bitop3_b32 v2, v2, v9, s6 bitop3:0xf8
	v_bitop3_b32 v8, v7, v188, s58 bitop3:0x60
	v_bitop3_b32 v9, v6, v185, s58 bitop3:0x60
	v_bcnt_u32_b32 v12, v8, 0
	v_bcnt_u32_b32 v12, v9, v12
	s_nop 1
	v_add_u32_dpp v12, v12, v12 row_ror:8 row_mask:0xf bank_mask:0xf bound_ctrl:1
	s_nop 1
	v_add_u32_dpp v12, v12, v12 row_ror:4 row_mask:0xf bank_mask:0xf bound_ctrl:1
	s_nop 1
	v_add_u32_dpp v12, v12, v12 row_ror:2 row_mask:0xf bank_mask:0xf bound_ctrl:1
	s_nop 1
	v_add_u32_dpp v12, v12, v12 row_ror:1 row_mask:0xf bank_mask:0xf bound_ctrl:1
	s_nop 0
	v_readlane_b32 s6, v12, 0
	v_readlane_b32 s7, v12, 16
	v_readlane_b32 s8, v12, 32
	v_readlane_b32 s9, v12, 48
	s_add_i32 s6, s6, s7
	s_add_i32 s8, s8, s9
	s_add_i32 s6, s6, s57
	s_add_i32 s8, s6, s8
	s_cmpk_eq_i32 s8, 0x100
	s_cbranch_scc1 .Lrdx_eq
	s_cmpk_lt_i32 s8, 0x100
	s_cselect_b32 s6, -1, 0
	s_cselect_b32 s57, s8, s57
	s_xor_b32 s59, s58, s6
	v_bitop3_b32 v7, v7, v188, s59 bitop3:0x60
	v_bitop3_b32 v6, v6, v185, s59 bitop3:0x60
	v_bitop3_b32 v3, v3, v8, s6 bitop3:0xf8
	v_bitop3_b32 v2, v2, v9, s6 bitop3:0xf8
	v_bitop3_b32 v8, v7, v187, s58 bitop3:0x60
	v_bitop3_b32 v9, v6, v183, s58 bitop3:0x60
	v_bcnt_u32_b32 v12, v8, 0
	v_bcnt_u32_b32 v12, v9, v12
	s_nop 1
	v_add_u32_dpp v12, v12, v12 row_ror:8 row_mask:0xf bank_mask:0xf bound_ctrl:1
	s_nop 1
	v_add_u32_dpp v12, v12, v12 row_ror:4 row_mask:0xf bank_mask:0xf bound_ctrl:1
	s_nop 1
	v_add_u32_dpp v12, v12, v12 row_ror:2 row_mask:0xf bank_mask:0xf bound_ctrl:1
	s_nop 1
	v_add_u32_dpp v12, v12, v12 row_ror:1 row_mask:0xf bank_mask:0xf bound_ctrl:1
	s_nop 0
	v_readlane_b32 s6, v12, 0
	v_readlane_b32 s7, v12, 16
	v_readlane_b32 s8, v12, 32
	v_readlane_b32 s9, v12, 48
	s_add_i32 s6, s6, s7
	s_add_i32 s8, s8, s9
	s_add_i32 s6, s6, s57
	s_add_i32 s8, s6, s8
	s_cmpk_eq_i32 s8, 0x100
	s_cbranch_scc1 .Lrdx_eq
	s_cmpk_lt_i32 s8, 0x100
	s_cselect_b32 s6, -1, 0
	s_cselect_b32 s57, s8, s57
	s_xor_b32 s59, s58, s6
	v_bitop3_b32 v7, v7, v187, s59 bitop3:0x60
	v_bitop3_b32 v6, v6, v183, s59 bitop3:0x60
	v_bitop3_b32 v3, v3, v8, s6 bitop3:0xf8
	v_bitop3_b32 v2, v2, v9, s6 bitop3:0xf8
	v_bitop3_b32 v8, v7, v184, s58 bitop3:0x60
	v_bitop3_b32 v9, v6, v161, s58 bitop3:0x60
	v_bcnt_u32_b32 v12, v8, 0
	v_bcnt_u32_b32 v12, v9, v12
	s_nop 1
	v_add_u32_dpp v12, v12, v12 row_ror:8 row_mask:0xf bank_mask:0xf bound_ctrl:1
	s_nop 1
	v_add_u32_dpp v12, v12, v12 row_ror:4 row_mask:0xf bank_mask:0xf bound_ctrl:1
	s_nop 1
	v_add_u32_dpp v12, v12, v12 row_ror:2 row_mask:0xf bank_mask:0xf bound_ctrl:1
	s_nop 1
	v_add_u32_dpp v12, v12, v12 row_ror:1 row_mask:0xf bank_mask:0xf bound_ctrl:1
	s_nop 0
	v_readlane_b32 s6, v12, 0
	v_readlane_b32 s7, v12, 16
	v_readlane_b32 s8, v12, 32
	v_readlane_b32 s9, v12, 48
	s_add_i32 s6, s6, s7
	s_add_i32 s8, s8, s9
	s_add_i32 s6, s6, s57
	s_add_i32 s8, s6, s8
	s_cmpk_eq_i32 s8, 0x100
	s_cbranch_scc1 .Lrdx_eq
	s_cmpk_lt_i32 s8, 0x100
	s_cselect_b32 s6, -1, 0
	s_cselect_b32 s57, s8, s57
	s_xor_b32 s59, s58, s6
	v_bitop3_b32 v7, v7, v184, s59 bitop3:0x60
	v_bitop3_b32 v6, v6, v161, s59 bitop3:0x60
	v_bitop3_b32 v3, v3, v8, s6 bitop3:0xf8
	v_bitop3_b32 v2, v2, v9, s6 bitop3:0xf8
	v_bitop3_b32 v8, v7, v181, s58 bitop3:0x60
	v_bitop3_b32 v9, v6, v159, s58 bitop3:0x60
	v_bcnt_u32_b32 v12, v8, 0
	v_bcnt_u32_b32 v12, v9, v12
	s_nop 1
	v_add_u32_dpp v12, v12, v12 row_ror:8 row_mask:0xf bank_mask:0xf bound_ctrl:1
	s_nop 1
	v_add_u32_dpp v12, v12, v12 row_ror:4 row_mask:0xf bank_mask:0xf bound_ctrl:1
	s_nop 1
	v_add_u32_dpp v12, v12, v12 row_ror:2 row_mask:0xf bank_mask:0xf bound_ctrl:1
	s_nop 1
	v_add_u32_dpp v12, v12, v12 row_ror:1 row_mask:0xf bank_mask:0xf bound_ctrl:1
	s_nop 0
	v_readlane_b32 s6, v12, 0
	v_readlane_b32 s7, v12, 16
	v_readlane_b32 s8, v12, 32
	v_readlane_b32 s9, v12, 48
	s_add_i32 s6, s6, s7
	s_add_i32 s8, s8, s9
	s_add_i32 s6, s6, s57
	s_add_i32 s8, s6, s8
	s_cmpk_eq_i32 s8, 0x100
	s_cbranch_scc1 .Lrdx_eq
	s_cmpk_lt_i32 s8, 0x100
	s_cselect_b32 s6, -1, 0
	s_cselect_b32 s57, s8, s57
	s_xor_b32 s59, s58, s6
	v_bitop3_b32 v7, v7, v181, s59 bitop3:0x60
	v_bitop3_b32 v6, v6, v159, s59 bitop3:0x60
	v_bitop3_b32 v3, v3, v8, s6 bitop3:0xf8
	v_bitop3_b32 v2, v2, v9, s6 bitop3:0xf8
	v_bitop3_b32 v8, v7, v160, s58 bitop3:0x60
	v_bitop3_b32 v9, v6, v157, s58 bitop3:0x60
	v_bcnt_u32_b32 v12, v8, 0
	v_bcnt_u32_b32 v12, v9, v12
	s_nop 1
	v_add_u32_dpp v12, v12, v12 row_ror:8 row_mask:0xf bank_mask:0xf bound_ctrl:1
	s_nop 1
	v_add_u32_dpp v12, v12, v12 row_ror:4 row_mask:0xf bank_mask:0xf bound_ctrl:1
	s_nop 1
	v_add_u32_dpp v12, v12, v12 row_ror:2 row_mask:0xf bank_mask:0xf bound_ctrl:1
	s_nop 1
	v_add_u32_dpp v12, v12, v12 row_ror:1 row_mask:0xf bank_mask:0xf bound_ctrl:1
	s_nop 0
	v_readlane_b32 s6, v12, 0
	v_readlane_b32 s7, v12, 16
	v_readlane_b32 s8, v12, 32
	v_readlane_b32 s9, v12, 48
	s_add_i32 s6, s6, s7
	s_add_i32 s8, s8, s9
	s_add_i32 s6, s6, s57
	s_add_i32 s8, s6, s8
	s_cmpk_eq_i32 s8, 0x100
	s_cbranch_scc1 .Lrdx_eq
	s_cmpk_lt_i32 s8, 0x100
	s_cselect_b32 s6, -1, 0
	s_cselect_b32 s57, s8, s57
	s_xor_b32 s59, s58, s6
	v_bitop3_b32 v7, v7, v160, s59 bitop3:0x60
	v_bitop3_b32 v6, v6, v157, s59 bitop3:0x60
	v_bitop3_b32 v3, v3, v8, s6 bitop3:0xf8
	v_bitop3_b32 v2, v2, v9, s6 bitop3:0xf8
	v_bitop3_b32 v8, v7, v158, s58 bitop3:0x60
	v_bitop3_b32 v9, v6, v155, s58 bitop3:0x60
	v_bcnt_u32_b32 v12, v8, 0
	v_bcnt_u32_b32 v12, v9, v12
	s_nop 1
	v_add_u32_dpp v12, v12, v12 row_ror:8 row_mask:0xf bank_mask:0xf bound_ctrl:1
	s_nop 1
	v_add_u32_dpp v12, v12, v12 row_ror:4 row_mask:0xf bank_mask:0xf bound_ctrl:1
	s_nop 1
	v_add_u32_dpp v12, v12, v12 row_ror:2 row_mask:0xf bank_mask:0xf bound_ctrl:1
	s_nop 1
	v_add_u32_dpp v12, v12, v12 row_ror:1 row_mask:0xf bank_mask:0xf bound_ctrl:1
	s_nop 0
	v_readlane_b32 s6, v12, 0
	v_readlane_b32 s7, v12, 16
	v_readlane_b32 s8, v12, 32
	v_readlane_b32 s9, v12, 48
	s_add_i32 s6, s6, s7
	s_add_i32 s8, s8, s9
	s_add_i32 s6, s6, s57
	s_add_i32 s8, s6, s8
	s_cmpk_eq_i32 s8, 0x100
	s_cbranch_scc1 .Lrdx_eq
	s_cmpk_lt_i32 s8, 0x100
	s_cselect_b32 s6, -1, 0
	s_cselect_b32 s57, s8, s57
	s_xor_b32 s59, s58, s6
	v_bitop3_b32 v7, v7, v158, s59 bitop3:0x60
	v_bitop3_b32 v6, v6, v155, s59 bitop3:0x60
	v_bitop3_b32 v3, v3, v8, s6 bitop3:0xf8
	v_bitop3_b32 v2, v2, v9, s6 bitop3:0xf8
	v_bitop3_b32 v8, v7, v156, s58 bitop3:0x60
	v_bitop3_b32 v9, v6, v153, s58 bitop3:0x60
	v_bcnt_u32_b32 v12, v8, 0
	v_bcnt_u32_b32 v12, v9, v12
	s_nop 1
	v_add_u32_dpp v12, v12, v12 row_ror:8 row_mask:0xf bank_mask:0xf bound_ctrl:1
	s_nop 1
	v_add_u32_dpp v12, v12, v12 row_ror:4 row_mask:0xf bank_mask:0xf bound_ctrl:1
	s_nop 1
	v_add_u32_dpp v12, v12, v12 row_ror:2 row_mask:0xf bank_mask:0xf bound_ctrl:1
	s_nop 1
	v_add_u32_dpp v12, v12, v12 row_ror:1 row_mask:0xf bank_mask:0xf bound_ctrl:1
	s_nop 0
	v_readlane_b32 s6, v12, 0
	v_readlane_b32 s7, v12, 16
	v_readlane_b32 s8, v12, 32
	v_readlane_b32 s9, v12, 48
	s_add_i32 s6, s6, s7
	s_add_i32 s8, s8, s9
	s_add_i32 s6, s6, s57
	s_add_i32 s8, s6, s8
	s_cmpk_eq_i32 s8, 0x100
	s_cbranch_scc1 .Lrdx_eq
	s_cmpk_lt_i32 s8, 0x100
	s_cselect_b32 s6, -1, 0
	s_cselect_b32 s57, s8, s57
	s_xor_b32 s59, s58, s6
	v_bitop3_b32 v7, v7, v156, s59 bitop3:0x60
	v_bitop3_b32 v6, v6, v153, s59 bitop3:0x60
	v_bitop3_b32 v3, v3, v8, s6 bitop3:0xf8
	v_bitop3_b32 v2, v2, v9, s6 bitop3:0xf8
	v_bitop3_b32 v8, v7, v154, s58 bitop3:0x60
	v_bitop3_b32 v9, v6, v151, s58 bitop3:0x60
	v_bcnt_u32_b32 v12, v8, 0
	v_bcnt_u32_b32 v12, v9, v12
	s_nop 1
	v_add_u32_dpp v12, v12, v12 row_ror:8 row_mask:0xf bank_mask:0xf bound_ctrl:1
	s_nop 1
	v_add_u32_dpp v12, v12, v12 row_ror:4 row_mask:0xf bank_mask:0xf bound_ctrl:1
	s_nop 1
	v_add_u32_dpp v12, v12, v12 row_ror:2 row_mask:0xf bank_mask:0xf bound_ctrl:1
	s_nop 1
	v_add_u32_dpp v12, v12, v12 row_ror:1 row_mask:0xf bank_mask:0xf bound_ctrl:1
	s_nop 0
	v_readlane_b32 s6, v12, 0
	v_readlane_b32 s7, v12, 16
	v_readlane_b32 s8, v12, 32
	v_readlane_b32 s9, v12, 48
	s_add_i32 s6, s6, s7
	s_add_i32 s8, s8, s9
	s_add_i32 s6, s6, s57
	s_add_i32 s8, s6, s8
	s_cmpk_eq_i32 s8, 0x100
	s_cbranch_scc1 .Lrdx_eq
	s_cmpk_lt_i32 s8, 0x100
	s_cselect_b32 s6, -1, 0
	s_cselect_b32 s57, s8, s57
	s_xor_b32 s59, s58, s6
	v_bitop3_b32 v7, v7, v154, s59 bitop3:0x60
	v_bitop3_b32 v6, v6, v151, s59 bitop3:0x60
	v_bitop3_b32 v3, v3, v8, s6 bitop3:0xf8
	v_bitop3_b32 v2, v2, v9, s6 bitop3:0xf8
	v_bitop3_b32 v8, v7, v152, s58 bitop3:0x60
	v_bitop3_b32 v9, v6, v149, s58 bitop3:0x60
	v_bcnt_u32_b32 v12, v8, 0
	v_bcnt_u32_b32 v12, v9, v12
	s_nop 1
	v_add_u32_dpp v12, v12, v12 row_ror:8 row_mask:0xf bank_mask:0xf bound_ctrl:1
	s_nop 1
	v_add_u32_dpp v12, v12, v12 row_ror:4 row_mask:0xf bank_mask:0xf bound_ctrl:1
	s_nop 1
	v_add_u32_dpp v12, v12, v12 row_ror:2 row_mask:0xf bank_mask:0xf bound_ctrl:1
	s_nop 1
	v_add_u32_dpp v12, v12, v12 row_ror:1 row_mask:0xf bank_mask:0xf bound_ctrl:1
	s_nop 0
	v_readlane_b32 s6, v12, 0
	v_readlane_b32 s7, v12, 16
	v_readlane_b32 s8, v12, 32
	v_readlane_b32 s9, v12, 48
	s_add_i32 s6, s6, s7
	s_add_i32 s8, s8, s9
	s_add_i32 s6, s6, s57
	s_add_i32 s8, s6, s8
	s_cmpk_eq_i32 s8, 0x100
	s_cbranch_scc1 .Lrdx_eq
	s_cmpk_lt_i32 s8, 0x100
	s_cselect_b32 s6, -1, 0
	s_cselect_b32 s57, s8, s57
	s_xor_b32 s59, s58, s6
	v_bitop3_b32 v7, v7, v152, s59 bitop3:0x60
	v_bitop3_b32 v6, v6, v149, s59 bitop3:0x60
	v_bitop3_b32 v3, v3, v8, s6 bitop3:0xf8
	v_bitop3_b32 v2, v2, v9, s6 bitop3:0xf8
	v_bitop3_b32 v8, v7, v150, s58 bitop3:0x60
	v_bitop3_b32 v9, v6, v147, s58 bitop3:0x60
	v_bcnt_u32_b32 v12, v8, 0
	v_bcnt_u32_b32 v12, v9, v12
	s_nop 1
	v_add_u32_dpp v12, v12, v12 row_ror:8 row_mask:0xf bank_mask:0xf bound_ctrl:1
	s_nop 1
	v_add_u32_dpp v12, v12, v12 row_ror:4 row_mask:0xf bank_mask:0xf bound_ctrl:1
	s_nop 1
	v_add_u32_dpp v12, v12, v12 row_ror:2 row_mask:0xf bank_mask:0xf bound_ctrl:1
	s_nop 1
	v_add_u32_dpp v12, v12, v12 row_ror:1 row_mask:0xf bank_mask:0xf bound_ctrl:1
	s_nop 0
	v_readlane_b32 s6, v12, 0
	v_readlane_b32 s7, v12, 16
	v_readlane_b32 s8, v12, 32
	v_readlane_b32 s9, v12, 48
	s_add_i32 s6, s6, s7
	s_add_i32 s8, s8, s9
	s_add_i32 s6, s6, s57
	s_add_i32 s8, s6, s8
	s_cmpk_eq_i32 s8, 0x100
	s_cbranch_scc1 .Lrdx_eq
	s_cmpk_lt_i32 s8, 0x100
	s_cselect_b32 s6, -1, 0
	s_cselect_b32 s57, s8, s57
	s_xor_b32 s59, s58, s6
	v_bitop3_b32 v7, v7, v150, s59 bitop3:0x60
	v_bitop3_b32 v6, v6, v147, s59 bitop3:0x60
	v_bitop3_b32 v3, v3, v8, s6 bitop3:0xf8
	v_bitop3_b32 v2, v2, v9, s6 bitop3:0xf8
	v_bitop3_b32 v8, v7, v148, s58 bitop3:0x60
	v_bitop3_b32 v9, v6, v145, s58 bitop3:0x60
	v_bcnt_u32_b32 v12, v8, 0
	v_bcnt_u32_b32 v12, v9, v12
	s_nop 1
	v_add_u32_dpp v12, v12, v12 row_ror:8 row_mask:0xf bank_mask:0xf bound_ctrl:1
	s_nop 1
	v_add_u32_dpp v12, v12, v12 row_ror:4 row_mask:0xf bank_mask:0xf bound_ctrl:1
	s_nop 1
	v_add_u32_dpp v12, v12, v12 row_ror:2 row_mask:0xf bank_mask:0xf bound_ctrl:1
	s_nop 1
	v_add_u32_dpp v12, v12, v12 row_ror:1 row_mask:0xf bank_mask:0xf bound_ctrl:1
	s_nop 0
	v_readlane_b32 s6, v12, 0
	v_readlane_b32 s7, v12, 16
	v_readlane_b32 s8, v12, 32
	v_readlane_b32 s9, v12, 48
	s_add_i32 s6, s6, s7
	s_add_i32 s8, s8, s9
	s_add_i32 s6, s6, s57
	s_add_i32 s8, s6, s8
	s_cmpk_eq_i32 s8, 0x100
	s_cbranch_scc1 .Lrdx_eq
	s_cmpk_lt_i32 s8, 0x100
	s_cselect_b32 s6, -1, 0
	s_cselect_b32 s57, s8, s57
	s_xor_b32 s59, s58, s6
	v_bitop3_b32 v7, v7, v148, s59 bitop3:0x60
	v_bitop3_b32 v6, v6, v145, s59 bitop3:0x60
	v_bitop3_b32 v3, v3, v8, s6 bitop3:0xf8
	v_bitop3_b32 v2, v2, v9, s6 bitop3:0xf8
	v_bitop3_b32 v8, v7, v146, s58 bitop3:0x60
	v_bitop3_b32 v9, v6, v143, s58 bitop3:0x60
	v_bcnt_u32_b32 v12, v8, 0
	v_bcnt_u32_b32 v12, v9, v12
	s_nop 1
	v_add_u32_dpp v12, v12, v12 row_ror:8 row_mask:0xf bank_mask:0xf bound_ctrl:1
	s_nop 1
	v_add_u32_dpp v12, v12, v12 row_ror:4 row_mask:0xf bank_mask:0xf bound_ctrl:1
	s_nop 1
	v_add_u32_dpp v12, v12, v12 row_ror:2 row_mask:0xf bank_mask:0xf bound_ctrl:1
	s_nop 1
	v_add_u32_dpp v12, v12, v12 row_ror:1 row_mask:0xf bank_mask:0xf bound_ctrl:1
	s_nop 0
	v_readlane_b32 s6, v12, 0
	v_readlane_b32 s7, v12, 16
	v_readlane_b32 s8, v12, 32
	v_readlane_b32 s9, v12, 48
	s_add_i32 s6, s6, s7
	s_add_i32 s8, s8, s9
	s_add_i32 s6, s6, s57
	s_add_i32 s8, s6, s8
	s_cmpk_eq_i32 s8, 0x100
	s_cbranch_scc1 .Lrdx_eq
	s_cmpk_lt_i32 s8, 0x100
	s_cselect_b32 s6, -1, 0
	s_cselect_b32 s57, s8, s57
	s_xor_b32 s59, s58, s6
	v_bitop3_b32 v7, v7, v146, s59 bitop3:0x60
	v_bitop3_b32 v6, v6, v143, s59 bitop3:0x60
	v_bitop3_b32 v3, v3, v8, s6 bitop3:0xf8
	v_bitop3_b32 v2, v2, v9, s6 bitop3:0xf8
	v_bitop3_b32 v8, v7, v144, s58 bitop3:0x60
	v_bitop3_b32 v9, v6, v141, s58 bitop3:0x60
	v_bcnt_u32_b32 v12, v8, 0
	v_bcnt_u32_b32 v12, v9, v12
	s_nop 1
	v_add_u32_dpp v12, v12, v12 row_ror:8 row_mask:0xf bank_mask:0xf bound_ctrl:1
	s_nop 1
	v_add_u32_dpp v12, v12, v12 row_ror:4 row_mask:0xf bank_mask:0xf bound_ctrl:1
	s_nop 1
	v_add_u32_dpp v12, v12, v12 row_ror:2 row_mask:0xf bank_mask:0xf bound_ctrl:1
	s_nop 1
	v_add_u32_dpp v12, v12, v12 row_ror:1 row_mask:0xf bank_mask:0xf bound_ctrl:1
	s_nop 0
	v_readlane_b32 s6, v12, 0
	v_readlane_b32 s7, v12, 16
	v_readlane_b32 s8, v12, 32
	v_readlane_b32 s9, v12, 48
	s_add_i32 s6, s6, s7
	s_add_i32 s8, s8, s9
	s_add_i32 s6, s6, s57
	s_add_i32 s8, s6, s8
	s_cmpk_eq_i32 s8, 0x100
	s_cbranch_scc1 .Lrdx_eq
	s_cmpk_lt_i32 s8, 0x100
	s_cselect_b32 s6, -1, 0
	s_cselect_b32 s57, s8, s57
	s_xor_b32 s59, s58, s6
	v_bitop3_b32 v7, v7, v144, s59 bitop3:0x60
	v_bitop3_b32 v6, v6, v141, s59 bitop3:0x60
	v_bitop3_b32 v3, v3, v8, s6 bitop3:0xf8
	v_bitop3_b32 v2, v2, v9, s6 bitop3:0xf8
	v_bitop3_b32 v8, v7, v142, s58 bitop3:0x60
	v_bitop3_b32 v9, v6, v139, s58 bitop3:0x60
	v_bcnt_u32_b32 v12, v8, 0
	v_bcnt_u32_b32 v12, v9, v12
	s_nop 1
	v_add_u32_dpp v12, v12, v12 row_ror:8 row_mask:0xf bank_mask:0xf bound_ctrl:1
	s_nop 1
	v_add_u32_dpp v12, v12, v12 row_ror:4 row_mask:0xf bank_mask:0xf bound_ctrl:1
	s_nop 1
	v_add_u32_dpp v12, v12, v12 row_ror:2 row_mask:0xf bank_mask:0xf bound_ctrl:1
	s_nop 1
	v_add_u32_dpp v12, v12, v12 row_ror:1 row_mask:0xf bank_mask:0xf bound_ctrl:1
	s_nop 0
	v_readlane_b32 s6, v12, 0
	v_readlane_b32 s7, v12, 16
	v_readlane_b32 s8, v12, 32
	v_readlane_b32 s9, v12, 48
	s_add_i32 s6, s6, s7
	s_add_i32 s8, s8, s9
	s_add_i32 s6, s6, s57
	s_add_i32 s8, s6, s8
	s_cmpk_eq_i32 s8, 0x100
	s_cbranch_scc1 .Lrdx_eq
	s_cmpk_lt_i32 s8, 0x100
	s_cselect_b32 s6, -1, 0
	s_cselect_b32 s57, s8, s57
	s_xor_b32 s59, s58, s6
	v_bitop3_b32 v7, v7, v142, s59 bitop3:0x60
	v_bitop3_b32 v6, v6, v139, s59 bitop3:0x60
	v_bitop3_b32 v3, v3, v8, s6 bitop3:0xf8
	v_bitop3_b32 v2, v2, v9, s6 bitop3:0xf8
	v_bitop3_b32 v8, v7, v140, s58 bitop3:0x60
	v_bitop3_b32 v9, v6, v137, s58 bitop3:0x60
	v_bcnt_u32_b32 v12, v8, 0
	v_bcnt_u32_b32 v12, v9, v12
	s_nop 1
	v_add_u32_dpp v12, v12, v12 row_ror:8 row_mask:0xf bank_mask:0xf bound_ctrl:1
	s_nop 1
	v_add_u32_dpp v12, v12, v12 row_ror:4 row_mask:0xf bank_mask:0xf bound_ctrl:1
	s_nop 1
	v_add_u32_dpp v12, v12, v12 row_ror:2 row_mask:0xf bank_mask:0xf bound_ctrl:1
	s_nop 1
	v_add_u32_dpp v12, v12, v12 row_ror:1 row_mask:0xf bank_mask:0xf bound_ctrl:1
	s_nop 0
	v_readlane_b32 s6, v12, 0
	v_readlane_b32 s7, v12, 16
	v_readlane_b32 s8, v12, 32
	v_readlane_b32 s9, v12, 48
	s_add_i32 s6, s6, s7
	s_add_i32 s8, s8, s9
	s_add_i32 s6, s6, s57
	s_add_i32 s8, s6, s8
	s_cmpk_eq_i32 s8, 0x100
	s_cbranch_scc1 .Lrdx_eq
	s_cmpk_lt_i32 s8, 0x100
	s_cselect_b32 s6, -1, 0
	s_cselect_b32 s57, s8, s57
	s_xor_b32 s59, s58, s6
	v_bitop3_b32 v7, v7, v140, s59 bitop3:0x60
	v_bitop3_b32 v6, v6, v137, s59 bitop3:0x60
	v_bitop3_b32 v3, v3, v8, s6 bitop3:0xf8
	v_bitop3_b32 v2, v2, v9, s6 bitop3:0xf8
	v_bitop3_b32 v8, v7, v138, s58 bitop3:0x60
	v_bitop3_b32 v9, v6, v135, s58 bitop3:0x60
	v_bcnt_u32_b32 v12, v8, 0
	v_bcnt_u32_b32 v12, v9, v12
	s_nop 1
	v_add_u32_dpp v12, v12, v12 row_ror:8 row_mask:0xf bank_mask:0xf bound_ctrl:1
	s_nop 1
	v_add_u32_dpp v12, v12, v12 row_ror:4 row_mask:0xf bank_mask:0xf bound_ctrl:1
	s_nop 1
	v_add_u32_dpp v12, v12, v12 row_ror:2 row_mask:0xf bank_mask:0xf bound_ctrl:1
	s_nop 1
	v_add_u32_dpp v12, v12, v12 row_ror:1 row_mask:0xf bank_mask:0xf bound_ctrl:1
	s_nop 0
	v_readlane_b32 s6, v12, 0
	v_readlane_b32 s7, v12, 16
	v_readlane_b32 s8, v12, 32
	v_readlane_b32 s9, v12, 48
	s_add_i32 s6, s6, s7
	s_add_i32 s8, s8, s9
	s_add_i32 s6, s6, s57
	s_add_i32 s8, s6, s8
	s_cmpk_eq_i32 s8, 0x100
	s_cbranch_scc1 .Lrdx_eq
	s_cmpk_lt_i32 s8, 0x100
	s_cselect_b32 s6, -1, 0
	s_cselect_b32 s57, s8, s57
	s_xor_b32 s59, s58, s6
	v_bitop3_b32 v7, v7, v138, s59 bitop3:0x60
	v_bitop3_b32 v6, v6, v135, s59 bitop3:0x60
	v_bitop3_b32 v3, v3, v8, s6 bitop3:0xf8
	v_bitop3_b32 v2, v2, v9, s6 bitop3:0xf8
	v_bitop3_b32 v8, v7, v136, s58 bitop3:0x60
	v_bitop3_b32 v9, v6, v133, s58 bitop3:0x60
	v_bcnt_u32_b32 v12, v8, 0
	v_bcnt_u32_b32 v12, v9, v12
	s_nop 1
	v_add_u32_dpp v12, v12, v12 row_ror:8 row_mask:0xf bank_mask:0xf bound_ctrl:1
	s_nop 1
	v_add_u32_dpp v12, v12, v12 row_ror:4 row_mask:0xf bank_mask:0xf bound_ctrl:1
	s_nop 1
	v_add_u32_dpp v12, v12, v12 row_ror:2 row_mask:0xf bank_mask:0xf bound_ctrl:1
	s_nop 1
	v_add_u32_dpp v12, v12, v12 row_ror:1 row_mask:0xf bank_mask:0xf bound_ctrl:1
	s_nop 0
	v_readlane_b32 s6, v12, 0
	v_readlane_b32 s7, v12, 16
	v_readlane_b32 s8, v12, 32
	v_readlane_b32 s9, v12, 48
	s_add_i32 s6, s6, s7
	s_add_i32 s8, s8, s9
	s_add_i32 s6, s6, s57
	s_add_i32 s8, s6, s8
	s_cmpk_eq_i32 s8, 0x100
	s_cbranch_scc1 .Lrdx_eq
	s_cmpk_lt_i32 s8, 0x100
	s_cselect_b32 s6, -1, 0
	s_cselect_b32 s57, s8, s57
	s_xor_b32 s59, s58, s6
	v_bitop3_b32 v7, v7, v136, s59 bitop3:0x60
	v_bitop3_b32 v6, v6, v133, s59 bitop3:0x60
	v_bitop3_b32 v3, v3, v8, s6 bitop3:0xf8
	v_bitop3_b32 v2, v2, v9, s6 bitop3:0xf8
	v_bitop3_b32 v8, v7, v134, s58 bitop3:0x60
	v_bitop3_b32 v9, v6, v131, s58 bitop3:0x60
	v_bcnt_u32_b32 v12, v8, 0
	v_bcnt_u32_b32 v12, v9, v12
	s_nop 1
	v_add_u32_dpp v12, v12, v12 row_ror:8 row_mask:0xf bank_mask:0xf bound_ctrl:1
	s_nop 1
	v_add_u32_dpp v12, v12, v12 row_ror:4 row_mask:0xf bank_mask:0xf bound_ctrl:1
	s_nop 1
	v_add_u32_dpp v12, v12, v12 row_ror:2 row_mask:0xf bank_mask:0xf bound_ctrl:1
	s_nop 1
	v_add_u32_dpp v12, v12, v12 row_ror:1 row_mask:0xf bank_mask:0xf bound_ctrl:1
	s_nop 0
	v_readlane_b32 s6, v12, 0
	v_readlane_b32 s7, v12, 16
	v_readlane_b32 s8, v12, 32
	v_readlane_b32 s9, v12, 48
	s_add_i32 s6, s6, s7
	s_add_i32 s8, s8, s9
	s_add_i32 s6, s6, s57
	s_add_i32 s8, s6, s8
	s_cmpk_eq_i32 s8, 0x100
	s_cbranch_scc1 .Lrdx_eq
	s_cmpk_lt_i32 s8, 0x100
	s_cselect_b32 s6, -1, 0
	s_cselect_b32 s57, s8, s57
	s_xor_b32 s59, s58, s6
	v_bitop3_b32 v7, v7, v134, s59 bitop3:0x60
	v_bitop3_b32 v6, v6, v131, s59 bitop3:0x60
	v_bitop3_b32 v3, v3, v8, s6 bitop3:0xf8
	v_bitop3_b32 v2, v2, v9, s6 bitop3:0xf8
	v_bitop3_b32 v8, v7, v132, s58 bitop3:0x60
	v_bitop3_b32 v9, v6, v129, s58 bitop3:0x60
	v_bcnt_u32_b32 v12, v8, 0
	v_bcnt_u32_b32 v12, v9, v12
	s_nop 1
	v_add_u32_dpp v12, v12, v12 row_ror:8 row_mask:0xf bank_mask:0xf bound_ctrl:1
	s_nop 1
	v_add_u32_dpp v12, v12, v12 row_ror:4 row_mask:0xf bank_mask:0xf bound_ctrl:1
	s_nop 1
	v_add_u32_dpp v12, v12, v12 row_ror:2 row_mask:0xf bank_mask:0xf bound_ctrl:1
	s_nop 1
	v_add_u32_dpp v12, v12, v12 row_ror:1 row_mask:0xf bank_mask:0xf bound_ctrl:1
	s_nop 0
	v_readlane_b32 s6, v12, 0
	v_readlane_b32 s7, v12, 16
	v_readlane_b32 s8, v12, 32
	v_readlane_b32 s9, v12, 48
	s_add_i32 s6, s6, s7
	s_add_i32 s8, s8, s9
	s_add_i32 s6, s6, s57
	s_add_i32 s8, s6, s8
	s_cmpk_eq_i32 s8, 0x100
	s_cbranch_scc1 .Lrdx_eq
	s_cmpk_lt_i32 s8, 0x100
	s_cselect_b32 s6, -1, 0
	s_cselect_b32 s57, s8, s57
	s_xor_b32 s59, s58, s6
	v_bitop3_b32 v7, v7, v132, s59 bitop3:0x60
	v_bitop3_b32 v6, v6, v129, s59 bitop3:0x60
	v_bitop3_b32 v3, v3, v8, s6 bitop3:0xf8
	v_bitop3_b32 v2, v2, v9, s6 bitop3:0xf8
	v_bitop3_b32 v8, v7, v130, s58 bitop3:0x60
	v_bitop3_b32 v9, v6, v127, s58 bitop3:0x60
	v_bcnt_u32_b32 v12, v8, 0
	v_bcnt_u32_b32 v12, v9, v12
	s_nop 1
	v_add_u32_dpp v12, v12, v12 row_ror:8 row_mask:0xf bank_mask:0xf bound_ctrl:1
	s_nop 1
	v_add_u32_dpp v12, v12, v12 row_ror:4 row_mask:0xf bank_mask:0xf bound_ctrl:1
	s_nop 1
	v_add_u32_dpp v12, v12, v12 row_ror:2 row_mask:0xf bank_mask:0xf bound_ctrl:1
	s_nop 1
	v_add_u32_dpp v12, v12, v12 row_ror:1 row_mask:0xf bank_mask:0xf bound_ctrl:1
	s_nop 0
	v_readlane_b32 s6, v12, 0
	v_readlane_b32 s7, v12, 16
	v_readlane_b32 s8, v12, 32
	v_readlane_b32 s9, v12, 48
	s_add_i32 s6, s6, s7
	s_add_i32 s8, s8, s9
	s_add_i32 s6, s6, s57
	s_add_i32 s8, s6, s8
	s_cmpk_eq_i32 s8, 0x100
	s_cbranch_scc1 .Lrdx_eq
	s_cmpk_lt_i32 s8, 0x100
	s_cselect_b32 s6, -1, 0
	s_cselect_b32 s57, s8, s57
	s_xor_b32 s59, s58, s6
	v_bitop3_b32 v7, v7, v130, s59 bitop3:0x60
	v_bitop3_b32 v6, v6, v127, s59 bitop3:0x60
	v_bitop3_b32 v3, v3, v8, s6 bitop3:0xf8
	v_bitop3_b32 v2, v2, v9, s6 bitop3:0xf8
	v_bitop3_b32 v8, v7, v128, s58 bitop3:0x60
	v_bitop3_b32 v9, v6, v125, s58 bitop3:0x60
	v_bcnt_u32_b32 v12, v8, 0
	v_bcnt_u32_b32 v12, v9, v12
	s_nop 1
	v_add_u32_dpp v12, v12, v12 row_ror:8 row_mask:0xf bank_mask:0xf bound_ctrl:1
	s_nop 1
	v_add_u32_dpp v12, v12, v12 row_ror:4 row_mask:0xf bank_mask:0xf bound_ctrl:1
	s_nop 1
	v_add_u32_dpp v12, v12, v12 row_ror:2 row_mask:0xf bank_mask:0xf bound_ctrl:1
	s_nop 1
	v_add_u32_dpp v12, v12, v12 row_ror:1 row_mask:0xf bank_mask:0xf bound_ctrl:1
	s_nop 0
	v_readlane_b32 s6, v12, 0
	v_readlane_b32 s7, v12, 16
	v_readlane_b32 s8, v12, 32
	v_readlane_b32 s9, v12, 48
	s_add_i32 s6, s6, s7
	s_add_i32 s8, s8, s9
	s_add_i32 s6, s6, s57
	s_add_i32 s8, s6, s8
	s_cmpk_eq_i32 s8, 0x100
	s_cbranch_scc1 .Lrdx_eq
	s_cmpk_lt_i32 s8, 0x100
	s_cselect_b32 s6, -1, 0
	s_cselect_b32 s57, s8, s57
	s_xor_b32 s59, s58, s6
	v_bitop3_b32 v7, v7, v128, s59 bitop3:0x60
	v_bitop3_b32 v6, v6, v125, s59 bitop3:0x60
	v_bitop3_b32 v3, v3, v8, s6 bitop3:0xf8
	v_bitop3_b32 v2, v2, v9, s6 bitop3:0xf8
	v_bitop3_b32 v8, v7, v126, s58 bitop3:0x60
	v_bitop3_b32 v9, v6, v123, s58 bitop3:0x60
	v_bcnt_u32_b32 v12, v8, 0
	v_bcnt_u32_b32 v12, v9, v12
	s_nop 1
	v_add_u32_dpp v12, v12, v12 row_ror:8 row_mask:0xf bank_mask:0xf bound_ctrl:1
	s_nop 1
	v_add_u32_dpp v12, v12, v12 row_ror:4 row_mask:0xf bank_mask:0xf bound_ctrl:1
	s_nop 1
	v_add_u32_dpp v12, v12, v12 row_ror:2 row_mask:0xf bank_mask:0xf bound_ctrl:1
	s_nop 1
	v_add_u32_dpp v12, v12, v12 row_ror:1 row_mask:0xf bank_mask:0xf bound_ctrl:1
	s_nop 0
	v_readlane_b32 s6, v12, 0
	v_readlane_b32 s7, v12, 16
	v_readlane_b32 s8, v12, 32
	v_readlane_b32 s9, v12, 48
	s_add_i32 s6, s6, s7
	s_add_i32 s8, s8, s9
	s_add_i32 s6, s6, s57
	s_add_i32 s8, s6, s8
	s_cmpk_eq_i32 s8, 0x100
	s_cbranch_scc1 .Lrdx_eq
	s_cmpk_lt_i32 s8, 0x100
	s_cselect_b32 s6, -1, 0
	s_cselect_b32 s57, s8, s57
	s_xor_b32 s59, s58, s6
	v_bitop3_b32 v7, v7, v126, s59 bitop3:0x60
	v_bitop3_b32 v6, v6, v123, s59 bitop3:0x60
	v_bitop3_b32 v3, v3, v8, s6 bitop3:0xf8
	v_bitop3_b32 v2, v2, v9, s6 bitop3:0xf8
	v_bitop3_b32 v8, v7, v124, s58 bitop3:0x60
	v_bitop3_b32 v9, v6, v121, s58 bitop3:0x60
	v_bcnt_u32_b32 v12, v8, 0
	v_bcnt_u32_b32 v12, v9, v12
	s_nop 1
	v_add_u32_dpp v12, v12, v12 row_ror:8 row_mask:0xf bank_mask:0xf bound_ctrl:1
	s_nop 1
	v_add_u32_dpp v12, v12, v12 row_ror:4 row_mask:0xf bank_mask:0xf bound_ctrl:1
	s_nop 1
	v_add_u32_dpp v12, v12, v12 row_ror:2 row_mask:0xf bank_mask:0xf bound_ctrl:1
	s_nop 1
	v_add_u32_dpp v12, v12, v12 row_ror:1 row_mask:0xf bank_mask:0xf bound_ctrl:1
	s_nop 0
	v_readlane_b32 s6, v12, 0
	v_readlane_b32 s7, v12, 16
	v_readlane_b32 s8, v12, 32
	v_readlane_b32 s9, v12, 48
	s_add_i32 s6, s6, s7
	s_add_i32 s8, s8, s9
	s_add_i32 s6, s6, s57
	s_add_i32 s8, s6, s8
	s_cmpk_eq_i32 s8, 0x100
	s_cbranch_scc1 .Lrdx_eq
	s_cmpk_lt_i32 s8, 0x100
	s_cselect_b32 s6, -1, 0
	s_cselect_b32 s57, s8, s57
	s_xor_b32 s59, s58, s6
	v_bitop3_b32 v7, v7, v124, s59 bitop3:0x60
	v_bitop3_b32 v6, v6, v121, s59 bitop3:0x60
	v_bitop3_b32 v3, v3, v8, s6 bitop3:0xf8
	v_bitop3_b32 v2, v2, v9, s6 bitop3:0xf8
	v_bitop3_b32 v8, v7, v122, s58 bitop3:0x60
	v_bitop3_b32 v9, v6, v119, s58 bitop3:0x60
	v_bcnt_u32_b32 v12, v8, 0
	v_bcnt_u32_b32 v12, v9, v12
	s_nop 1
	v_add_u32_dpp v12, v12, v12 row_ror:8 row_mask:0xf bank_mask:0xf bound_ctrl:1
	s_nop 1
	v_add_u32_dpp v12, v12, v12 row_ror:4 row_mask:0xf bank_mask:0xf bound_ctrl:1
	s_nop 1
	v_add_u32_dpp v12, v12, v12 row_ror:2 row_mask:0xf bank_mask:0xf bound_ctrl:1
	s_nop 1
	v_add_u32_dpp v12, v12, v12 row_ror:1 row_mask:0xf bank_mask:0xf bound_ctrl:1
	s_nop 0
	v_readlane_b32 s6, v12, 0
	v_readlane_b32 s7, v12, 16
	v_readlane_b32 s8, v12, 32
	v_readlane_b32 s9, v12, 48
	s_add_i32 s6, s6, s7
	s_add_i32 s8, s8, s9
	s_add_i32 s6, s6, s57
	s_add_i32 s8, s6, s8
	s_cmpk_eq_i32 s8, 0x100
	s_cbranch_scc1 .Lrdx_eq
	s_cmpk_lt_i32 s8, 0x100
	s_cselect_b32 s6, -1, 0
	s_cselect_b32 s57, s8, s57
	s_xor_b32 s59, s58, s6
	v_bitop3_b32 v7, v7, v122, s59 bitop3:0x60
	v_bitop3_b32 v6, v6, v119, s59 bitop3:0x60
	v_bitop3_b32 v3, v3, v8, s6 bitop3:0xf8
	v_bitop3_b32 v2, v2, v9, s6 bitop3:0xf8
	v_bitop3_b32 v8, v7, v120, s58 bitop3:0x60
	v_bitop3_b32 v9, v6, v117, s58 bitop3:0x60
	v_bcnt_u32_b32 v12, v8, 0
	v_bcnt_u32_b32 v12, v9, v12
	s_nop 1
	v_add_u32_dpp v12, v12, v12 row_ror:8 row_mask:0xf bank_mask:0xf bound_ctrl:1
	s_nop 1
	v_add_u32_dpp v12, v12, v12 row_ror:4 row_mask:0xf bank_mask:0xf bound_ctrl:1
	s_nop 1
	v_add_u32_dpp v12, v12, v12 row_ror:2 row_mask:0xf bank_mask:0xf bound_ctrl:1
	s_nop 1
	v_add_u32_dpp v12, v12, v12 row_ror:1 row_mask:0xf bank_mask:0xf bound_ctrl:1
	s_nop 0
	v_readlane_b32 s6, v12, 0
	v_readlane_b32 s7, v12, 16
	v_readlane_b32 s8, v12, 32
	v_readlane_b32 s9, v12, 48
	s_add_i32 s6, s6, s7
	s_add_i32 s8, s8, s9
	s_add_i32 s6, s6, s57
	s_add_i32 s8, s6, s8
	s_cmpk_eq_i32 s8, 0x100
	s_cbranch_scc1 .Lrdx_eq
	s_cmpk_lt_i32 s8, 0x100
	s_cselect_b32 s6, -1, 0
	s_cselect_b32 s57, s8, s57
	s_xor_b32 s59, s58, s6
	v_bitop3_b32 v7, v7, v120, s59 bitop3:0x60
	v_bitop3_b32 v6, v6, v117, s59 bitop3:0x60
	v_bitop3_b32 v3, v3, v8, s6 bitop3:0xf8
	v_bitop3_b32 v2, v2, v9, s6 bitop3:0xf8
	v_bitop3_b32 v8, v7, v118, s58 bitop3:0x60
	v_bitop3_b32 v9, v6, v115, s58 bitop3:0x60
	v_bcnt_u32_b32 v12, v8, 0
	v_bcnt_u32_b32 v12, v9, v12
	s_nop 1
	v_add_u32_dpp v12, v12, v12 row_ror:8 row_mask:0xf bank_mask:0xf bound_ctrl:1
	s_nop 1
	v_add_u32_dpp v12, v12, v12 row_ror:4 row_mask:0xf bank_mask:0xf bound_ctrl:1
	s_nop 1
	v_add_u32_dpp v12, v12, v12 row_ror:2 row_mask:0xf bank_mask:0xf bound_ctrl:1
	s_nop 1
	v_add_u32_dpp v12, v12, v12 row_ror:1 row_mask:0xf bank_mask:0xf bound_ctrl:1
	s_nop 0
	v_readlane_b32 s6, v12, 0
	v_readlane_b32 s7, v12, 16
	v_readlane_b32 s8, v12, 32
	v_readlane_b32 s9, v12, 48
	s_add_i32 s6, s6, s7
	s_add_i32 s8, s8, s9
	s_add_i32 s6, s6, s57
	s_add_i32 s8, s6, s8
	s_cmpk_eq_i32 s8, 0x100
	s_cbranch_scc1 .Lrdx_eq
	s_cmpk_lt_i32 s8, 0x100
	s_cselect_b32 s6, -1, 0
	s_cselect_b32 s57, s8, s57
	s_xor_b32 s59, s58, s6
	v_bitop3_b32 v7, v7, v118, s59 bitop3:0x60
	v_bitop3_b32 v6, v6, v115, s59 bitop3:0x60
	v_bitop3_b32 v3, v3, v8, s6 bitop3:0xf8
	v_bitop3_b32 v2, v2, v9, s6 bitop3:0xf8
	v_bitop3_b32 v8, v7, v116, s58 bitop3:0x60
	v_bitop3_b32 v9, v6, v113, s58 bitop3:0x60
	v_bcnt_u32_b32 v12, v8, 0
	v_bcnt_u32_b32 v12, v9, v12
	s_nop 1
	v_add_u32_dpp v12, v12, v12 row_ror:8 row_mask:0xf bank_mask:0xf bound_ctrl:1
	s_nop 1
	v_add_u32_dpp v12, v12, v12 row_ror:4 row_mask:0xf bank_mask:0xf bound_ctrl:1
	s_nop 1
	v_add_u32_dpp v12, v12, v12 row_ror:2 row_mask:0xf bank_mask:0xf bound_ctrl:1
	s_nop 1
	v_add_u32_dpp v12, v12, v12 row_ror:1 row_mask:0xf bank_mask:0xf bound_ctrl:1
	s_nop 0
	v_readlane_b32 s6, v12, 0
	v_readlane_b32 s7, v12, 16
	v_readlane_b32 s8, v12, 32
	v_readlane_b32 s9, v12, 48
	s_add_i32 s6, s6, s7
	s_add_i32 s8, s8, s9
	s_add_i32 s6, s6, s57
	s_add_i32 s8, s6, s8
	s_cmpk_eq_i32 s8, 0x100
	s_cbranch_scc1 .Lrdx_eq
	s_cmpk_lt_i32 s8, 0x100
	s_cselect_b32 s6, -1, 0
	s_cselect_b32 s57, s8, s57
	s_xor_b32 s59, s58, s6
	v_bitop3_b32 v7, v7, v116, s59 bitop3:0x60
	v_bitop3_b32 v6, v6, v113, s59 bitop3:0x60
	v_bitop3_b32 v3, v3, v8, s6 bitop3:0xf8
	v_bitop3_b32 v2, v2, v9, s6 bitop3:0xf8
	v_bitop3_b32 v8, v7, v114, s58 bitop3:0x60
	v_bitop3_b32 v9, v6, v111, s58 bitop3:0x60
	v_bcnt_u32_b32 v12, v8, 0
	v_bcnt_u32_b32 v12, v9, v12
	s_nop 1
	v_add_u32_dpp v12, v12, v12 row_ror:8 row_mask:0xf bank_mask:0xf bound_ctrl:1
	s_nop 1
	v_add_u32_dpp v12, v12, v12 row_ror:4 row_mask:0xf bank_mask:0xf bound_ctrl:1
	s_nop 1
	v_add_u32_dpp v12, v12, v12 row_ror:2 row_mask:0xf bank_mask:0xf bound_ctrl:1
	s_nop 1
	v_add_u32_dpp v12, v12, v12 row_ror:1 row_mask:0xf bank_mask:0xf bound_ctrl:1
	s_nop 0
	v_readlane_b32 s6, v12, 0
	v_readlane_b32 s7, v12, 16
	v_readlane_b32 s8, v12, 32
	v_readlane_b32 s9, v12, 48
	s_add_i32 s6, s6, s7
	s_add_i32 s8, s8, s9
	s_add_i32 s6, s6, s57
	s_add_i32 s8, s6, s8
	s_cmpk_eq_i32 s8, 0x100
	s_cbranch_scc1 .Lrdx_eq
	s_cmpk_lt_i32 s8, 0x100
	s_cselect_b32 s6, -1, 0
	s_cselect_b32 s57, s8, s57
	s_xor_b32 s59, s58, s6
	v_bitop3_b32 v7, v7, v114, s59 bitop3:0x60
	v_bitop3_b32 v6, v6, v111, s59 bitop3:0x60
	v_bitop3_b32 v3, v3, v8, s6 bitop3:0xf8
	v_bitop3_b32 v2, v2, v9, s6 bitop3:0xf8
	v_bitop3_b32 v8, v7, v112, s58 bitop3:0x60
	v_bitop3_b32 v9, v6, v109, s58 bitop3:0x60
	v_bcnt_u32_b32 v12, v8, 0
	v_bcnt_u32_b32 v12, v9, v12
	s_nop 1
	v_add_u32_dpp v12, v12, v12 row_ror:8 row_mask:0xf bank_mask:0xf bound_ctrl:1
	s_nop 1
	v_add_u32_dpp v12, v12, v12 row_ror:4 row_mask:0xf bank_mask:0xf bound_ctrl:1
	s_nop 1
	v_add_u32_dpp v12, v12, v12 row_ror:2 row_mask:0xf bank_mask:0xf bound_ctrl:1
	s_nop 1
	v_add_u32_dpp v12, v12, v12 row_ror:1 row_mask:0xf bank_mask:0xf bound_ctrl:1
	s_nop 0
	v_readlane_b32 s6, v12, 0
	v_readlane_b32 s7, v12, 16
	v_readlane_b32 s8, v12, 32
	v_readlane_b32 s9, v12, 48
	s_add_i32 s6, s6, s7
	s_add_i32 s8, s8, s9
	s_add_i32 s6, s6, s57
	s_add_i32 s8, s6, s8
	s_cmpk_eq_i32 s8, 0x100
	s_cbranch_scc1 .Lrdx_eq
	s_cmpk_lt_i32 s8, 0x100
	s_cselect_b32 s6, -1, 0
	s_cselect_b32 s57, s8, s57
	s_xor_b32 s59, s58, s6
	v_bitop3_b32 v7, v7, v112, s59 bitop3:0x60
	v_bitop3_b32 v6, v6, v109, s59 bitop3:0x60
	v_bitop3_b32 v3, v3, v8, s6 bitop3:0xf8
	v_bitop3_b32 v2, v2, v9, s6 bitop3:0xf8
	v_bitop3_b32 v8, v7, v110, s58 bitop3:0x60
	v_bitop3_b32 v9, v6, v107, s58 bitop3:0x60
	v_bcnt_u32_b32 v12, v8, 0
	v_bcnt_u32_b32 v12, v9, v12
	s_nop 1
	v_add_u32_dpp v12, v12, v12 row_ror:8 row_mask:0xf bank_mask:0xf bound_ctrl:1
	s_nop 1
	v_add_u32_dpp v12, v12, v12 row_ror:4 row_mask:0xf bank_mask:0xf bound_ctrl:1
	s_nop 1
	v_add_u32_dpp v12, v12, v12 row_ror:2 row_mask:0xf bank_mask:0xf bound_ctrl:1
	s_nop 1
	v_add_u32_dpp v12, v12, v12 row_ror:1 row_mask:0xf bank_mask:0xf bound_ctrl:1
	s_nop 0
	v_readlane_b32 s6, v12, 0
	v_readlane_b32 s7, v12, 16
	v_readlane_b32 s8, v12, 32
	v_readlane_b32 s9, v12, 48
	s_add_i32 s6, s6, s7
	s_add_i32 s8, s8, s9
	s_add_i32 s6, s6, s57
	s_add_i32 s8, s6, s8
	s_cmpk_eq_i32 s8, 0x100
	s_cbranch_scc1 .Lrdx_eq
	s_cmpk_lt_i32 s8, 0x100
	s_cselect_b32 s6, -1, 0
	s_cselect_b32 s57, s8, s57
	s_xor_b32 s59, s58, s6
	v_bitop3_b32 v7, v7, v110, s59 bitop3:0x60
	v_bitop3_b32 v6, v6, v107, s59 bitop3:0x60
	v_bitop3_b32 v3, v3, v8, s6 bitop3:0xf8
	v_bitop3_b32 v2, v2, v9, s6 bitop3:0xf8
	v_bitop3_b32 v8, v7, v108, s58 bitop3:0x60
	v_bitop3_b32 v9, v6, v106, s58 bitop3:0x60
	v_bcnt_u32_b32 v12, v8, 0
	v_bcnt_u32_b32 v12, v9, v12
	s_nop 1
	v_add_u32_dpp v12, v12, v12 row_ror:8 row_mask:0xf bank_mask:0xf bound_ctrl:1
	s_nop 1
	v_add_u32_dpp v12, v12, v12 row_ror:4 row_mask:0xf bank_mask:0xf bound_ctrl:1
	s_nop 1
	v_add_u32_dpp v12, v12, v12 row_ror:2 row_mask:0xf bank_mask:0xf bound_ctrl:1
	s_nop 1
	v_add_u32_dpp v12, v12, v12 row_ror:1 row_mask:0xf bank_mask:0xf bound_ctrl:1
	s_nop 0
	v_readlane_b32 s6, v12, 0
	v_readlane_b32 s7, v12, 16
	v_readlane_b32 s8, v12, 32
	v_readlane_b32 s9, v12, 48
	s_add_i32 s6, s6, s7
	s_add_i32 s8, s8, s9
	s_add_i32 s6, s6, s57
	s_add_i32 s8, s6, s8
	s_cmpk_eq_i32 s8, 0x100
	s_cbranch_scc1 .Lrdx_eq
	s_cmpk_lt_i32 s8, 0x100
	s_cselect_b32 s6, -1, 0
	s_cselect_b32 s57, s8, s57
	s_xor_b32 s59, s58, s6
	v_bitop3_b32 v7, v7, v108, s59 bitop3:0x60
	v_bitop3_b32 v6, v6, v106, s59 bitop3:0x60
	v_bitop3_b32 v3, v3, v8, s6 bitop3:0xf8
	v_bitop3_b32 v2, v2, v9, s6 bitop3:0xf8
	s_branch .LBB0_1099
.Lrdx_w3:
	v_mov_b32_e32 v11, 0
	s_mov_b32 s58, -1
	v_bitop3_b32 v8, v7, v189, s58 bitop3:0x60
	v_bitop3_b32 v9, v6, v186, s58 bitop3:0x60
	v_bcnt_u32_b32 v12, v8, 0
	v_bitop3_b32 v10, v5, v95, s58 bitop3:0x60
	v_bcnt_u32_b32 v12, v9, v12
	v_bcnt_u32_b32 v12, v10, v12
	s_nop 1
	v_add_u32_dpp v12, v12, v12 row_ror:8 row_mask:0xf bank_mask:0xf bound_ctrl:1
	s_nop 1
	v_add_u32_dpp v12, v12, v12 row_ror:4 row_mask:0xf bank_mask:0xf bound_ctrl:1
	s_nop 1
	v_add_u32_dpp v12, v12, v12 row_ror:2 row_mask:0xf bank_mask:0xf bound_ctrl:1
	s_nop 1
	v_add_u32_dpp v12, v12, v12 row_ror:1 row_mask:0xf bank_mask:0xf bound_ctrl:1
	s_nop 0
	v_readlane_b32 s6, v12, 0
	v_readlane_b32 s7, v12, 16
	v_readlane_b32 s8, v12, 32
	v_readlane_b32 s9, v12, 48
	s_add_i32 s6, s6, s7
	s_add_i32 s8, s8, s9
	s_add_i32 s6, s6, s57
	s_add_i32 s8, s6, s8
	s_cmpk_eq_i32 s8, 0x100
	s_cbranch_scc1 .Lrdx_eq
	s_cmpk_lt_i32 s8, 0x100
	s_cselect_b32 s6, -1, 0
	s_cselect_b32 s57, s8, s57
	s_xor_b32 s59, s58, s6
	v_bitop3_b32 v7, v7, v189, s59 bitop3:0x60
	v_bitop3_b32 v6, v6, v186, s59 bitop3:0x60
	v_bitop3_b32 v5, v5, v95, s59 bitop3:0x60
	s_mov_b32 s58, s6
	v_bitop3_b32 v3, v3, v8, s6 bitop3:0xf8
	v_bitop3_b32 v2, v2, v9, s6 bitop3:0xf8
	v_bitop3_b32 v1, v1, v10, s6 bitop3:0xf8
	v_bitop3_b32 v8, v7, v188, s58 bitop3:0x60
	v_bitop3_b32 v9, v6, v185, s58 bitop3:0x60
	v_bcnt_u32_b32 v12, v8, 0
	v_bitop3_b32 v10, v5, v94, s58 bitop3:0x60
	v_bcnt_u32_b32 v12, v9, v12
	v_bcnt_u32_b32 v12, v10, v12
	s_nop 1
	v_add_u32_dpp v12, v12, v12 row_ror:8 row_mask:0xf bank_mask:0xf bound_ctrl:1
	s_nop 1
	v_add_u32_dpp v12, v12, v12 row_ror:4 row_mask:0xf bank_mask:0xf bound_ctrl:1
	s_nop 1
	v_add_u32_dpp v12, v12, v12 row_ror:2 row_mask:0xf bank_mask:0xf bound_ctrl:1
	s_nop 1
	v_add_u32_dpp v12, v12, v12 row_ror:1 row_mask:0xf bank_mask:0xf bound_ctrl:1
	s_nop 0
	v_readlane_b32 s6, v12, 0
	v_readlane_b32 s7, v12, 16
	v_readlane_b32 s8, v12, 32
	v_readlane_b32 s9, v12, 48
	s_add_i32 s6, s6, s7
	s_add_i32 s8, s8, s9
	s_add_i32 s6, s6, s57
	s_add_i32 s8, s6, s8
	s_cmpk_eq_i32 s8, 0x100
	s_cbranch_scc1 .Lrdx_eq
	s_cmpk_lt_i32 s8, 0x100
	s_cselect_b32 s6, -1, 0
	s_cselect_b32 s57, s8, s57
	s_xor_b32 s59, s58, s6
	v_bitop3_b32 v7, v7, v188, s59 bitop3:0x60
	v_bitop3_b32 v6, v6, v185, s59 bitop3:0x60
	v_bitop3_b32 v5, v5, v94, s59 bitop3:0x60
	v_bitop3_b32 v3, v3, v8, s6 bitop3:0xf8
	v_bitop3_b32 v2, v2, v9, s6 bitop3:0xf8
	v_bitop3_b32 v1, v1, v10, s6 bitop3:0xf8
	v_bitop3_b32 v8, v7, v187, s58 bitop3:0x60
	v_bitop3_b32 v9, v6, v183, s58 bitop3:0x60
	v_bcnt_u32_b32 v12, v8, 0
	v_bitop3_b32 v10, v5, v93, s58 bitop3:0x60
	v_bcnt_u32_b32 v12, v9, v12
	v_bcnt_u32_b32 v12, v10, v12
	s_nop 1
	v_add_u32_dpp v12, v12, v12 row_ror:8 row_mask:0xf bank_mask:0xf bound_ctrl:1
	s_nop 1
	v_add_u32_dpp v12, v12, v12 row_ror:4 row_mask:0xf bank_mask:0xf bound_ctrl:1
	s_nop 1
	v_add_u32_dpp v12, v12, v12 row_ror:2 row_mask:0xf bank_mask:0xf bound_ctrl:1
	s_nop 1
	v_add_u32_dpp v12, v12, v12 row_ror:1 row_mask:0xf bank_mask:0xf bound_ctrl:1
	s_nop 0
	v_readlane_b32 s6, v12, 0
	v_readlane_b32 s7, v12, 16
	v_readlane_b32 s8, v12, 32
	v_readlane_b32 s9, v12, 48
	s_add_i32 s6, s6, s7
	s_add_i32 s8, s8, s9
	s_add_i32 s6, s6, s57
	s_add_i32 s8, s6, s8
	s_cmpk_eq_i32 s8, 0x100
	s_cbranch_scc1 .Lrdx_eq
	s_cmpk_lt_i32 s8, 0x100
	s_cselect_b32 s6, -1, 0
	s_cselect_b32 s57, s8, s57
	s_xor_b32 s59, s58, s6
	v_bitop3_b32 v7, v7, v187, s59 bitop3:0x60
	v_bitop3_b32 v6, v6, v183, s59 bitop3:0x60
	v_bitop3_b32 v5, v5, v93, s59 bitop3:0x60
	v_bitop3_b32 v3, v3, v8, s6 bitop3:0xf8
	v_bitop3_b32 v2, v2, v9, s6 bitop3:0xf8
	v_bitop3_b32 v1, v1, v10, s6 bitop3:0xf8
	v_bitop3_b32 v8, v7, v184, s58 bitop3:0x60
	v_bitop3_b32 v9, v6, v161, s58 bitop3:0x60
	v_bcnt_u32_b32 v12, v8, 0
	v_bitop3_b32 v10, v5, v91, s58 bitop3:0x60
	v_bcnt_u32_b32 v12, v9, v12
	v_bcnt_u32_b32 v12, v10, v12
	s_nop 1
	v_add_u32_dpp v12, v12, v12 row_ror:8 row_mask:0xf bank_mask:0xf bound_ctrl:1
	s_nop 1
	v_add_u32_dpp v12, v12, v12 row_ror:4 row_mask:0xf bank_mask:0xf bound_ctrl:1
	s_nop 1
	v_add_u32_dpp v12, v12, v12 row_ror:2 row_mask:0xf bank_mask:0xf bound_ctrl:1
	s_nop 1
	v_add_u32_dpp v12, v12, v12 row_ror:1 row_mask:0xf bank_mask:0xf bound_ctrl:1
	s_nop 0
	v_readlane_b32 s6, v12, 0
	v_readlane_b32 s7, v12, 16
	v_readlane_b32 s8, v12, 32
	v_readlane_b32 s9, v12, 48
	s_add_i32 s6, s6, s7
	s_add_i32 s8, s8, s9
	s_add_i32 s6, s6, s57
	s_add_i32 s8, s6, s8
	s_cmpk_eq_i32 s8, 0x100
	s_cbranch_scc1 .Lrdx_eq
	s_cmpk_lt_i32 s8, 0x100
	s_cselect_b32 s6, -1, 0
	s_cselect_b32 s57, s8, s57
	s_xor_b32 s59, s58, s6
	v_bitop3_b32 v7, v7, v184, s59 bitop3:0x60
	v_bitop3_b32 v6, v6, v161, s59 bitop3:0x60
	v_bitop3_b32 v5, v5, v91, s59 bitop3:0x60
	v_bitop3_b32 v3, v3, v8, s6 bitop3:0xf8
	v_bitop3_b32 v2, v2, v9, s6 bitop3:0xf8
	v_bitop3_b32 v1, v1, v10, s6 bitop3:0xf8
	v_bitop3_b32 v8, v7, v181, s58 bitop3:0x60
	v_bitop3_b32 v9, v6, v159, s58 bitop3:0x60
	v_bcnt_u32_b32 v12, v8, 0
	v_bitop3_b32 v10, v5, v89, s58 bitop3:0x60
	v_bcnt_u32_b32 v12, v9, v12
	v_bcnt_u32_b32 v12, v10, v12
	s_nop 1
	v_add_u32_dpp v12, v12, v12 row_ror:8 row_mask:0xf bank_mask:0xf bound_ctrl:1
	s_nop 1
	v_add_u32_dpp v12, v12, v12 row_ror:4 row_mask:0xf bank_mask:0xf bound_ctrl:1
	s_nop 1
	v_add_u32_dpp v12, v12, v12 row_ror:2 row_mask:0xf bank_mask:0xf bound_ctrl:1
	s_nop 1
	v_add_u32_dpp v12, v12, v12 row_ror:1 row_mask:0xf bank_mask:0xf bound_ctrl:1
	s_nop 0
	v_readlane_b32 s6, v12, 0
	v_readlane_b32 s7, v12, 16
	v_readlane_b32 s8, v12, 32
	v_readlane_b32 s9, v12, 48
	s_add_i32 s6, s6, s7
	s_add_i32 s8, s8, s9
	s_add_i32 s6, s6, s57
	s_add_i32 s8, s6, s8
	s_cmpk_eq_i32 s8, 0x100
	s_cbranch_scc1 .Lrdx_eq
	s_cmpk_lt_i32 s8, 0x100
	s_cselect_b32 s6, -1, 0
	s_cselect_b32 s57, s8, s57
	s_xor_b32 s59, s58, s6
	v_bitop3_b32 v7, v7, v181, s59 bitop3:0x60
	v_bitop3_b32 v6, v6, v159, s59 bitop3:0x60
	v_bitop3_b32 v5, v5, v89, s59 bitop3:0x60
	v_bitop3_b32 v3, v3, v8, s6 bitop3:0xf8
	v_bitop3_b32 v2, v2, v9, s6 bitop3:0xf8
	v_bitop3_b32 v1, v1, v10, s6 bitop3:0xf8
	v_bitop3_b32 v8, v7, v160, s58 bitop3:0x60
	v_bitop3_b32 v9, v6, v157, s58 bitop3:0x60
	v_bcnt_u32_b32 v12, v8, 0
	v_bitop3_b32 v10, v5, v87, s58 bitop3:0x60
	v_bcnt_u32_b32 v12, v9, v12
	v_bcnt_u32_b32 v12, v10, v12
	s_nop 1
	v_add_u32_dpp v12, v12, v12 row_ror:8 row_mask:0xf bank_mask:0xf bound_ctrl:1
	s_nop 1
	v_add_u32_dpp v12, v12, v12 row_ror:4 row_mask:0xf bank_mask:0xf bound_ctrl:1
	s_nop 1
	v_add_u32_dpp v12, v12, v12 row_ror:2 row_mask:0xf bank_mask:0xf bound_ctrl:1
	s_nop 1
	v_add_u32_dpp v12, v12, v12 row_ror:1 row_mask:0xf bank_mask:0xf bound_ctrl:1
	s_nop 0
	v_readlane_b32 s6, v12, 0
	v_readlane_b32 s7, v12, 16
	v_readlane_b32 s8, v12, 32
	v_readlane_b32 s9, v12, 48
	s_add_i32 s6, s6, s7
	s_add_i32 s8, s8, s9
	s_add_i32 s6, s6, s57
	s_add_i32 s8, s6, s8
	s_cmpk_eq_i32 s8, 0x100
	s_cbranch_scc1 .Lrdx_eq
	s_cmpk_lt_i32 s8, 0x100
	s_cselect_b32 s6, -1, 0
	s_cselect_b32 s57, s8, s57
	s_xor_b32 s59, s58, s6
	v_bitop3_b32 v7, v7, v160, s59 bitop3:0x60
	v_bitop3_b32 v6, v6, v157, s59 bitop3:0x60
	v_bitop3_b32 v5, v5, v87, s59 bitop3:0x60
	v_bitop3_b32 v3, v3, v8, s6 bitop3:0xf8
	v_bitop3_b32 v2, v2, v9, s6 bitop3:0xf8
	v_bitop3_b32 v1, v1, v10, s6 bitop3:0xf8
	v_bitop3_b32 v8, v7, v158, s58 bitop3:0x60
	v_bitop3_b32 v9, v6, v155, s58 bitop3:0x60
	v_bcnt_u32_b32 v12, v8, 0
	v_bitop3_b32 v10, v5, v85, s58 bitop3:0x60
	v_bcnt_u32_b32 v12, v9, v12
	v_bcnt_u32_b32 v12, v10, v12
	s_nop 1
	v_add_u32_dpp v12, v12, v12 row_ror:8 row_mask:0xf bank_mask:0xf bound_ctrl:1
	s_nop 1
	v_add_u32_dpp v12, v12, v12 row_ror:4 row_mask:0xf bank_mask:0xf bound_ctrl:1
	s_nop 1
	v_add_u32_dpp v12, v12, v12 row_ror:2 row_mask:0xf bank_mask:0xf bound_ctrl:1
	s_nop 1
	v_add_u32_dpp v12, v12, v12 row_ror:1 row_mask:0xf bank_mask:0xf bound_ctrl:1
	s_nop 0
	v_readlane_b32 s6, v12, 0
	v_readlane_b32 s7, v12, 16
	v_readlane_b32 s8, v12, 32
	v_readlane_b32 s9, v12, 48
	s_add_i32 s6, s6, s7
	s_add_i32 s8, s8, s9
	s_add_i32 s6, s6, s57
	s_add_i32 s8, s6, s8
	s_cmpk_eq_i32 s8, 0x100
	s_cbranch_scc1 .Lrdx_eq
	s_cmpk_lt_i32 s8, 0x100
	s_cselect_b32 s6, -1, 0
	s_cselect_b32 s57, s8, s57
	s_xor_b32 s59, s58, s6
	v_bitop3_b32 v7, v7, v158, s59 bitop3:0x60
	v_bitop3_b32 v6, v6, v155, s59 bitop3:0x60
	v_bitop3_b32 v5, v5, v85, s59 bitop3:0x60
	v_bitop3_b32 v3, v3, v8, s6 bitop3:0xf8
	v_bitop3_b32 v2, v2, v9, s6 bitop3:0xf8
	v_bitop3_b32 v1, v1, v10, s6 bitop3:0xf8
	v_bitop3_b32 v8, v7, v156, s58 bitop3:0x60
	v_bitop3_b32 v9, v6, v153, s58 bitop3:0x60
	v_bcnt_u32_b32 v12, v8, 0
	v_bitop3_b32 v10, v5, v83, s58 bitop3:0x60
	v_bcnt_u32_b32 v12, v9, v12
	v_bcnt_u32_b32 v12, v10, v12
	s_nop 1
	v_add_u32_dpp v12, v12, v12 row_ror:8 row_mask:0xf bank_mask:0xf bound_ctrl:1
	s_nop 1
	v_add_u32_dpp v12, v12, v12 row_ror:4 row_mask:0xf bank_mask:0xf bound_ctrl:1
	s_nop 1
	v_add_u32_dpp v12, v12, v12 row_ror:2 row_mask:0xf bank_mask:0xf bound_ctrl:1
	s_nop 1
	v_add_u32_dpp v12, v12, v12 row_ror:1 row_mask:0xf bank_mask:0xf bound_ctrl:1
	s_nop 0
	v_readlane_b32 s6, v12, 0
	v_readlane_b32 s7, v12, 16
	v_readlane_b32 s8, v12, 32
	v_readlane_b32 s9, v12, 48
	s_add_i32 s6, s6, s7
	s_add_i32 s8, s8, s9
	s_add_i32 s6, s6, s57
	s_add_i32 s8, s6, s8
	s_cmpk_eq_i32 s8, 0x100
	s_cbranch_scc1 .Lrdx_eq
	s_cmpk_lt_i32 s8, 0x100
	s_cselect_b32 s6, -1, 0
	s_cselect_b32 s57, s8, s57
	s_xor_b32 s59, s58, s6
	v_bitop3_b32 v7, v7, v156, s59 bitop3:0x60
	v_bitop3_b32 v6, v6, v153, s59 bitop3:0x60
	v_bitop3_b32 v5, v5, v83, s59 bitop3:0x60
	v_bitop3_b32 v3, v3, v8, s6 bitop3:0xf8
	v_bitop3_b32 v2, v2, v9, s6 bitop3:0xf8
	v_bitop3_b32 v1, v1, v10, s6 bitop3:0xf8
	v_bitop3_b32 v8, v7, v154, s58 bitop3:0x60
	v_bitop3_b32 v9, v6, v151, s58 bitop3:0x60
	v_bcnt_u32_b32 v12, v8, 0
	v_bitop3_b32 v10, v5, v81, s58 bitop3:0x60
	v_bcnt_u32_b32 v12, v9, v12
	v_bcnt_u32_b32 v12, v10, v12
	s_nop 1
	v_add_u32_dpp v12, v12, v12 row_ror:8 row_mask:0xf bank_mask:0xf bound_ctrl:1
	s_nop 1
	v_add_u32_dpp v12, v12, v12 row_ror:4 row_mask:0xf bank_mask:0xf bound_ctrl:1
	s_nop 1
	v_add_u32_dpp v12, v12, v12 row_ror:2 row_mask:0xf bank_mask:0xf bound_ctrl:1
	s_nop 1
	v_add_u32_dpp v12, v12, v12 row_ror:1 row_mask:0xf bank_mask:0xf bound_ctrl:1
	s_nop 0
	v_readlane_b32 s6, v12, 0
	v_readlane_b32 s7, v12, 16
	v_readlane_b32 s8, v12, 32
	v_readlane_b32 s9, v12, 48
	s_add_i32 s6, s6, s7
	s_add_i32 s8, s8, s9
	s_add_i32 s6, s6, s57
	s_add_i32 s8, s6, s8
	s_cmpk_eq_i32 s8, 0x100
	s_cbranch_scc1 .Lrdx_eq
	s_cmpk_lt_i32 s8, 0x100
	s_cselect_b32 s6, -1, 0
	s_cselect_b32 s57, s8, s57
	s_xor_b32 s59, s58, s6
	v_bitop3_b32 v7, v7, v154, s59 bitop3:0x60
	v_bitop3_b32 v6, v6, v151, s59 bitop3:0x60
	v_bitop3_b32 v5, v5, v81, s59 bitop3:0x60
	v_bitop3_b32 v3, v3, v8, s6 bitop3:0xf8
	v_bitop3_b32 v2, v2, v9, s6 bitop3:0xf8
	v_bitop3_b32 v1, v1, v10, s6 bitop3:0xf8
	v_bitop3_b32 v8, v7, v152, s58 bitop3:0x60
	v_bitop3_b32 v9, v6, v149, s58 bitop3:0x60
	v_bcnt_u32_b32 v12, v8, 0
	v_bitop3_b32 v10, v5, v79, s58 bitop3:0x60
	v_bcnt_u32_b32 v12, v9, v12
	v_bcnt_u32_b32 v12, v10, v12
	s_nop 1
	v_add_u32_dpp v12, v12, v12 row_ror:8 row_mask:0xf bank_mask:0xf bound_ctrl:1
	s_nop 1
	v_add_u32_dpp v12, v12, v12 row_ror:4 row_mask:0xf bank_mask:0xf bound_ctrl:1
	s_nop 1
	v_add_u32_dpp v12, v12, v12 row_ror:2 row_mask:0xf bank_mask:0xf bound_ctrl:1
	s_nop 1
	v_add_u32_dpp v12, v12, v12 row_ror:1 row_mask:0xf bank_mask:0xf bound_ctrl:1
	s_nop 0
	v_readlane_b32 s6, v12, 0
	v_readlane_b32 s7, v12, 16
	v_readlane_b32 s8, v12, 32
	v_readlane_b32 s9, v12, 48
	s_add_i32 s6, s6, s7
	s_add_i32 s8, s8, s9
	s_add_i32 s6, s6, s57
	s_add_i32 s8, s6, s8
	s_cmpk_eq_i32 s8, 0x100
	s_cbranch_scc1 .Lrdx_eq
	s_cmpk_lt_i32 s8, 0x100
	s_cselect_b32 s6, -1, 0
	s_cselect_b32 s57, s8, s57
	s_xor_b32 s59, s58, s6
	v_bitop3_b32 v7, v7, v152, s59 bitop3:0x60
	v_bitop3_b32 v6, v6, v149, s59 bitop3:0x60
	v_bitop3_b32 v5, v5, v79, s59 bitop3:0x60
	v_bitop3_b32 v3, v3, v8, s6 bitop3:0xf8
	v_bitop3_b32 v2, v2, v9, s6 bitop3:0xf8
	v_bitop3_b32 v1, v1, v10, s6 bitop3:0xf8
	v_bitop3_b32 v8, v7, v150, s58 bitop3:0x60
	v_bitop3_b32 v9, v6, v147, s58 bitop3:0x60
	v_bcnt_u32_b32 v12, v8, 0
	v_bitop3_b32 v10, v5, v77, s58 bitop3:0x60
	v_bcnt_u32_b32 v12, v9, v12
	v_bcnt_u32_b32 v12, v10, v12
	s_nop 1
	v_add_u32_dpp v12, v12, v12 row_ror:8 row_mask:0xf bank_mask:0xf bound_ctrl:1
	s_nop 1
	v_add_u32_dpp v12, v12, v12 row_ror:4 row_mask:0xf bank_mask:0xf bound_ctrl:1
	s_nop 1
	v_add_u32_dpp v12, v12, v12 row_ror:2 row_mask:0xf bank_mask:0xf bound_ctrl:1
	s_nop 1
	v_add_u32_dpp v12, v12, v12 row_ror:1 row_mask:0xf bank_mask:0xf bound_ctrl:1
	s_nop 0
	v_readlane_b32 s6, v12, 0
	v_readlane_b32 s7, v12, 16
	v_readlane_b32 s8, v12, 32
	v_readlane_b32 s9, v12, 48
	s_add_i32 s6, s6, s7
	s_add_i32 s8, s8, s9
	s_add_i32 s6, s6, s57
	s_add_i32 s8, s6, s8
	s_cmpk_eq_i32 s8, 0x100
	s_cbranch_scc1 .Lrdx_eq
	s_cmpk_lt_i32 s8, 0x100
	s_cselect_b32 s6, -1, 0
	s_cselect_b32 s57, s8, s57
	s_xor_b32 s59, s58, s6
	v_bitop3_b32 v7, v7, v150, s59 bitop3:0x60
	v_bitop3_b32 v6, v6, v147, s59 bitop3:0x60
	v_bitop3_b32 v5, v5, v77, s59 bitop3:0x60
	v_bitop3_b32 v3, v3, v8, s6 bitop3:0xf8
	v_bitop3_b32 v2, v2, v9, s6 bitop3:0xf8
	v_bitop3_b32 v1, v1, v10, s6 bitop3:0xf8
	v_bitop3_b32 v8, v7, v148, s58 bitop3:0x60
	v_bitop3_b32 v9, v6, v145, s58 bitop3:0x60
	v_bcnt_u32_b32 v12, v8, 0
	v_bitop3_b32 v10, v5, v75, s58 bitop3:0x60
	v_bcnt_u32_b32 v12, v9, v12
	v_bcnt_u32_b32 v12, v10, v12
	s_nop 1
	v_add_u32_dpp v12, v12, v12 row_ror:8 row_mask:0xf bank_mask:0xf bound_ctrl:1
	s_nop 1
	v_add_u32_dpp v12, v12, v12 row_ror:4 row_mask:0xf bank_mask:0xf bound_ctrl:1
	s_nop 1
	v_add_u32_dpp v12, v12, v12 row_ror:2 row_mask:0xf bank_mask:0xf bound_ctrl:1
	s_nop 1
	v_add_u32_dpp v12, v12, v12 row_ror:1 row_mask:0xf bank_mask:0xf bound_ctrl:1
	s_nop 0
	v_readlane_b32 s6, v12, 0
	v_readlane_b32 s7, v12, 16
	v_readlane_b32 s8, v12, 32
	v_readlane_b32 s9, v12, 48
	s_add_i32 s6, s6, s7
	s_add_i32 s8, s8, s9
	s_add_i32 s6, s6, s57
	s_add_i32 s8, s6, s8
	s_cmpk_eq_i32 s8, 0x100
	s_cbranch_scc1 .Lrdx_eq
	s_cmpk_lt_i32 s8, 0x100
	s_cselect_b32 s6, -1, 0
	s_cselect_b32 s57, s8, s57
	s_xor_b32 s59, s58, s6
	v_bitop3_b32 v7, v7, v148, s59 bitop3:0x60
	v_bitop3_b32 v6, v6, v145, s59 bitop3:0x60
	v_bitop3_b32 v5, v5, v75, s59 bitop3:0x60
	v_bitop3_b32 v3, v3, v8, s6 bitop3:0xf8
	v_bitop3_b32 v2, v2, v9, s6 bitop3:0xf8
	v_bitop3_b32 v1, v1, v10, s6 bitop3:0xf8
	v_bitop3_b32 v8, v7, v146, s58 bitop3:0x60
	v_bitop3_b32 v9, v6, v143, s58 bitop3:0x60
	v_bcnt_u32_b32 v12, v8, 0
	v_bitop3_b32 v10, v5, v73, s58 bitop3:0x60
	v_bcnt_u32_b32 v12, v9, v12
	v_bcnt_u32_b32 v12, v10, v12
	s_nop 1
	v_add_u32_dpp v12, v12, v12 row_ror:8 row_mask:0xf bank_mask:0xf bound_ctrl:1
	s_nop 1
	v_add_u32_dpp v12, v12, v12 row_ror:4 row_mask:0xf bank_mask:0xf bound_ctrl:1
	s_nop 1
	v_add_u32_dpp v12, v12, v12 row_ror:2 row_mask:0xf bank_mask:0xf bound_ctrl:1
	s_nop 1
	v_add_u32_dpp v12, v12, v12 row_ror:1 row_mask:0xf bank_mask:0xf bound_ctrl:1
	s_nop 0
	v_readlane_b32 s6, v12, 0
	v_readlane_b32 s7, v12, 16
	v_readlane_b32 s8, v12, 32
	v_readlane_b32 s9, v12, 48
	s_add_i32 s6, s6, s7
	s_add_i32 s8, s8, s9
	s_add_i32 s6, s6, s57
	s_add_i32 s8, s6, s8
	s_cmpk_eq_i32 s8, 0x100
	s_cbranch_scc1 .Lrdx_eq
	s_cmpk_lt_i32 s8, 0x100
	s_cselect_b32 s6, -1, 0
	s_cselect_b32 s57, s8, s57
	s_xor_b32 s59, s58, s6
	v_bitop3_b32 v7, v7, v146, s59 bitop3:0x60
	v_bitop3_b32 v6, v6, v143, s59 bitop3:0x60
	v_bitop3_b32 v5, v5, v73, s59 bitop3:0x60
	v_bitop3_b32 v3, v3, v8, s6 bitop3:0xf8
	v_bitop3_b32 v2, v2, v9, s6 bitop3:0xf8
	v_bitop3_b32 v1, v1, v10, s6 bitop3:0xf8
	v_bitop3_b32 v8, v7, v144, s58 bitop3:0x60
	v_bitop3_b32 v9, v6, v141, s58 bitop3:0x60
	v_bcnt_u32_b32 v12, v8, 0
	v_bitop3_b32 v10, v5, v71, s58 bitop3:0x60
	v_bcnt_u32_b32 v12, v9, v12
	v_bcnt_u32_b32 v12, v10, v12
	s_nop 1
	v_add_u32_dpp v12, v12, v12 row_ror:8 row_mask:0xf bank_mask:0xf bound_ctrl:1
	s_nop 1
	v_add_u32_dpp v12, v12, v12 row_ror:4 row_mask:0xf bank_mask:0xf bound_ctrl:1
	s_nop 1
	v_add_u32_dpp v12, v12, v12 row_ror:2 row_mask:0xf bank_mask:0xf bound_ctrl:1
	s_nop 1
	v_add_u32_dpp v12, v12, v12 row_ror:1 row_mask:0xf bank_mask:0xf bound_ctrl:1
	s_nop 0
	v_readlane_b32 s6, v12, 0
	v_readlane_b32 s7, v12, 16
	v_readlane_b32 s8, v12, 32
	v_readlane_b32 s9, v12, 48
	s_add_i32 s6, s6, s7
	s_add_i32 s8, s8, s9
	s_add_i32 s6, s6, s57
	s_add_i32 s8, s6, s8
	s_cmpk_eq_i32 s8, 0x100
	s_cbranch_scc1 .Lrdx_eq
	s_cmpk_lt_i32 s8, 0x100
	s_cselect_b32 s6, -1, 0
	s_cselect_b32 s57, s8, s57
	s_xor_b32 s59, s58, s6
	v_bitop3_b32 v7, v7, v144, s59 bitop3:0x60
	v_bitop3_b32 v6, v6, v141, s59 bitop3:0x60
	v_bitop3_b32 v5, v5, v71, s59 bitop3:0x60
	v_bitop3_b32 v3, v3, v8, s6 bitop3:0xf8
	v_bitop3_b32 v2, v2, v9, s6 bitop3:0xf8
	v_bitop3_b32 v1, v1, v10, s6 bitop3:0xf8
	v_bitop3_b32 v8, v7, v142, s58 bitop3:0x60
	v_bitop3_b32 v9, v6, v139, s58 bitop3:0x60
	v_bcnt_u32_b32 v12, v8, 0
	v_bitop3_b32 v10, v5, v69, s58 bitop3:0x60
	v_bcnt_u32_b32 v12, v9, v12
	v_bcnt_u32_b32 v12, v10, v12
	s_nop 1
	v_add_u32_dpp v12, v12, v12 row_ror:8 row_mask:0xf bank_mask:0xf bound_ctrl:1
	s_nop 1
	v_add_u32_dpp v12, v12, v12 row_ror:4 row_mask:0xf bank_mask:0xf bound_ctrl:1
	s_nop 1
	v_add_u32_dpp v12, v12, v12 row_ror:2 row_mask:0xf bank_mask:0xf bound_ctrl:1
	s_nop 1
	v_add_u32_dpp v12, v12, v12 row_ror:1 row_mask:0xf bank_mask:0xf bound_ctrl:1
	s_nop 0
	v_readlane_b32 s6, v12, 0
	v_readlane_b32 s7, v12, 16
	v_readlane_b32 s8, v12, 32
	v_readlane_b32 s9, v12, 48
	s_add_i32 s6, s6, s7
	s_add_i32 s8, s8, s9
	s_add_i32 s6, s6, s57
	s_add_i32 s8, s6, s8
	s_cmpk_eq_i32 s8, 0x100
	s_cbranch_scc1 .Lrdx_eq
	s_cmpk_lt_i32 s8, 0x100
	s_cselect_b32 s6, -1, 0
	s_cselect_b32 s57, s8, s57
	s_xor_b32 s59, s58, s6
	v_bitop3_b32 v7, v7, v142, s59 bitop3:0x60
	v_bitop3_b32 v6, v6, v139, s59 bitop3:0x60
	v_bitop3_b32 v5, v5, v69, s59 bitop3:0x60
	v_bitop3_b32 v3, v3, v8, s6 bitop3:0xf8
	v_bitop3_b32 v2, v2, v9, s6 bitop3:0xf8
	v_bitop3_b32 v1, v1, v10, s6 bitop3:0xf8
	v_bitop3_b32 v8, v7, v140, s58 bitop3:0x60
	v_bitop3_b32 v9, v6, v137, s58 bitop3:0x60
	v_bcnt_u32_b32 v12, v8, 0
	v_bitop3_b32 v10, v5, v67, s58 bitop3:0x60
	v_bcnt_u32_b32 v12, v9, v12
	v_bcnt_u32_b32 v12, v10, v12
	s_nop 1
	v_add_u32_dpp v12, v12, v12 row_ror:8 row_mask:0xf bank_mask:0xf bound_ctrl:1
	s_nop 1
	v_add_u32_dpp v12, v12, v12 row_ror:4 row_mask:0xf bank_mask:0xf bound_ctrl:1
	s_nop 1
	v_add_u32_dpp v12, v12, v12 row_ror:2 row_mask:0xf bank_mask:0xf bound_ctrl:1
	s_nop 1
	v_add_u32_dpp v12, v12, v12 row_ror:1 row_mask:0xf bank_mask:0xf bound_ctrl:1
	s_nop 0
	v_readlane_b32 s6, v12, 0
	v_readlane_b32 s7, v12, 16
	v_readlane_b32 s8, v12, 32
	v_readlane_b32 s9, v12, 48
	s_add_i32 s6, s6, s7
	s_add_i32 s8, s8, s9
	s_add_i32 s6, s6, s57
	s_add_i32 s8, s6, s8
	s_cmpk_eq_i32 s8, 0x100
	s_cbranch_scc1 .Lrdx_eq
	s_cmpk_lt_i32 s8, 0x100
	s_cselect_b32 s6, -1, 0
	s_cselect_b32 s57, s8, s57
	s_xor_b32 s59, s58, s6
	v_bitop3_b32 v7, v7, v140, s59 bitop3:0x60
	v_bitop3_b32 v6, v6, v137, s59 bitop3:0x60
	v_bitop3_b32 v5, v5, v67, s59 bitop3:0x60
	v_bitop3_b32 v3, v3, v8, s6 bitop3:0xf8
	v_bitop3_b32 v2, v2, v9, s6 bitop3:0xf8
	v_bitop3_b32 v1, v1, v10, s6 bitop3:0xf8
	v_bitop3_b32 v8, v7, v138, s58 bitop3:0x60
	v_bitop3_b32 v9, v6, v135, s58 bitop3:0x60
	v_bcnt_u32_b32 v12, v8, 0
	v_bitop3_b32 v10, v5, v65, s58 bitop3:0x60
	v_bcnt_u32_b32 v12, v9, v12
	v_bcnt_u32_b32 v12, v10, v12
	s_nop 1
	v_add_u32_dpp v12, v12, v12 row_ror:8 row_mask:0xf bank_mask:0xf bound_ctrl:1
	s_nop 1
	v_add_u32_dpp v12, v12, v12 row_ror:4 row_mask:0xf bank_mask:0xf bound_ctrl:1
	s_nop 1
	v_add_u32_dpp v12, v12, v12 row_ror:2 row_mask:0xf bank_mask:0xf bound_ctrl:1
	s_nop 1
	v_add_u32_dpp v12, v12, v12 row_ror:1 row_mask:0xf bank_mask:0xf bound_ctrl:1
	s_nop 0
	v_readlane_b32 s6, v12, 0
	v_readlane_b32 s7, v12, 16
	v_readlane_b32 s8, v12, 32
	v_readlane_b32 s9, v12, 48
	s_add_i32 s6, s6, s7
	s_add_i32 s8, s8, s9
	s_add_i32 s6, s6, s57
	s_add_i32 s8, s6, s8
	s_cmpk_eq_i32 s8, 0x100
	s_cbranch_scc1 .Lrdx_eq
	s_cmpk_lt_i32 s8, 0x100
	s_cselect_b32 s6, -1, 0
	s_cselect_b32 s57, s8, s57
	s_xor_b32 s59, s58, s6
	v_bitop3_b32 v7, v7, v138, s59 bitop3:0x60
	v_bitop3_b32 v6, v6, v135, s59 bitop3:0x60
	v_bitop3_b32 v5, v5, v65, s59 bitop3:0x60
	v_bitop3_b32 v3, v3, v8, s6 bitop3:0xf8
	v_bitop3_b32 v2, v2, v9, s6 bitop3:0xf8
	v_bitop3_b32 v1, v1, v10, s6 bitop3:0xf8
	v_bitop3_b32 v8, v7, v136, s58 bitop3:0x60
	v_bitop3_b32 v9, v6, v133, s58 bitop3:0x60
	v_bcnt_u32_b32 v12, v8, 0
	v_bitop3_b32 v10, v5, v63, s58 bitop3:0x60
	v_bcnt_u32_b32 v12, v9, v12
	v_bcnt_u32_b32 v12, v10, v12
	s_nop 1
	v_add_u32_dpp v12, v12, v12 row_ror:8 row_mask:0xf bank_mask:0xf bound_ctrl:1
	s_nop 1
	v_add_u32_dpp v12, v12, v12 row_ror:4 row_mask:0xf bank_mask:0xf bound_ctrl:1
	s_nop 1
	v_add_u32_dpp v12, v12, v12 row_ror:2 row_mask:0xf bank_mask:0xf bound_ctrl:1
	s_nop 1
	v_add_u32_dpp v12, v12, v12 row_ror:1 row_mask:0xf bank_mask:0xf bound_ctrl:1
	s_nop 0
	v_readlane_b32 s6, v12, 0
	v_readlane_b32 s7, v12, 16
	v_readlane_b32 s8, v12, 32
	v_readlane_b32 s9, v12, 48
	s_add_i32 s6, s6, s7
	s_add_i32 s8, s8, s9
	s_add_i32 s6, s6, s57
	s_add_i32 s8, s6, s8
	s_cmpk_eq_i32 s8, 0x100
	s_cbranch_scc1 .Lrdx_eq
	s_cmpk_lt_i32 s8, 0x100
	s_cselect_b32 s6, -1, 0
	s_cselect_b32 s57, s8, s57
	s_xor_b32 s59, s58, s6
	v_bitop3_b32 v7, v7, v136, s59 bitop3:0x60
	v_bitop3_b32 v6, v6, v133, s59 bitop3:0x60
	v_bitop3_b32 v5, v5, v63, s59 bitop3:0x60
	v_bitop3_b32 v3, v3, v8, s6 bitop3:0xf8
	v_bitop3_b32 v2, v2, v9, s6 bitop3:0xf8
	v_bitop3_b32 v1, v1, v10, s6 bitop3:0xf8
	v_bitop3_b32 v8, v7, v134, s58 bitop3:0x60
	v_bitop3_b32 v9, v6, v131, s58 bitop3:0x60
	v_bcnt_u32_b32 v12, v8, 0
	v_bitop3_b32 v10, v5, v61, s58 bitop3:0x60
	v_bcnt_u32_b32 v12, v9, v12
	v_bcnt_u32_b32 v12, v10, v12
	s_nop 1
	v_add_u32_dpp v12, v12, v12 row_ror:8 row_mask:0xf bank_mask:0xf bound_ctrl:1
	s_nop 1
	v_add_u32_dpp v12, v12, v12 row_ror:4 row_mask:0xf bank_mask:0xf bound_ctrl:1
	s_nop 1
	v_add_u32_dpp v12, v12, v12 row_ror:2 row_mask:0xf bank_mask:0xf bound_ctrl:1
	s_nop 1
	v_add_u32_dpp v12, v12, v12 row_ror:1 row_mask:0xf bank_mask:0xf bound_ctrl:1
	s_nop 0
	v_readlane_b32 s6, v12, 0
	v_readlane_b32 s7, v12, 16
	v_readlane_b32 s8, v12, 32
	v_readlane_b32 s9, v12, 48
	s_add_i32 s6, s6, s7
	s_add_i32 s8, s8, s9
	s_add_i32 s6, s6, s57
	s_add_i32 s8, s6, s8
	s_cmpk_eq_i32 s8, 0x100
	s_cbranch_scc1 .Lrdx_eq
	s_cmpk_lt_i32 s8, 0x100
	s_cselect_b32 s6, -1, 0
	s_cselect_b32 s57, s8, s57
	s_xor_b32 s59, s58, s6
	v_bitop3_b32 v7, v7, v134, s59 bitop3:0x60
	v_bitop3_b32 v6, v6, v131, s59 bitop3:0x60
	v_bitop3_b32 v5, v5, v61, s59 bitop3:0x60
	v_bitop3_b32 v3, v3, v8, s6 bitop3:0xf8
	v_bitop3_b32 v2, v2, v9, s6 bitop3:0xf8
	v_bitop3_b32 v1, v1, v10, s6 bitop3:0xf8
	v_bitop3_b32 v8, v7, v132, s58 bitop3:0x60
	v_bitop3_b32 v9, v6, v129, s58 bitop3:0x60
	v_bcnt_u32_b32 v12, v8, 0
	v_bitop3_b32 v10, v5, v59, s58 bitop3:0x60
	v_bcnt_u32_b32 v12, v9, v12
	v_bcnt_u32_b32 v12, v10, v12
	s_nop 1
	v_add_u32_dpp v12, v12, v12 row_ror:8 row_mask:0xf bank_mask:0xf bound_ctrl:1
	s_nop 1
	v_add_u32_dpp v12, v12, v12 row_ror:4 row_mask:0xf bank_mask:0xf bound_ctrl:1
	s_nop 1
	v_add_u32_dpp v12, v12, v12 row_ror:2 row_mask:0xf bank_mask:0xf bound_ctrl:1
	s_nop 1
	v_add_u32_dpp v12, v12, v12 row_ror:1 row_mask:0xf bank_mask:0xf bound_ctrl:1
	s_nop 0
	v_readlane_b32 s6, v12, 0
	v_readlane_b32 s7, v12, 16
	v_readlane_b32 s8, v12, 32
	v_readlane_b32 s9, v12, 48
	s_add_i32 s6, s6, s7
	s_add_i32 s8, s8, s9
	s_add_i32 s6, s6, s57
	s_add_i32 s8, s6, s8
	s_cmpk_eq_i32 s8, 0x100
	s_cbranch_scc1 .Lrdx_eq
	s_cmpk_lt_i32 s8, 0x100
	s_cselect_b32 s6, -1, 0
	s_cselect_b32 s57, s8, s57
	s_xor_b32 s59, s58, s6
	v_bitop3_b32 v7, v7, v132, s59 bitop3:0x60
	v_bitop3_b32 v6, v6, v129, s59 bitop3:0x60
	v_bitop3_b32 v5, v5, v59, s59 bitop3:0x60
	v_bitop3_b32 v3, v3, v8, s6 bitop3:0xf8
	v_bitop3_b32 v2, v2, v9, s6 bitop3:0xf8
	v_bitop3_b32 v1, v1, v10, s6 bitop3:0xf8
	v_bitop3_b32 v8, v7, v130, s58 bitop3:0x60
	v_bitop3_b32 v9, v6, v127, s58 bitop3:0x60
	v_bcnt_u32_b32 v12, v8, 0
	v_bitop3_b32 v10, v5, v57, s58 bitop3:0x60
	v_bcnt_u32_b32 v12, v9, v12
	v_bcnt_u32_b32 v12, v10, v12
	s_nop 1
	v_add_u32_dpp v12, v12, v12 row_ror:8 row_mask:0xf bank_mask:0xf bound_ctrl:1
	s_nop 1
	v_add_u32_dpp v12, v12, v12 row_ror:4 row_mask:0xf bank_mask:0xf bound_ctrl:1
	s_nop 1
	v_add_u32_dpp v12, v12, v12 row_ror:2 row_mask:0xf bank_mask:0xf bound_ctrl:1
	s_nop 1
	v_add_u32_dpp v12, v12, v12 row_ror:1 row_mask:0xf bank_mask:0xf bound_ctrl:1
	s_nop 0
	v_readlane_b32 s6, v12, 0
	v_readlane_b32 s7, v12, 16
	v_readlane_b32 s8, v12, 32
	v_readlane_b32 s9, v12, 48
	s_add_i32 s6, s6, s7
	s_add_i32 s8, s8, s9
	s_add_i32 s6, s6, s57
	s_add_i32 s8, s6, s8
	s_cmpk_eq_i32 s8, 0x100
	s_cbranch_scc1 .Lrdx_eq
	s_cmpk_lt_i32 s8, 0x100
	s_cselect_b32 s6, -1, 0
	s_cselect_b32 s57, s8, s57
	s_xor_b32 s59, s58, s6
	v_bitop3_b32 v7, v7, v130, s59 bitop3:0x60
	v_bitop3_b32 v6, v6, v127, s59 bitop3:0x60
	v_bitop3_b32 v5, v5, v57, s59 bitop3:0x60
	v_bitop3_b32 v3, v3, v8, s6 bitop3:0xf8
	v_bitop3_b32 v2, v2, v9, s6 bitop3:0xf8
	v_bitop3_b32 v1, v1, v10, s6 bitop3:0xf8
	v_bitop3_b32 v8, v7, v128, s58 bitop3:0x60
	v_bitop3_b32 v9, v6, v125, s58 bitop3:0x60
	v_bcnt_u32_b32 v12, v8, 0
	v_bitop3_b32 v10, v5, v55, s58 bitop3:0x60
	v_bcnt_u32_b32 v12, v9, v12
	v_bcnt_u32_b32 v12, v10, v12
	s_nop 1
	v_add_u32_dpp v12, v12, v12 row_ror:8 row_mask:0xf bank_mask:0xf bound_ctrl:1
	s_nop 1
	v_add_u32_dpp v12, v12, v12 row_ror:4 row_mask:0xf bank_mask:0xf bound_ctrl:1
	s_nop 1
	v_add_u32_dpp v12, v12, v12 row_ror:2 row_mask:0xf bank_mask:0xf bound_ctrl:1
	s_nop 1
	v_add_u32_dpp v12, v12, v12 row_ror:1 row_mask:0xf bank_mask:0xf bound_ctrl:1
	s_nop 0
	v_readlane_b32 s6, v12, 0
	v_readlane_b32 s7, v12, 16
	v_readlane_b32 s8, v12, 32
	v_readlane_b32 s9, v12, 48
	s_add_i32 s6, s6, s7
	s_add_i32 s8, s8, s9
	s_add_i32 s6, s6, s57
	s_add_i32 s8, s6, s8
	s_cmpk_eq_i32 s8, 0x100
	s_cbranch_scc1 .Lrdx_eq
	s_cmpk_lt_i32 s8, 0x100
	s_cselect_b32 s6, -1, 0
	s_cselect_b32 s57, s8, s57
	s_xor_b32 s59, s58, s6
	v_bitop3_b32 v7, v7, v128, s59 bitop3:0x60
	v_bitop3_b32 v6, v6, v125, s59 bitop3:0x60
	v_bitop3_b32 v5, v5, v55, s59 bitop3:0x60
	v_bitop3_b32 v3, v3, v8, s6 bitop3:0xf8
	v_bitop3_b32 v2, v2, v9, s6 bitop3:0xf8
	v_bitop3_b32 v1, v1, v10, s6 bitop3:0xf8
	v_bitop3_b32 v8, v7, v126, s58 bitop3:0x60
	v_bitop3_b32 v9, v6, v123, s58 bitop3:0x60
	v_bcnt_u32_b32 v12, v8, 0
	v_bitop3_b32 v10, v5, v53, s58 bitop3:0x60
	v_bcnt_u32_b32 v12, v9, v12
	v_bcnt_u32_b32 v12, v10, v12
	s_nop 1
	v_add_u32_dpp v12, v12, v12 row_ror:8 row_mask:0xf bank_mask:0xf bound_ctrl:1
	s_nop 1
	v_add_u32_dpp v12, v12, v12 row_ror:4 row_mask:0xf bank_mask:0xf bound_ctrl:1
	s_nop 1
	v_add_u32_dpp v12, v12, v12 row_ror:2 row_mask:0xf bank_mask:0xf bound_ctrl:1
	s_nop 1
	v_add_u32_dpp v12, v12, v12 row_ror:1 row_mask:0xf bank_mask:0xf bound_ctrl:1
	s_nop 0
	v_readlane_b32 s6, v12, 0
	v_readlane_b32 s7, v12, 16
	v_readlane_b32 s8, v12, 32
	v_readlane_b32 s9, v12, 48
	s_add_i32 s6, s6, s7
	s_add_i32 s8, s8, s9
	s_add_i32 s6, s6, s57
	s_add_i32 s8, s6, s8
	s_cmpk_eq_i32 s8, 0x100
	s_cbranch_scc1 .Lrdx_eq
	s_cmpk_lt_i32 s8, 0x100
	s_cselect_b32 s6, -1, 0
	s_cselect_b32 s57, s8, s57
	s_xor_b32 s59, s58, s6
	v_bitop3_b32 v7, v7, v126, s59 bitop3:0x60
	v_bitop3_b32 v6, v6, v123, s59 bitop3:0x60
	v_bitop3_b32 v5, v5, v53, s59 bitop3:0x60
	v_bitop3_b32 v3, v3, v8, s6 bitop3:0xf8
	v_bitop3_b32 v2, v2, v9, s6 bitop3:0xf8
	v_bitop3_b32 v1, v1, v10, s6 bitop3:0xf8
	v_bitop3_b32 v8, v7, v124, s58 bitop3:0x60
	v_bitop3_b32 v9, v6, v121, s58 bitop3:0x60
	v_bcnt_u32_b32 v12, v8, 0
	v_bitop3_b32 v10, v5, v51, s58 bitop3:0x60
	v_bcnt_u32_b32 v12, v9, v12
	v_bcnt_u32_b32 v12, v10, v12
	s_nop 1
	v_add_u32_dpp v12, v12, v12 row_ror:8 row_mask:0xf bank_mask:0xf bound_ctrl:1
	s_nop 1
	v_add_u32_dpp v12, v12, v12 row_ror:4 row_mask:0xf bank_mask:0xf bound_ctrl:1
	s_nop 1
	v_add_u32_dpp v12, v12, v12 row_ror:2 row_mask:0xf bank_mask:0xf bound_ctrl:1
	s_nop 1
	v_add_u32_dpp v12, v12, v12 row_ror:1 row_mask:0xf bank_mask:0xf bound_ctrl:1
	s_nop 0
	v_readlane_b32 s6, v12, 0
	v_readlane_b32 s7, v12, 16
	v_readlane_b32 s8, v12, 32
	v_readlane_b32 s9, v12, 48
	s_add_i32 s6, s6, s7
	s_add_i32 s8, s8, s9
	s_add_i32 s6, s6, s57
	s_add_i32 s8, s6, s8
	s_cmpk_eq_i32 s8, 0x100
	s_cbranch_scc1 .Lrdx_eq
	s_cmpk_lt_i32 s8, 0x100
	s_cselect_b32 s6, -1, 0
	s_cselect_b32 s57, s8, s57
	s_xor_b32 s59, s58, s6
	v_bitop3_b32 v7, v7, v124, s59 bitop3:0x60
	v_bitop3_b32 v6, v6, v121, s59 bitop3:0x60
	v_bitop3_b32 v5, v5, v51, s59 bitop3:0x60
	v_bitop3_b32 v3, v3, v8, s6 bitop3:0xf8
	v_bitop3_b32 v2, v2, v9, s6 bitop3:0xf8
	v_bitop3_b32 v1, v1, v10, s6 bitop3:0xf8
	v_bitop3_b32 v8, v7, v122, s58 bitop3:0x60
	v_bitop3_b32 v9, v6, v119, s58 bitop3:0x60
	v_bcnt_u32_b32 v12, v8, 0
	v_bitop3_b32 v10, v5, v49, s58 bitop3:0x60
	v_bcnt_u32_b32 v12, v9, v12
	v_bcnt_u32_b32 v12, v10, v12
	s_nop 1
	v_add_u32_dpp v12, v12, v12 row_ror:8 row_mask:0xf bank_mask:0xf bound_ctrl:1
	s_nop 1
	v_add_u32_dpp v12, v12, v12 row_ror:4 row_mask:0xf bank_mask:0xf bound_ctrl:1
	s_nop 1
	v_add_u32_dpp v12, v12, v12 row_ror:2 row_mask:0xf bank_mask:0xf bound_ctrl:1
	s_nop 1
	v_add_u32_dpp v12, v12, v12 row_ror:1 row_mask:0xf bank_mask:0xf bound_ctrl:1
	s_nop 0
	v_readlane_b32 s6, v12, 0
	v_readlane_b32 s7, v12, 16
	v_readlane_b32 s8, v12, 32
	v_readlane_b32 s9, v12, 48
	s_add_i32 s6, s6, s7
	s_add_i32 s8, s8, s9
	s_add_i32 s6, s6, s57
	s_add_i32 s8, s6, s8
	s_cmpk_eq_i32 s8, 0x100
	s_cbranch_scc1 .Lrdx_eq
	s_cmpk_lt_i32 s8, 0x100
	s_cselect_b32 s6, -1, 0
	s_cselect_b32 s57, s8, s57
	s_xor_b32 s59, s58, s6
	v_bitop3_b32 v7, v7, v122, s59 bitop3:0x60
	v_bitop3_b32 v6, v6, v119, s59 bitop3:0x60
	v_bitop3_b32 v5, v5, v49, s59 bitop3:0x60
	v_bitop3_b32 v3, v3, v8, s6 bitop3:0xf8
	v_bitop3_b32 v2, v2, v9, s6 bitop3:0xf8
	v_bitop3_b32 v1, v1, v10, s6 bitop3:0xf8
	v_bitop3_b32 v8, v7, v120, s58 bitop3:0x60
	v_bitop3_b32 v9, v6, v117, s58 bitop3:0x60
	v_bcnt_u32_b32 v12, v8, 0
	v_bitop3_b32 v10, v5, v47, s58 bitop3:0x60
	v_bcnt_u32_b32 v12, v9, v12
	v_bcnt_u32_b32 v12, v10, v12
	s_nop 1
	v_add_u32_dpp v12, v12, v12 row_ror:8 row_mask:0xf bank_mask:0xf bound_ctrl:1
	s_nop 1
	v_add_u32_dpp v12, v12, v12 row_ror:4 row_mask:0xf bank_mask:0xf bound_ctrl:1
	s_nop 1
	v_add_u32_dpp v12, v12, v12 row_ror:2 row_mask:0xf bank_mask:0xf bound_ctrl:1
	s_nop 1
	v_add_u32_dpp v12, v12, v12 row_ror:1 row_mask:0xf bank_mask:0xf bound_ctrl:1
	s_nop 0
	v_readlane_b32 s6, v12, 0
	v_readlane_b32 s7, v12, 16
	v_readlane_b32 s8, v12, 32
	v_readlane_b32 s9, v12, 48
	s_add_i32 s6, s6, s7
	s_add_i32 s8, s8, s9
	s_add_i32 s6, s6, s57
	s_add_i32 s8, s6, s8
	s_cmpk_eq_i32 s8, 0x100
	s_cbranch_scc1 .Lrdx_eq
	s_cmpk_lt_i32 s8, 0x100
	s_cselect_b32 s6, -1, 0
	s_cselect_b32 s57, s8, s57
	s_xor_b32 s59, s58, s6
	v_bitop3_b32 v7, v7, v120, s59 bitop3:0x60
	v_bitop3_b32 v6, v6, v117, s59 bitop3:0x60
	v_bitop3_b32 v5, v5, v47, s59 bitop3:0x60
	v_bitop3_b32 v3, v3, v8, s6 bitop3:0xf8
	v_bitop3_b32 v2, v2, v9, s6 bitop3:0xf8
	v_bitop3_b32 v1, v1, v10, s6 bitop3:0xf8
	v_bitop3_b32 v8, v7, v118, s58 bitop3:0x60
	v_bitop3_b32 v9, v6, v115, s58 bitop3:0x60
	v_bcnt_u32_b32 v12, v8, 0
	v_bitop3_b32 v10, v5, v45, s58 bitop3:0x60
	v_bcnt_u32_b32 v12, v9, v12
	v_bcnt_u32_b32 v12, v10, v12
	s_nop 1
	v_add_u32_dpp v12, v12, v12 row_ror:8 row_mask:0xf bank_mask:0xf bound_ctrl:1
	s_nop 1
	v_add_u32_dpp v12, v12, v12 row_ror:4 row_mask:0xf bank_mask:0xf bound_ctrl:1
	s_nop 1
	v_add_u32_dpp v12, v12, v12 row_ror:2 row_mask:0xf bank_mask:0xf bound_ctrl:1
	s_nop 1
	v_add_u32_dpp v12, v12, v12 row_ror:1 row_mask:0xf bank_mask:0xf bound_ctrl:1
	s_nop 0
	v_readlane_b32 s6, v12, 0
	v_readlane_b32 s7, v12, 16
	v_readlane_b32 s8, v12, 32
	v_readlane_b32 s9, v12, 48
	s_add_i32 s6, s6, s7
	s_add_i32 s8, s8, s9
	s_add_i32 s6, s6, s57
	s_add_i32 s8, s6, s8
	s_cmpk_eq_i32 s8, 0x100
	s_cbranch_scc1 .Lrdx_eq
	s_cmpk_lt_i32 s8, 0x100
	s_cselect_b32 s6, -1, 0
	s_cselect_b32 s57, s8, s57
	s_xor_b32 s59, s58, s6
	v_bitop3_b32 v7, v7, v118, s59 bitop3:0x60
	v_bitop3_b32 v6, v6, v115, s59 bitop3:0x60
	v_bitop3_b32 v5, v5, v45, s59 bitop3:0x60
	v_bitop3_b32 v3, v3, v8, s6 bitop3:0xf8
	v_bitop3_b32 v2, v2, v9, s6 bitop3:0xf8
	v_bitop3_b32 v1, v1, v10, s6 bitop3:0xf8
	v_bitop3_b32 v8, v7, v116, s58 bitop3:0x60
	v_bitop3_b32 v9, v6, v113, s58 bitop3:0x60
	v_bcnt_u32_b32 v12, v8, 0
	v_bitop3_b32 v10, v5, v42, s58 bitop3:0x60
	v_bcnt_u32_b32 v12, v9, v12
	v_bcnt_u32_b32 v12, v10, v12
	s_nop 1
	v_add_u32_dpp v12, v12, v12 row_ror:8 row_mask:0xf bank_mask:0xf bound_ctrl:1
	s_nop 1
	v_add_u32_dpp v12, v12, v12 row_ror:4 row_mask:0xf bank_mask:0xf bound_ctrl:1
	s_nop 1
	v_add_u32_dpp v12, v12, v12 row_ror:2 row_mask:0xf bank_mask:0xf bound_ctrl:1
	s_nop 1
	v_add_u32_dpp v12, v12, v12 row_ror:1 row_mask:0xf bank_mask:0xf bound_ctrl:1
	s_nop 0
	v_readlane_b32 s6, v12, 0
	v_readlane_b32 s7, v12, 16
	v_readlane_b32 s8, v12, 32
	v_readlane_b32 s9, v12, 48
	s_add_i32 s6, s6, s7
	s_add_i32 s8, s8, s9
	s_add_i32 s6, s6, s57
	s_add_i32 s8, s6, s8
	s_cmpk_eq_i32 s8, 0x100
	s_cbranch_scc1 .Lrdx_eq
	s_cmpk_lt_i32 s8, 0x100
	s_cselect_b32 s6, -1, 0
	s_cselect_b32 s57, s8, s57
	s_xor_b32 s59, s58, s6
	v_bitop3_b32 v7, v7, v116, s59 bitop3:0x60
	v_bitop3_b32 v6, v6, v113, s59 bitop3:0x60
	v_bitop3_b32 v5, v5, v42, s59 bitop3:0x60
	v_bitop3_b32 v3, v3, v8, s6 bitop3:0xf8
	v_bitop3_b32 v2, v2, v9, s6 bitop3:0xf8
	v_bitop3_b32 v1, v1, v10, s6 bitop3:0xf8
	v_bitop3_b32 v8, v7, v114, s58 bitop3:0x60
	v_bitop3_b32 v9, v6, v111, s58 bitop3:0x60
	v_bcnt_u32_b32 v12, v8, 0
	v_bitop3_b32 v10, v5, v40, s58 bitop3:0x60
	v_bcnt_u32_b32 v12, v9, v12
	v_bcnt_u32_b32 v12, v10, v12
	s_nop 1
	v_add_u32_dpp v12, v12, v12 row_ror:8 row_mask:0xf bank_mask:0xf bound_ctrl:1
	s_nop 1
	v_add_u32_dpp v12, v12, v12 row_ror:4 row_mask:0xf bank_mask:0xf bound_ctrl:1
	s_nop 1
	v_add_u32_dpp v12, v12, v12 row_ror:2 row_mask:0xf bank_mask:0xf bound_ctrl:1
	s_nop 1
	v_add_u32_dpp v12, v12, v12 row_ror:1 row_mask:0xf bank_mask:0xf bound_ctrl:1
	s_nop 0
	v_readlane_b32 s6, v12, 0
	v_readlane_b32 s7, v12, 16
	v_readlane_b32 s8, v12, 32
	v_readlane_b32 s9, v12, 48
	s_add_i32 s6, s6, s7
	s_add_i32 s8, s8, s9
	s_add_i32 s6, s6, s57
	s_add_i32 s8, s6, s8
	s_cmpk_eq_i32 s8, 0x100
	s_cbranch_scc1 .Lrdx_eq
	s_cmpk_lt_i32 s8, 0x100
	s_cselect_b32 s6, -1, 0
	s_cselect_b32 s57, s8, s57
	s_xor_b32 s59, s58, s6
	v_bitop3_b32 v7, v7, v114, s59 bitop3:0x60
	v_bitop3_b32 v6, v6, v111, s59 bitop3:0x60
	v_bitop3_b32 v5, v5, v40, s59 bitop3:0x60
	v_bitop3_b32 v3, v3, v8, s6 bitop3:0xf8
	v_bitop3_b32 v2, v2, v9, s6 bitop3:0xf8
	v_bitop3_b32 v1, v1, v10, s6 bitop3:0xf8
	v_bitop3_b32 v8, v7, v112, s58 bitop3:0x60
	v_bitop3_b32 v9, v6, v109, s58 bitop3:0x60
	v_bcnt_u32_b32 v12, v8, 0
	v_bitop3_b32 v10, v5, v38, s58 bitop3:0x60
	v_bcnt_u32_b32 v12, v9, v12
	v_bcnt_u32_b32 v12, v10, v12
	s_nop 1
	v_add_u32_dpp v12, v12, v12 row_ror:8 row_mask:0xf bank_mask:0xf bound_ctrl:1
	s_nop 1
	v_add_u32_dpp v12, v12, v12 row_ror:4 row_mask:0xf bank_mask:0xf bound_ctrl:1
	s_nop 1
	v_add_u32_dpp v12, v12, v12 row_ror:2 row_mask:0xf bank_mask:0xf bound_ctrl:1
	s_nop 1
	v_add_u32_dpp v12, v12, v12 row_ror:1 row_mask:0xf bank_mask:0xf bound_ctrl:1
	s_nop 0
	v_readlane_b32 s6, v12, 0
	v_readlane_b32 s7, v12, 16
	v_readlane_b32 s8, v12, 32
	v_readlane_b32 s9, v12, 48
	s_add_i32 s6, s6, s7
	s_add_i32 s8, s8, s9
	s_add_i32 s6, s6, s57
	s_add_i32 s8, s6, s8
	s_cmpk_eq_i32 s8, 0x100
	s_cbranch_scc1 .Lrdx_eq
	s_cmpk_lt_i32 s8, 0x100
	s_cselect_b32 s6, -1, 0
	s_cselect_b32 s57, s8, s57
	s_xor_b32 s59, s58, s6
	v_bitop3_b32 v7, v7, v112, s59 bitop3:0x60
	v_bitop3_b32 v6, v6, v109, s59 bitop3:0x60
	v_bitop3_b32 v5, v5, v38, s59 bitop3:0x60
	v_bitop3_b32 v3, v3, v8, s6 bitop3:0xf8
	v_bitop3_b32 v2, v2, v9, s6 bitop3:0xf8
	v_bitop3_b32 v1, v1, v10, s6 bitop3:0xf8
	v_bitop3_b32 v8, v7, v110, s58 bitop3:0x60
	v_bitop3_b32 v9, v6, v107, s58 bitop3:0x60
	v_bcnt_u32_b32 v12, v8, 0
	v_bitop3_b32 v10, v5, v36, s58 bitop3:0x60
	v_bcnt_u32_b32 v12, v9, v12
	v_bcnt_u32_b32 v12, v10, v12
	s_nop 1
	v_add_u32_dpp v12, v12, v12 row_ror:8 row_mask:0xf bank_mask:0xf bound_ctrl:1
	s_nop 1
	v_add_u32_dpp v12, v12, v12 row_ror:4 row_mask:0xf bank_mask:0xf bound_ctrl:1
	s_nop 1
	v_add_u32_dpp v12, v12, v12 row_ror:2 row_mask:0xf bank_mask:0xf bound_ctrl:1
	s_nop 1
	v_add_u32_dpp v12, v12, v12 row_ror:1 row_mask:0xf bank_mask:0xf bound_ctrl:1
	s_nop 0
	v_readlane_b32 s6, v12, 0
	v_readlane_b32 s7, v12, 16
	v_readlane_b32 s8, v12, 32
	v_readlane_b32 s9, v12, 48
	s_add_i32 s6, s6, s7
	s_add_i32 s8, s8, s9
	s_add_i32 s6, s6, s57
	s_add_i32 s8, s6, s8
	s_cmpk_eq_i32 s8, 0x100
	s_cbranch_scc1 .Lrdx_eq
	s_cmpk_lt_i32 s8, 0x100
	s_cselect_b32 s6, -1, 0
	s_cselect_b32 s57, s8, s57
	s_xor_b32 s59, s58, s6
	v_bitop3_b32 v7, v7, v110, s59 bitop3:0x60
	v_bitop3_b32 v6, v6, v107, s59 bitop3:0x60
	v_bitop3_b32 v5, v5, v36, s59 bitop3:0x60
	v_bitop3_b32 v3, v3, v8, s6 bitop3:0xf8
	v_bitop3_b32 v2, v2, v9, s6 bitop3:0xf8
	v_bitop3_b32 v1, v1, v10, s6 bitop3:0xf8
	v_bitop3_b32 v8, v7, v108, s58 bitop3:0x60
	v_bitop3_b32 v9, v6, v106, s58 bitop3:0x60
	v_bcnt_u32_b32 v12, v8, 0
	v_bitop3_b32 v10, v5, v34, s58 bitop3:0x60
	v_bcnt_u32_b32 v12, v9, v12
	v_bcnt_u32_b32 v12, v10, v12
	s_nop 1
	v_add_u32_dpp v12, v12, v12 row_ror:8 row_mask:0xf bank_mask:0xf bound_ctrl:1
	s_nop 1
	v_add_u32_dpp v12, v12, v12 row_ror:4 row_mask:0xf bank_mask:0xf bound_ctrl:1
	s_nop 1
	v_add_u32_dpp v12, v12, v12 row_ror:2 row_mask:0xf bank_mask:0xf bound_ctrl:1
	s_nop 1
	v_add_u32_dpp v12, v12, v12 row_ror:1 row_mask:0xf bank_mask:0xf bound_ctrl:1
	s_nop 0
	v_readlane_b32 s6, v12, 0
	v_readlane_b32 s7, v12, 16
	v_readlane_b32 s8, v12, 32
	v_readlane_b32 s9, v12, 48
	s_add_i32 s6, s6, s7
	s_add_i32 s8, s8, s9
	s_add_i32 s6, s6, s57
	s_add_i32 s8, s6, s8
	s_cmpk_eq_i32 s8, 0x100
	s_cbranch_scc1 .Lrdx_eq
	s_cmpk_lt_i32 s8, 0x100
	s_cselect_b32 s6, -1, 0
	s_cselect_b32 s57, s8, s57
	s_xor_b32 s59, s58, s6
	v_bitop3_b32 v7, v7, v108, s59 bitop3:0x60
	v_bitop3_b32 v6, v6, v106, s59 bitop3:0x60
	v_bitop3_b32 v5, v5, v34, s59 bitop3:0x60
	v_bitop3_b32 v3, v3, v8, s6 bitop3:0xf8
	v_bitop3_b32 v2, v2, v9, s6 bitop3:0xf8
	v_bitop3_b32 v1, v1, v10, s6 bitop3:0xf8
	s_branch .LBB0_1099
.Lrdx_w4:
	s_mov_b32 s58, -1
	v_bitop3_b32 v8, v7, v189, s58 bitop3:0x60
	v_bitop3_b32 v9, v6, v186, s58 bitop3:0x60
	v_bcnt_u32_b32 v12, v8, 0
	v_bitop3_b32 v10, v5, v95, s58 bitop3:0x60
	v_bcnt_u32_b32 v12, v9, v12
	v_bitop3_b32 v11, v4, v92, s58 bitop3:0x60
	v_bcnt_u32_b32 v12, v10, v12
	v_bcnt_u32_b32 v12, v11, v12
	s_nop 1
	v_add_u32_dpp v12, v12, v12 row_ror:8 row_mask:0xf bank_mask:0xf bound_ctrl:1
	s_nop 1
	v_add_u32_dpp v12, v12, v12 row_ror:4 row_mask:0xf bank_mask:0xf bound_ctrl:1
	s_nop 1
	v_add_u32_dpp v12, v12, v12 row_ror:2 row_mask:0xf bank_mask:0xf bound_ctrl:1
	s_nop 1
	v_add_u32_dpp v12, v12, v12 row_ror:1 row_mask:0xf bank_mask:0xf bound_ctrl:1
	s_nop 0
	v_readlane_b32 s6, v12, 0
	v_readlane_b32 s7, v12, 16
	v_readlane_b32 s8, v12, 32
	v_readlane_b32 s9, v12, 48
	s_add_i32 s6, s6, s7
	s_add_i32 s8, s8, s9
	s_add_i32 s6, s6, s57
	s_add_i32 s8, s6, s8
	s_cmpk_eq_i32 s8, 0x100
	s_cbranch_scc1 .Lrdx_eq
	s_cmpk_lt_i32 s8, 0x100
	s_cselect_b32 s6, -1, 0
	s_cselect_b32 s57, s8, s57
	s_xor_b32 s59, s58, s6
	v_bitop3_b32 v7, v7, v189, s59 bitop3:0x60
	v_bitop3_b32 v6, v6, v186, s59 bitop3:0x60
	v_bitop3_b32 v5, v5, v95, s59 bitop3:0x60
	v_bitop3_b32 v4, v4, v92, s59 bitop3:0x60
	s_mov_b32 s58, s6
	v_bitop3_b32 v3, v3, v8, s6 bitop3:0xf8
	v_bitop3_b32 v2, v2, v9, s6 bitop3:0xf8
	v_bitop3_b32 v1, v1, v10, s6 bitop3:0xf8
	v_bitop3_b32 v0, v0, v11, s6 bitop3:0xf8
	v_bitop3_b32 v8, v7, v188, s58 bitop3:0x60
	v_bitop3_b32 v9, v6, v185, s58 bitop3:0x60
	v_bcnt_u32_b32 v12, v8, 0
	v_bitop3_b32 v10, v5, v94, s58 bitop3:0x60
	v_bcnt_u32_b32 v12, v9, v12
	v_bitop3_b32 v11, v4, v90, s58 bitop3:0x60
	v_bcnt_u32_b32 v12, v10, v12
	v_bcnt_u32_b32 v12, v11, v12
	s_nop 1
	v_add_u32_dpp v12, v12, v12 row_ror:8 row_mask:0xf bank_mask:0xf bound_ctrl:1
	s_nop 1
	v_add_u32_dpp v12, v12, v12 row_ror:4 row_mask:0xf bank_mask:0xf bound_ctrl:1
	s_nop 1
	v_add_u32_dpp v12, v12, v12 row_ror:2 row_mask:0xf bank_mask:0xf bound_ctrl:1
	s_nop 1
	v_add_u32_dpp v12, v12, v12 row_ror:1 row_mask:0xf bank_mask:0xf bound_ctrl:1
	s_nop 0
	v_readlane_b32 s6, v12, 0
	v_readlane_b32 s7, v12, 16
	v_readlane_b32 s8, v12, 32
	v_readlane_b32 s9, v12, 48
	s_add_i32 s6, s6, s7
	s_add_i32 s8, s8, s9
	s_add_i32 s6, s6, s57
	s_add_i32 s8, s6, s8
	s_cmpk_eq_i32 s8, 0x100
	s_cbranch_scc1 .Lrdx_eq
	s_cmpk_lt_i32 s8, 0x100
	s_cselect_b32 s6, -1, 0
	s_cselect_b32 s57, s8, s57
	s_xor_b32 s59, s58, s6
	v_bitop3_b32 v7, v7, v188, s59 bitop3:0x60
	v_bitop3_b32 v6, v6, v185, s59 bitop3:0x60
	v_bitop3_b32 v5, v5, v94, s59 bitop3:0x60
	v_bitop3_b32 v4, v4, v90, s59 bitop3:0x60
	v_bitop3_b32 v3, v3, v8, s6 bitop3:0xf8
	v_bitop3_b32 v2, v2, v9, s6 bitop3:0xf8
	v_bitop3_b32 v1, v1, v10, s6 bitop3:0xf8
	v_bitop3_b32 v0, v0, v11, s6 bitop3:0xf8
	v_bitop3_b32 v8, v7, v187, s58 bitop3:0x60
	v_bitop3_b32 v9, v6, v183, s58 bitop3:0x60
	v_bcnt_u32_b32 v12, v8, 0
	v_bitop3_b32 v10, v5, v93, s58 bitop3:0x60
	v_bcnt_u32_b32 v12, v9, v12
	v_bitop3_b32 v11, v4, v88, s58 bitop3:0x60
	v_bcnt_u32_b32 v12, v10, v12
	v_bcnt_u32_b32 v12, v11, v12
	s_nop 1
	v_add_u32_dpp v12, v12, v12 row_ror:8 row_mask:0xf bank_mask:0xf bound_ctrl:1
	s_nop 1
	v_add_u32_dpp v12, v12, v12 row_ror:4 row_mask:0xf bank_mask:0xf bound_ctrl:1
	s_nop 1
	v_add_u32_dpp v12, v12, v12 row_ror:2 row_mask:0xf bank_mask:0xf bound_ctrl:1
	s_nop 1
	v_add_u32_dpp v12, v12, v12 row_ror:1 row_mask:0xf bank_mask:0xf bound_ctrl:1
	s_nop 0
	v_readlane_b32 s6, v12, 0
	v_readlane_b32 s7, v12, 16
	v_readlane_b32 s8, v12, 32
	v_readlane_b32 s9, v12, 48
	s_add_i32 s6, s6, s7
	s_add_i32 s8, s8, s9
	s_add_i32 s6, s6, s57
	s_add_i32 s8, s6, s8
	s_cmpk_eq_i32 s8, 0x100
	s_cbranch_scc1 .Lrdx_eq
	s_cmpk_lt_i32 s8, 0x100
	s_cselect_b32 s6, -1, 0
	s_cselect_b32 s57, s8, s57
	s_xor_b32 s59, s58, s6
	v_bitop3_b32 v7, v7, v187, s59 bitop3:0x60
	v_bitop3_b32 v6, v6, v183, s59 bitop3:0x60
	v_bitop3_b32 v5, v5, v93, s59 bitop3:0x60
	v_bitop3_b32 v4, v4, v88, s59 bitop3:0x60
	v_bitop3_b32 v3, v3, v8, s6 bitop3:0xf8
	v_bitop3_b32 v2, v2, v9, s6 bitop3:0xf8
	v_bitop3_b32 v1, v1, v10, s6 bitop3:0xf8
	v_bitop3_b32 v0, v0, v11, s6 bitop3:0xf8
	v_bitop3_b32 v8, v7, v184, s58 bitop3:0x60
	v_bitop3_b32 v9, v6, v161, s58 bitop3:0x60
	v_bcnt_u32_b32 v12, v8, 0
	v_bitop3_b32 v10, v5, v91, s58 bitop3:0x60
	v_bcnt_u32_b32 v12, v9, v12
	v_bitop3_b32 v11, v4, v86, s58 bitop3:0x60
	v_bcnt_u32_b32 v12, v10, v12
	v_bcnt_u32_b32 v12, v11, v12
	s_nop 1
	v_add_u32_dpp v12, v12, v12 row_ror:8 row_mask:0xf bank_mask:0xf bound_ctrl:1
	s_nop 1
	v_add_u32_dpp v12, v12, v12 row_ror:4 row_mask:0xf bank_mask:0xf bound_ctrl:1
	s_nop 1
	v_add_u32_dpp v12, v12, v12 row_ror:2 row_mask:0xf bank_mask:0xf bound_ctrl:1
	s_nop 1
	v_add_u32_dpp v12, v12, v12 row_ror:1 row_mask:0xf bank_mask:0xf bound_ctrl:1
	s_nop 0
	v_readlane_b32 s6, v12, 0
	v_readlane_b32 s7, v12, 16
	v_readlane_b32 s8, v12, 32
	v_readlane_b32 s9, v12, 48
	s_add_i32 s6, s6, s7
	s_add_i32 s8, s8, s9
	s_add_i32 s6, s6, s57
	s_add_i32 s8, s6, s8
	s_cmpk_eq_i32 s8, 0x100
	s_cbranch_scc1 .Lrdx_eq
	s_cmpk_lt_i32 s8, 0x100
	s_cselect_b32 s6, -1, 0
	s_cselect_b32 s57, s8, s57
	s_xor_b32 s59, s58, s6
	v_bitop3_b32 v7, v7, v184, s59 bitop3:0x60
	v_bitop3_b32 v6, v6, v161, s59 bitop3:0x60
	v_bitop3_b32 v5, v5, v91, s59 bitop3:0x60
	v_bitop3_b32 v4, v4, v86, s59 bitop3:0x60
	v_bitop3_b32 v3, v3, v8, s6 bitop3:0xf8
	v_bitop3_b32 v2, v2, v9, s6 bitop3:0xf8
	v_bitop3_b32 v1, v1, v10, s6 bitop3:0xf8
	v_bitop3_b32 v0, v0, v11, s6 bitop3:0xf8
	v_bitop3_b32 v8, v7, v181, s58 bitop3:0x60
	v_bitop3_b32 v9, v6, v159, s58 bitop3:0x60
	v_bcnt_u32_b32 v12, v8, 0
	v_bitop3_b32 v10, v5, v89, s58 bitop3:0x60
	v_bcnt_u32_b32 v12, v9, v12
	v_bitop3_b32 v11, v4, v84, s58 bitop3:0x60
	v_bcnt_u32_b32 v12, v10, v12
	v_bcnt_u32_b32 v12, v11, v12
	s_nop 1
	v_add_u32_dpp v12, v12, v12 row_ror:8 row_mask:0xf bank_mask:0xf bound_ctrl:1
	s_nop 1
	v_add_u32_dpp v12, v12, v12 row_ror:4 row_mask:0xf bank_mask:0xf bound_ctrl:1
	s_nop 1
	v_add_u32_dpp v12, v12, v12 row_ror:2 row_mask:0xf bank_mask:0xf bound_ctrl:1
	s_nop 1
	v_add_u32_dpp v12, v12, v12 row_ror:1 row_mask:0xf bank_mask:0xf bound_ctrl:1
	s_nop 0
	v_readlane_b32 s6, v12, 0
	v_readlane_b32 s7, v12, 16
	v_readlane_b32 s8, v12, 32
	v_readlane_b32 s9, v12, 48
	s_add_i32 s6, s6, s7
	s_add_i32 s8, s8, s9
	s_add_i32 s6, s6, s57
	s_add_i32 s8, s6, s8
	s_cmpk_eq_i32 s8, 0x100
	s_cbranch_scc1 .Lrdx_eq
	s_cmpk_lt_i32 s8, 0x100
	s_cselect_b32 s6, -1, 0
	s_cselect_b32 s57, s8, s57
	s_xor_b32 s59, s58, s6
	v_bitop3_b32 v7, v7, v181, s59 bitop3:0x60
	v_bitop3_b32 v6, v6, v159, s59 bitop3:0x60
	v_bitop3_b32 v5, v5, v89, s59 bitop3:0x60
	v_bitop3_b32 v4, v4, v84, s59 bitop3:0x60
	v_bitop3_b32 v3, v3, v8, s6 bitop3:0xf8
	v_bitop3_b32 v2, v2, v9, s6 bitop3:0xf8
	v_bitop3_b32 v1, v1, v10, s6 bitop3:0xf8
	v_bitop3_b32 v0, v0, v11, s6 bitop3:0xf8
	v_bitop3_b32 v8, v7, v160, s58 bitop3:0x60
	v_bitop3_b32 v9, v6, v157, s58 bitop3:0x60
	v_bcnt_u32_b32 v12, v8, 0
	v_bitop3_b32 v10, v5, v87, s58 bitop3:0x60
	v_bcnt_u32_b32 v12, v9, v12
	v_bitop3_b32 v11, v4, v82, s58 bitop3:0x60
	v_bcnt_u32_b32 v12, v10, v12
	v_bcnt_u32_b32 v12, v11, v12
	s_nop 1
	v_add_u32_dpp v12, v12, v12 row_ror:8 row_mask:0xf bank_mask:0xf bound_ctrl:1
	s_nop 1
	v_add_u32_dpp v12, v12, v12 row_ror:4 row_mask:0xf bank_mask:0xf bound_ctrl:1
	s_nop 1
	v_add_u32_dpp v12, v12, v12 row_ror:2 row_mask:0xf bank_mask:0xf bound_ctrl:1
	s_nop 1
	v_add_u32_dpp v12, v12, v12 row_ror:1 row_mask:0xf bank_mask:0xf bound_ctrl:1
	s_nop 0
	v_readlane_b32 s6, v12, 0
	v_readlane_b32 s7, v12, 16
	v_readlane_b32 s8, v12, 32
	v_readlane_b32 s9, v12, 48
	s_add_i32 s6, s6, s7
	s_add_i32 s8, s8, s9
	s_add_i32 s6, s6, s57
	s_add_i32 s8, s6, s8
	s_cmpk_eq_i32 s8, 0x100
	s_cbranch_scc1 .Lrdx_eq
	s_cmpk_lt_i32 s8, 0x100
	s_cselect_b32 s6, -1, 0
	s_cselect_b32 s57, s8, s57
	s_xor_b32 s59, s58, s6
	v_bitop3_b32 v7, v7, v160, s59 bitop3:0x60
	v_bitop3_b32 v6, v6, v157, s59 bitop3:0x60
	v_bitop3_b32 v5, v5, v87, s59 bitop3:0x60
	v_bitop3_b32 v4, v4, v82, s59 bitop3:0x60
	v_bitop3_b32 v3, v3, v8, s6 bitop3:0xf8
	v_bitop3_b32 v2, v2, v9, s6 bitop3:0xf8
	v_bitop3_b32 v1, v1, v10, s6 bitop3:0xf8
	v_bitop3_b32 v0, v0, v11, s6 bitop3:0xf8
	v_bitop3_b32 v8, v7, v158, s58 bitop3:0x60
	v_bitop3_b32 v9, v6, v155, s58 bitop3:0x60
	v_bcnt_u32_b32 v12, v8, 0
	v_bitop3_b32 v10, v5, v85, s58 bitop3:0x60
	v_bcnt_u32_b32 v12, v9, v12
	v_bitop3_b32 v11, v4, v80, s58 bitop3:0x60
	v_bcnt_u32_b32 v12, v10, v12
	v_bcnt_u32_b32 v12, v11, v12
	s_nop 1
	v_add_u32_dpp v12, v12, v12 row_ror:8 row_mask:0xf bank_mask:0xf bound_ctrl:1
	s_nop 1
	v_add_u32_dpp v12, v12, v12 row_ror:4 row_mask:0xf bank_mask:0xf bound_ctrl:1
	s_nop 1
	v_add_u32_dpp v12, v12, v12 row_ror:2 row_mask:0xf bank_mask:0xf bound_ctrl:1
	s_nop 1
	v_add_u32_dpp v12, v12, v12 row_ror:1 row_mask:0xf bank_mask:0xf bound_ctrl:1
	s_nop 0
	v_readlane_b32 s6, v12, 0
	v_readlane_b32 s7, v12, 16
	v_readlane_b32 s8, v12, 32
	v_readlane_b32 s9, v12, 48
	s_add_i32 s6, s6, s7
	s_add_i32 s8, s8, s9
	s_add_i32 s6, s6, s57
	s_add_i32 s8, s6, s8
	s_cmpk_eq_i32 s8, 0x100
	s_cbranch_scc1 .Lrdx_eq
	s_cmpk_lt_i32 s8, 0x100
	s_cselect_b32 s6, -1, 0
	s_cselect_b32 s57, s8, s57
	s_xor_b32 s59, s58, s6
	v_bitop3_b32 v7, v7, v158, s59 bitop3:0x60
	v_bitop3_b32 v6, v6, v155, s59 bitop3:0x60
	v_bitop3_b32 v5, v5, v85, s59 bitop3:0x60
	v_bitop3_b32 v4, v4, v80, s59 bitop3:0x60
	v_bitop3_b32 v3, v3, v8, s6 bitop3:0xf8
	v_bitop3_b32 v2, v2, v9, s6 bitop3:0xf8
	v_bitop3_b32 v1, v1, v10, s6 bitop3:0xf8
	v_bitop3_b32 v0, v0, v11, s6 bitop3:0xf8
	v_bitop3_b32 v8, v7, v156, s58 bitop3:0x60
	v_bitop3_b32 v9, v6, v153, s58 bitop3:0x60
	v_bcnt_u32_b32 v12, v8, 0
	v_bitop3_b32 v10, v5, v83, s58 bitop3:0x60
	v_bcnt_u32_b32 v12, v9, v12
	v_bitop3_b32 v11, v4, v78, s58 bitop3:0x60
	v_bcnt_u32_b32 v12, v10, v12
	v_bcnt_u32_b32 v12, v11, v12
	s_nop 1
	v_add_u32_dpp v12, v12, v12 row_ror:8 row_mask:0xf bank_mask:0xf bound_ctrl:1
	s_nop 1
	v_add_u32_dpp v12, v12, v12 row_ror:4 row_mask:0xf bank_mask:0xf bound_ctrl:1
	s_nop 1
	v_add_u32_dpp v12, v12, v12 row_ror:2 row_mask:0xf bank_mask:0xf bound_ctrl:1
	s_nop 1
	v_add_u32_dpp v12, v12, v12 row_ror:1 row_mask:0xf bank_mask:0xf bound_ctrl:1
	s_nop 0
	v_readlane_b32 s6, v12, 0
	v_readlane_b32 s7, v12, 16
	v_readlane_b32 s8, v12, 32
	v_readlane_b32 s9, v12, 48
	s_add_i32 s6, s6, s7
	s_add_i32 s8, s8, s9
	s_add_i32 s6, s6, s57
	s_add_i32 s8, s6, s8
	s_cmpk_eq_i32 s8, 0x100
	s_cbranch_scc1 .Lrdx_eq
	s_cmpk_lt_i32 s8, 0x100
	s_cselect_b32 s6, -1, 0
	s_cselect_b32 s57, s8, s57
	s_xor_b32 s59, s58, s6
	v_bitop3_b32 v7, v7, v156, s59 bitop3:0x60
	v_bitop3_b32 v6, v6, v153, s59 bitop3:0x60
	v_bitop3_b32 v5, v5, v83, s59 bitop3:0x60
	v_bitop3_b32 v4, v4, v78, s59 bitop3:0x60
	v_bitop3_b32 v3, v3, v8, s6 bitop3:0xf8
	v_bitop3_b32 v2, v2, v9, s6 bitop3:0xf8
	v_bitop3_b32 v1, v1, v10, s6 bitop3:0xf8
	v_bitop3_b32 v0, v0, v11, s6 bitop3:0xf8
	v_bitop3_b32 v8, v7, v154, s58 bitop3:0x60
	v_bitop3_b32 v9, v6, v151, s58 bitop3:0x60
	v_bcnt_u32_b32 v12, v8, 0
	v_bitop3_b32 v10, v5, v81, s58 bitop3:0x60
	v_bcnt_u32_b32 v12, v9, v12
	v_bitop3_b32 v11, v4, v76, s58 bitop3:0x60
	v_bcnt_u32_b32 v12, v10, v12
	v_bcnt_u32_b32 v12, v11, v12
	s_nop 1
	v_add_u32_dpp v12, v12, v12 row_ror:8 row_mask:0xf bank_mask:0xf bound_ctrl:1
	s_nop 1
	v_add_u32_dpp v12, v12, v12 row_ror:4 row_mask:0xf bank_mask:0xf bound_ctrl:1
	s_nop 1
	v_add_u32_dpp v12, v12, v12 row_ror:2 row_mask:0xf bank_mask:0xf bound_ctrl:1
	s_nop 1
	v_add_u32_dpp v12, v12, v12 row_ror:1 row_mask:0xf bank_mask:0xf bound_ctrl:1
	s_nop 0
	v_readlane_b32 s6, v12, 0
	v_readlane_b32 s7, v12, 16
	v_readlane_b32 s8, v12, 32
	v_readlane_b32 s9, v12, 48
	s_add_i32 s6, s6, s7
	s_add_i32 s8, s8, s9
	s_add_i32 s6, s6, s57
	s_add_i32 s8, s6, s8
	s_cmpk_eq_i32 s8, 0x100
	s_cbranch_scc1 .Lrdx_eq
	s_cmpk_lt_i32 s8, 0x100
	s_cselect_b32 s6, -1, 0
	s_cselect_b32 s57, s8, s57
	s_xor_b32 s59, s58, s6
	v_bitop3_b32 v7, v7, v154, s59 bitop3:0x60
	v_bitop3_b32 v6, v6, v151, s59 bitop3:0x60
	v_bitop3_b32 v5, v5, v81, s59 bitop3:0x60
	v_bitop3_b32 v4, v4, v76, s59 bitop3:0x60
	v_bitop3_b32 v3, v3, v8, s6 bitop3:0xf8
	v_bitop3_b32 v2, v2, v9, s6 bitop3:0xf8
	v_bitop3_b32 v1, v1, v10, s6 bitop3:0xf8
	v_bitop3_b32 v0, v0, v11, s6 bitop3:0xf8
	v_bitop3_b32 v8, v7, v152, s58 bitop3:0x60
	v_bitop3_b32 v9, v6, v149, s58 bitop3:0x60
	v_bcnt_u32_b32 v12, v8, 0
	v_bitop3_b32 v10, v5, v79, s58 bitop3:0x60
	v_bcnt_u32_b32 v12, v9, v12
	v_bitop3_b32 v11, v4, v74, s58 bitop3:0x60
	v_bcnt_u32_b32 v12, v10, v12
	v_bcnt_u32_b32 v12, v11, v12
	s_nop 1
	v_add_u32_dpp v12, v12, v12 row_ror:8 row_mask:0xf bank_mask:0xf bound_ctrl:1
	s_nop 1
	v_add_u32_dpp v12, v12, v12 row_ror:4 row_mask:0xf bank_mask:0xf bound_ctrl:1
	s_nop 1
	v_add_u32_dpp v12, v12, v12 row_ror:2 row_mask:0xf bank_mask:0xf bound_ctrl:1
	s_nop 1
	v_add_u32_dpp v12, v12, v12 row_ror:1 row_mask:0xf bank_mask:0xf bound_ctrl:1
	s_nop 0
	v_readlane_b32 s6, v12, 0
	v_readlane_b32 s7, v12, 16
	v_readlane_b32 s8, v12, 32
	v_readlane_b32 s9, v12, 48
	s_add_i32 s6, s6, s7
	s_add_i32 s8, s8, s9
	s_add_i32 s6, s6, s57
	s_add_i32 s8, s6, s8
	s_cmpk_eq_i32 s8, 0x100
	s_cbranch_scc1 .Lrdx_eq
	s_cmpk_lt_i32 s8, 0x100
	s_cselect_b32 s6, -1, 0
	s_cselect_b32 s57, s8, s57
	s_xor_b32 s59, s58, s6
	v_bitop3_b32 v7, v7, v152, s59 bitop3:0x60
	v_bitop3_b32 v6, v6, v149, s59 bitop3:0x60
	v_bitop3_b32 v5, v5, v79, s59 bitop3:0x60
	v_bitop3_b32 v4, v4, v74, s59 bitop3:0x60
	v_bitop3_b32 v3, v3, v8, s6 bitop3:0xf8
	v_bitop3_b32 v2, v2, v9, s6 bitop3:0xf8
	v_bitop3_b32 v1, v1, v10, s6 bitop3:0xf8
	v_bitop3_b32 v0, v0, v11, s6 bitop3:0xf8
	v_bitop3_b32 v8, v7, v150, s58 bitop3:0x60
	v_bitop3_b32 v9, v6, v147, s58 bitop3:0x60
	v_bcnt_u32_b32 v12, v8, 0
	v_bitop3_b32 v10, v5, v77, s58 bitop3:0x60
	v_bcnt_u32_b32 v12, v9, v12
	v_bitop3_b32 v11, v4, v72, s58 bitop3:0x60
	v_bcnt_u32_b32 v12, v10, v12
	v_bcnt_u32_b32 v12, v11, v12
	s_nop 1
	v_add_u32_dpp v12, v12, v12 row_ror:8 row_mask:0xf bank_mask:0xf bound_ctrl:1
	s_nop 1
	v_add_u32_dpp v12, v12, v12 row_ror:4 row_mask:0xf bank_mask:0xf bound_ctrl:1
	s_nop 1
	v_add_u32_dpp v12, v12, v12 row_ror:2 row_mask:0xf bank_mask:0xf bound_ctrl:1
	s_nop 1
	v_add_u32_dpp v12, v12, v12 row_ror:1 row_mask:0xf bank_mask:0xf bound_ctrl:1
	s_nop 0
	v_readlane_b32 s6, v12, 0
	v_readlane_b32 s7, v12, 16
	v_readlane_b32 s8, v12, 32
	v_readlane_b32 s9, v12, 48
	s_add_i32 s6, s6, s7
	s_add_i32 s8, s8, s9
	s_add_i32 s6, s6, s57
	s_add_i32 s8, s6, s8
	s_cmpk_eq_i32 s8, 0x100
	s_cbranch_scc1 .Lrdx_eq
	s_cmpk_lt_i32 s8, 0x100
	s_cselect_b32 s6, -1, 0
	s_cselect_b32 s57, s8, s57
	s_xor_b32 s59, s58, s6
	v_bitop3_b32 v7, v7, v150, s59 bitop3:0x60
	v_bitop3_b32 v6, v6, v147, s59 bitop3:0x60
	v_bitop3_b32 v5, v5, v77, s59 bitop3:0x60
	v_bitop3_b32 v4, v4, v72, s59 bitop3:0x60
	v_bitop3_b32 v3, v3, v8, s6 bitop3:0xf8
	v_bitop3_b32 v2, v2, v9, s6 bitop3:0xf8
	v_bitop3_b32 v1, v1, v10, s6 bitop3:0xf8
	v_bitop3_b32 v0, v0, v11, s6 bitop3:0xf8
	v_bitop3_b32 v8, v7, v148, s58 bitop3:0x60
	v_bitop3_b32 v9, v6, v145, s58 bitop3:0x60
	v_bcnt_u32_b32 v12, v8, 0
	v_bitop3_b32 v10, v5, v75, s58 bitop3:0x60
	v_bcnt_u32_b32 v12, v9, v12
	v_bitop3_b32 v11, v4, v70, s58 bitop3:0x60
	v_bcnt_u32_b32 v12, v10, v12
	v_bcnt_u32_b32 v12, v11, v12
	s_nop 1
	v_add_u32_dpp v12, v12, v12 row_ror:8 row_mask:0xf bank_mask:0xf bound_ctrl:1
	s_nop 1
	v_add_u32_dpp v12, v12, v12 row_ror:4 row_mask:0xf bank_mask:0xf bound_ctrl:1
	s_nop 1
	v_add_u32_dpp v12, v12, v12 row_ror:2 row_mask:0xf bank_mask:0xf bound_ctrl:1
	s_nop 1
	v_add_u32_dpp v12, v12, v12 row_ror:1 row_mask:0xf bank_mask:0xf bound_ctrl:1
	s_nop 0
	v_readlane_b32 s6, v12, 0
	v_readlane_b32 s7, v12, 16
	v_readlane_b32 s8, v12, 32
	v_readlane_b32 s9, v12, 48
	s_add_i32 s6, s6, s7
	s_add_i32 s8, s8, s9
	s_add_i32 s6, s6, s57
	s_add_i32 s8, s6, s8
	s_cmpk_eq_i32 s8, 0x100
	s_cbranch_scc1 .Lrdx_eq
	s_cmpk_lt_i32 s8, 0x100
	s_cselect_b32 s6, -1, 0
	s_cselect_b32 s57, s8, s57
	s_xor_b32 s59, s58, s6
	v_bitop3_b32 v7, v7, v148, s59 bitop3:0x60
	v_bitop3_b32 v6, v6, v145, s59 bitop3:0x60
	v_bitop3_b32 v5, v5, v75, s59 bitop3:0x60
	v_bitop3_b32 v4, v4, v70, s59 bitop3:0x60
	v_bitop3_b32 v3, v3, v8, s6 bitop3:0xf8
	v_bitop3_b32 v2, v2, v9, s6 bitop3:0xf8
	v_bitop3_b32 v1, v1, v10, s6 bitop3:0xf8
	v_bitop3_b32 v0, v0, v11, s6 bitop3:0xf8
	v_bitop3_b32 v8, v7, v146, s58 bitop3:0x60
	v_bitop3_b32 v9, v6, v143, s58 bitop3:0x60
	v_bcnt_u32_b32 v12, v8, 0
	v_bitop3_b32 v10, v5, v73, s58 bitop3:0x60
	v_bcnt_u32_b32 v12, v9, v12
	v_bitop3_b32 v11, v4, v68, s58 bitop3:0x60
	v_bcnt_u32_b32 v12, v10, v12
	v_bcnt_u32_b32 v12, v11, v12
	s_nop 1
	v_add_u32_dpp v12, v12, v12 row_ror:8 row_mask:0xf bank_mask:0xf bound_ctrl:1
	s_nop 1
	v_add_u32_dpp v12, v12, v12 row_ror:4 row_mask:0xf bank_mask:0xf bound_ctrl:1
	s_nop 1
	v_add_u32_dpp v12, v12, v12 row_ror:2 row_mask:0xf bank_mask:0xf bound_ctrl:1
	s_nop 1
	v_add_u32_dpp v12, v12, v12 row_ror:1 row_mask:0xf bank_mask:0xf bound_ctrl:1
	s_nop 0
	v_readlane_b32 s6, v12, 0
	v_readlane_b32 s7, v12, 16
	v_readlane_b32 s8, v12, 32
	v_readlane_b32 s9, v12, 48
	s_add_i32 s6, s6, s7
	s_add_i32 s8, s8, s9
	s_add_i32 s6, s6, s57
	s_add_i32 s8, s6, s8
	s_cmpk_eq_i32 s8, 0x100
	s_cbranch_scc1 .Lrdx_eq
	s_cmpk_lt_i32 s8, 0x100
	s_cselect_b32 s6, -1, 0
	s_cselect_b32 s57, s8, s57
	s_xor_b32 s59, s58, s6
	v_bitop3_b32 v7, v7, v146, s59 bitop3:0x60
	v_bitop3_b32 v6, v6, v143, s59 bitop3:0x60
	v_bitop3_b32 v5, v5, v73, s59 bitop3:0x60
	v_bitop3_b32 v4, v4, v68, s59 bitop3:0x60
	v_bitop3_b32 v3, v3, v8, s6 bitop3:0xf8
	v_bitop3_b32 v2, v2, v9, s6 bitop3:0xf8
	v_bitop3_b32 v1, v1, v10, s6 bitop3:0xf8
	v_bitop3_b32 v0, v0, v11, s6 bitop3:0xf8
	v_bitop3_b32 v8, v7, v144, s58 bitop3:0x60
	v_bitop3_b32 v9, v6, v141, s58 bitop3:0x60
	v_bcnt_u32_b32 v12, v8, 0
	v_bitop3_b32 v10, v5, v71, s58 bitop3:0x60
	v_bcnt_u32_b32 v12, v9, v12
	v_bitop3_b32 v11, v4, v66, s58 bitop3:0x60
	v_bcnt_u32_b32 v12, v10, v12
	v_bcnt_u32_b32 v12, v11, v12
	s_nop 1
	v_add_u32_dpp v12, v12, v12 row_ror:8 row_mask:0xf bank_mask:0xf bound_ctrl:1
	s_nop 1
	v_add_u32_dpp v12, v12, v12 row_ror:4 row_mask:0xf bank_mask:0xf bound_ctrl:1
	s_nop 1
	v_add_u32_dpp v12, v12, v12 row_ror:2 row_mask:0xf bank_mask:0xf bound_ctrl:1
	s_nop 1
	v_add_u32_dpp v12, v12, v12 row_ror:1 row_mask:0xf bank_mask:0xf bound_ctrl:1
	s_nop 0
	v_readlane_b32 s6, v12, 0
	v_readlane_b32 s7, v12, 16
	v_readlane_b32 s8, v12, 32
	v_readlane_b32 s9, v12, 48
	s_add_i32 s6, s6, s7
	s_add_i32 s8, s8, s9
	s_add_i32 s6, s6, s57
	s_add_i32 s8, s6, s8
	s_cmpk_eq_i32 s8, 0x100
	s_cbranch_scc1 .Lrdx_eq
	s_cmpk_lt_i32 s8, 0x100
	s_cselect_b32 s6, -1, 0
	s_cselect_b32 s57, s8, s57
	s_xor_b32 s59, s58, s6
	v_bitop3_b32 v7, v7, v144, s59 bitop3:0x60
	v_bitop3_b32 v6, v6, v141, s59 bitop3:0x60
	v_bitop3_b32 v5, v5, v71, s59 bitop3:0x60
	v_bitop3_b32 v4, v4, v66, s59 bitop3:0x60
	v_bitop3_b32 v3, v3, v8, s6 bitop3:0xf8
	v_bitop3_b32 v2, v2, v9, s6 bitop3:0xf8
	v_bitop3_b32 v1, v1, v10, s6 bitop3:0xf8
	v_bitop3_b32 v0, v0, v11, s6 bitop3:0xf8
	v_bitop3_b32 v8, v7, v142, s58 bitop3:0x60
	v_bitop3_b32 v9, v6, v139, s58 bitop3:0x60
	v_bcnt_u32_b32 v12, v8, 0
	v_bitop3_b32 v10, v5, v69, s58 bitop3:0x60
	v_bcnt_u32_b32 v12, v9, v12
	v_bitop3_b32 v11, v4, v64, s58 bitop3:0x60
	v_bcnt_u32_b32 v12, v10, v12
	v_bcnt_u32_b32 v12, v11, v12
	s_nop 1
	v_add_u32_dpp v12, v12, v12 row_ror:8 row_mask:0xf bank_mask:0xf bound_ctrl:1
	s_nop 1
	v_add_u32_dpp v12, v12, v12 row_ror:4 row_mask:0xf bank_mask:0xf bound_ctrl:1
	s_nop 1
	v_add_u32_dpp v12, v12, v12 row_ror:2 row_mask:0xf bank_mask:0xf bound_ctrl:1
	s_nop 1
	v_add_u32_dpp v12, v12, v12 row_ror:1 row_mask:0xf bank_mask:0xf bound_ctrl:1
	s_nop 0
	v_readlane_b32 s6, v12, 0
	v_readlane_b32 s7, v12, 16
	v_readlane_b32 s8, v12, 32
	v_readlane_b32 s9, v12, 48
	s_add_i32 s6, s6, s7
	s_add_i32 s8, s8, s9
	s_add_i32 s6, s6, s57
	s_add_i32 s8, s6, s8
	s_cmpk_eq_i32 s8, 0x100
	s_cbranch_scc1 .Lrdx_eq
	s_cmpk_lt_i32 s8, 0x100
	s_cselect_b32 s6, -1, 0
	s_cselect_b32 s57, s8, s57
	s_xor_b32 s59, s58, s6
	v_bitop3_b32 v7, v7, v142, s59 bitop3:0x60
	v_bitop3_b32 v6, v6, v139, s59 bitop3:0x60
	v_bitop3_b32 v5, v5, v69, s59 bitop3:0x60
	v_bitop3_b32 v4, v4, v64, s59 bitop3:0x60
	v_bitop3_b32 v3, v3, v8, s6 bitop3:0xf8
	v_bitop3_b32 v2, v2, v9, s6 bitop3:0xf8
	v_bitop3_b32 v1, v1, v10, s6 bitop3:0xf8
	v_bitop3_b32 v0, v0, v11, s6 bitop3:0xf8
	v_bitop3_b32 v8, v7, v140, s58 bitop3:0x60
	v_bitop3_b32 v9, v6, v137, s58 bitop3:0x60
	v_bcnt_u32_b32 v12, v8, 0
	v_bitop3_b32 v10, v5, v67, s58 bitop3:0x60
	v_bcnt_u32_b32 v12, v9, v12
	v_bitop3_b32 v11, v4, v62, s58 bitop3:0x60
	v_bcnt_u32_b32 v12, v10, v12
	v_bcnt_u32_b32 v12, v11, v12
	s_nop 1
	v_add_u32_dpp v12, v12, v12 row_ror:8 row_mask:0xf bank_mask:0xf bound_ctrl:1
	s_nop 1
	v_add_u32_dpp v12, v12, v12 row_ror:4 row_mask:0xf bank_mask:0xf bound_ctrl:1
	s_nop 1
	v_add_u32_dpp v12, v12, v12 row_ror:2 row_mask:0xf bank_mask:0xf bound_ctrl:1
	s_nop 1
	v_add_u32_dpp v12, v12, v12 row_ror:1 row_mask:0xf bank_mask:0xf bound_ctrl:1
	s_nop 0
	v_readlane_b32 s6, v12, 0
	v_readlane_b32 s7, v12, 16
	v_readlane_b32 s8, v12, 32
	v_readlane_b32 s9, v12, 48
	s_add_i32 s6, s6, s7
	s_add_i32 s8, s8, s9
	s_add_i32 s6, s6, s57
	s_add_i32 s8, s6, s8
	s_cmpk_eq_i32 s8, 0x100
	s_cbranch_scc1 .Lrdx_eq
	s_cmpk_lt_i32 s8, 0x100
	s_cselect_b32 s6, -1, 0
	s_cselect_b32 s57, s8, s57
	s_xor_b32 s59, s58, s6
	v_bitop3_b32 v7, v7, v140, s59 bitop3:0x60
	v_bitop3_b32 v6, v6, v137, s59 bitop3:0x60
	v_bitop3_b32 v5, v5, v67, s59 bitop3:0x60
	v_bitop3_b32 v4, v4, v62, s59 bitop3:0x60
	v_bitop3_b32 v3, v3, v8, s6 bitop3:0xf8
	v_bitop3_b32 v2, v2, v9, s6 bitop3:0xf8
	v_bitop3_b32 v1, v1, v10, s6 bitop3:0xf8
	v_bitop3_b32 v0, v0, v11, s6 bitop3:0xf8
	v_bitop3_b32 v8, v7, v138, s58 bitop3:0x60
	v_bitop3_b32 v9, v6, v135, s58 bitop3:0x60
	v_bcnt_u32_b32 v12, v8, 0
	v_bitop3_b32 v10, v5, v65, s58 bitop3:0x60
	v_bcnt_u32_b32 v12, v9, v12
	v_bitop3_b32 v11, v4, v60, s58 bitop3:0x60
	v_bcnt_u32_b32 v12, v10, v12
	v_bcnt_u32_b32 v12, v11, v12
	s_nop 1
	v_add_u32_dpp v12, v12, v12 row_ror:8 row_mask:0xf bank_mask:0xf bound_ctrl:1
	s_nop 1
	v_add_u32_dpp v12, v12, v12 row_ror:4 row_mask:0xf bank_mask:0xf bound_ctrl:1
	s_nop 1
	v_add_u32_dpp v12, v12, v12 row_ror:2 row_mask:0xf bank_mask:0xf bound_ctrl:1
	s_nop 1
	v_add_u32_dpp v12, v12, v12 row_ror:1 row_mask:0xf bank_mask:0xf bound_ctrl:1
	s_nop 0
	v_readlane_b32 s6, v12, 0
	v_readlane_b32 s7, v12, 16
	v_readlane_b32 s8, v12, 32
	v_readlane_b32 s9, v12, 48
	s_add_i32 s6, s6, s7
	s_add_i32 s8, s8, s9
	s_add_i32 s6, s6, s57
	s_add_i32 s8, s6, s8
	s_cmpk_eq_i32 s8, 0x100
	s_cbranch_scc1 .Lrdx_eq
	s_cmpk_lt_i32 s8, 0x100
	s_cselect_b32 s6, -1, 0
	s_cselect_b32 s57, s8, s57
	s_xor_b32 s59, s58, s6
	v_bitop3_b32 v7, v7, v138, s59 bitop3:0x60
	v_bitop3_b32 v6, v6, v135, s59 bitop3:0x60
	v_bitop3_b32 v5, v5, v65, s59 bitop3:0x60
	v_bitop3_b32 v4, v4, v60, s59 bitop3:0x60
	v_bitop3_b32 v3, v3, v8, s6 bitop3:0xf8
	v_bitop3_b32 v2, v2, v9, s6 bitop3:0xf8
	v_bitop3_b32 v1, v1, v10, s6 bitop3:0xf8
	v_bitop3_b32 v0, v0, v11, s6 bitop3:0xf8
	v_bitop3_b32 v8, v7, v136, s58 bitop3:0x60
	v_bitop3_b32 v9, v6, v133, s58 bitop3:0x60
	v_bcnt_u32_b32 v12, v8, 0
	v_bitop3_b32 v10, v5, v63, s58 bitop3:0x60
	v_bcnt_u32_b32 v12, v9, v12
	v_bitop3_b32 v11, v4, v58, s58 bitop3:0x60
	v_bcnt_u32_b32 v12, v10, v12
	v_bcnt_u32_b32 v12, v11, v12
	s_nop 1
	v_add_u32_dpp v12, v12, v12 row_ror:8 row_mask:0xf bank_mask:0xf bound_ctrl:1
	s_nop 1
	v_add_u32_dpp v12, v12, v12 row_ror:4 row_mask:0xf bank_mask:0xf bound_ctrl:1
	s_nop 1
	v_add_u32_dpp v12, v12, v12 row_ror:2 row_mask:0xf bank_mask:0xf bound_ctrl:1
	s_nop 1
	v_add_u32_dpp v12, v12, v12 row_ror:1 row_mask:0xf bank_mask:0xf bound_ctrl:1
	s_nop 0
	v_readlane_b32 s6, v12, 0
	v_readlane_b32 s7, v12, 16
	v_readlane_b32 s8, v12, 32
	v_readlane_b32 s9, v12, 48
	s_add_i32 s6, s6, s7
	s_add_i32 s8, s8, s9
	s_add_i32 s6, s6, s57
	s_add_i32 s8, s6, s8
	s_cmpk_eq_i32 s8, 0x100
	s_cbranch_scc1 .Lrdx_eq
	s_cmpk_lt_i32 s8, 0x100
	s_cselect_b32 s6, -1, 0
	s_cselect_b32 s57, s8, s57
	s_xor_b32 s59, s58, s6
	v_bitop3_b32 v7, v7, v136, s59 bitop3:0x60
	v_bitop3_b32 v6, v6, v133, s59 bitop3:0x60
	v_bitop3_b32 v5, v5, v63, s59 bitop3:0x60
	v_bitop3_b32 v4, v4, v58, s59 bitop3:0x60
	v_bitop3_b32 v3, v3, v8, s6 bitop3:0xf8
	v_bitop3_b32 v2, v2, v9, s6 bitop3:0xf8
	v_bitop3_b32 v1, v1, v10, s6 bitop3:0xf8
	v_bitop3_b32 v0, v0, v11, s6 bitop3:0xf8
	v_bitop3_b32 v8, v7, v134, s58 bitop3:0x60
	v_bitop3_b32 v9, v6, v131, s58 bitop3:0x60
	v_bcnt_u32_b32 v12, v8, 0
	v_bitop3_b32 v10, v5, v61, s58 bitop3:0x60
	v_bcnt_u32_b32 v12, v9, v12
	v_bitop3_b32 v11, v4, v56, s58 bitop3:0x60
	v_bcnt_u32_b32 v12, v10, v12
	v_bcnt_u32_b32 v12, v11, v12
	s_nop 1
	v_add_u32_dpp v12, v12, v12 row_ror:8 row_mask:0xf bank_mask:0xf bound_ctrl:1
	s_nop 1
	v_add_u32_dpp v12, v12, v12 row_ror:4 row_mask:0xf bank_mask:0xf bound_ctrl:1
	s_nop 1
	v_add_u32_dpp v12, v12, v12 row_ror:2 row_mask:0xf bank_mask:0xf bound_ctrl:1
	s_nop 1
	v_add_u32_dpp v12, v12, v12 row_ror:1 row_mask:0xf bank_mask:0xf bound_ctrl:1
	s_nop 0
	v_readlane_b32 s6, v12, 0
	v_readlane_b32 s7, v12, 16
	v_readlane_b32 s8, v12, 32
	v_readlane_b32 s9, v12, 48
	s_add_i32 s6, s6, s7
	s_add_i32 s8, s8, s9
	s_add_i32 s6, s6, s57
	s_add_i32 s8, s6, s8
	s_cmpk_eq_i32 s8, 0x100
	s_cbranch_scc1 .Lrdx_eq
	s_cmpk_lt_i32 s8, 0x100
	s_cselect_b32 s6, -1, 0
	s_cselect_b32 s57, s8, s57
	s_xor_b32 s59, s58, s6
	v_bitop3_b32 v7, v7, v134, s59 bitop3:0x60
	v_bitop3_b32 v6, v6, v131, s59 bitop3:0x60
	v_bitop3_b32 v5, v5, v61, s59 bitop3:0x60
	v_bitop3_b32 v4, v4, v56, s59 bitop3:0x60
	v_bitop3_b32 v3, v3, v8, s6 bitop3:0xf8
	v_bitop3_b32 v2, v2, v9, s6 bitop3:0xf8
	v_bitop3_b32 v1, v1, v10, s6 bitop3:0xf8
	v_bitop3_b32 v0, v0, v11, s6 bitop3:0xf8
	v_bitop3_b32 v8, v7, v132, s58 bitop3:0x60
	v_bitop3_b32 v9, v6, v129, s58 bitop3:0x60
	v_bcnt_u32_b32 v12, v8, 0
	v_bitop3_b32 v10, v5, v59, s58 bitop3:0x60
	v_bcnt_u32_b32 v12, v9, v12
	v_bitop3_b32 v11, v4, v54, s58 bitop3:0x60
	v_bcnt_u32_b32 v12, v10, v12
	v_bcnt_u32_b32 v12, v11, v12
	s_nop 1
	v_add_u32_dpp v12, v12, v12 row_ror:8 row_mask:0xf bank_mask:0xf bound_ctrl:1
	s_nop 1
	v_add_u32_dpp v12, v12, v12 row_ror:4 row_mask:0xf bank_mask:0xf bound_ctrl:1
	s_nop 1
	v_add_u32_dpp v12, v12, v12 row_ror:2 row_mask:0xf bank_mask:0xf bound_ctrl:1
	s_nop 1
	v_add_u32_dpp v12, v12, v12 row_ror:1 row_mask:0xf bank_mask:0xf bound_ctrl:1
	s_nop 0
	v_readlane_b32 s6, v12, 0
	v_readlane_b32 s7, v12, 16
	v_readlane_b32 s8, v12, 32
	v_readlane_b32 s9, v12, 48
	s_add_i32 s6, s6, s7
	s_add_i32 s8, s8, s9
	s_add_i32 s6, s6, s57
	s_add_i32 s8, s6, s8
	s_cmpk_eq_i32 s8, 0x100
	s_cbranch_scc1 .Lrdx_eq
	s_cmpk_lt_i32 s8, 0x100
	s_cselect_b32 s6, -1, 0
	s_cselect_b32 s57, s8, s57
	s_xor_b32 s59, s58, s6
	v_bitop3_b32 v7, v7, v132, s59 bitop3:0x60
	v_bitop3_b32 v6, v6, v129, s59 bitop3:0x60
	v_bitop3_b32 v5, v5, v59, s59 bitop3:0x60
	v_bitop3_b32 v4, v4, v54, s59 bitop3:0x60
	v_bitop3_b32 v3, v3, v8, s6 bitop3:0xf8
	v_bitop3_b32 v2, v2, v9, s6 bitop3:0xf8
	v_bitop3_b32 v1, v1, v10, s6 bitop3:0xf8
	v_bitop3_b32 v0, v0, v11, s6 bitop3:0xf8
	v_bitop3_b32 v8, v7, v130, s58 bitop3:0x60
	v_bitop3_b32 v9, v6, v127, s58 bitop3:0x60
	v_bcnt_u32_b32 v12, v8, 0
	v_bitop3_b32 v10, v5, v57, s58 bitop3:0x60
	v_bcnt_u32_b32 v12, v9, v12
	v_bitop3_b32 v11, v4, v52, s58 bitop3:0x60
	v_bcnt_u32_b32 v12, v10, v12
	v_bcnt_u32_b32 v12, v11, v12
	s_nop 1
	v_add_u32_dpp v12, v12, v12 row_ror:8 row_mask:0xf bank_mask:0xf bound_ctrl:1
	s_nop 1
	v_add_u32_dpp v12, v12, v12 row_ror:4 row_mask:0xf bank_mask:0xf bound_ctrl:1
	s_nop 1
	v_add_u32_dpp v12, v12, v12 row_ror:2 row_mask:0xf bank_mask:0xf bound_ctrl:1
	s_nop 1
	v_add_u32_dpp v12, v12, v12 row_ror:1 row_mask:0xf bank_mask:0xf bound_ctrl:1
	s_nop 0
	v_readlane_b32 s6, v12, 0
	v_readlane_b32 s7, v12, 16
	v_readlane_b32 s8, v12, 32
	v_readlane_b32 s9, v12, 48
	s_add_i32 s6, s6, s7
	s_add_i32 s8, s8, s9
	s_add_i32 s6, s6, s57
	s_add_i32 s8, s6, s8
	s_cmpk_eq_i32 s8, 0x100
	s_cbranch_scc1 .Lrdx_eq
	s_cmpk_lt_i32 s8, 0x100
	s_cselect_b32 s6, -1, 0
	s_cselect_b32 s57, s8, s57
	s_xor_b32 s59, s58, s6
	v_bitop3_b32 v7, v7, v130, s59 bitop3:0x60
	v_bitop3_b32 v6, v6, v127, s59 bitop3:0x60
	v_bitop3_b32 v5, v5, v57, s59 bitop3:0x60
	v_bitop3_b32 v4, v4, v52, s59 bitop3:0x60
	v_bitop3_b32 v3, v3, v8, s6 bitop3:0xf8
	v_bitop3_b32 v2, v2, v9, s6 bitop3:0xf8
	v_bitop3_b32 v1, v1, v10, s6 bitop3:0xf8
	v_bitop3_b32 v0, v0, v11, s6 bitop3:0xf8
	v_bitop3_b32 v8, v7, v128, s58 bitop3:0x60
	v_bitop3_b32 v9, v6, v125, s58 bitop3:0x60
	v_bcnt_u32_b32 v12, v8, 0
	v_bitop3_b32 v10, v5, v55, s58 bitop3:0x60
	v_bcnt_u32_b32 v12, v9, v12
	v_bitop3_b32 v11, v4, v50, s58 bitop3:0x60
	v_bcnt_u32_b32 v12, v10, v12
	v_bcnt_u32_b32 v12, v11, v12
	s_nop 1
	v_add_u32_dpp v12, v12, v12 row_ror:8 row_mask:0xf bank_mask:0xf bound_ctrl:1
	s_nop 1
	v_add_u32_dpp v12, v12, v12 row_ror:4 row_mask:0xf bank_mask:0xf bound_ctrl:1
	s_nop 1
	v_add_u32_dpp v12, v12, v12 row_ror:2 row_mask:0xf bank_mask:0xf bound_ctrl:1
	s_nop 1
	v_add_u32_dpp v12, v12, v12 row_ror:1 row_mask:0xf bank_mask:0xf bound_ctrl:1
	s_nop 0
	v_readlane_b32 s6, v12, 0
	v_readlane_b32 s7, v12, 16
	v_readlane_b32 s8, v12, 32
	v_readlane_b32 s9, v12, 48
	s_add_i32 s6, s6, s7
	s_add_i32 s8, s8, s9
	s_add_i32 s6, s6, s57
	s_add_i32 s8, s6, s8
	s_cmpk_eq_i32 s8, 0x100
	s_cbranch_scc1 .Lrdx_eq
	s_cmpk_lt_i32 s8, 0x100
	s_cselect_b32 s6, -1, 0
	s_cselect_b32 s57, s8, s57
	s_xor_b32 s59, s58, s6
	v_bitop3_b32 v7, v7, v128, s59 bitop3:0x60
	v_bitop3_b32 v6, v6, v125, s59 bitop3:0x60
	v_bitop3_b32 v5, v5, v55, s59 bitop3:0x60
	v_bitop3_b32 v4, v4, v50, s59 bitop3:0x60
	v_bitop3_b32 v3, v3, v8, s6 bitop3:0xf8
	v_bitop3_b32 v2, v2, v9, s6 bitop3:0xf8
	v_bitop3_b32 v1, v1, v10, s6 bitop3:0xf8
	v_bitop3_b32 v0, v0, v11, s6 bitop3:0xf8
	v_bitop3_b32 v8, v7, v126, s58 bitop3:0x60
	v_bitop3_b32 v9, v6, v123, s58 bitop3:0x60
	v_bcnt_u32_b32 v12, v8, 0
	v_bitop3_b32 v10, v5, v53, s58 bitop3:0x60
	v_bcnt_u32_b32 v12, v9, v12
	v_bitop3_b32 v11, v4, v48, s58 bitop3:0x60
	v_bcnt_u32_b32 v12, v10, v12
	v_bcnt_u32_b32 v12, v11, v12
	s_nop 1
	v_add_u32_dpp v12, v12, v12 row_ror:8 row_mask:0xf bank_mask:0xf bound_ctrl:1
	s_nop 1
	v_add_u32_dpp v12, v12, v12 row_ror:4 row_mask:0xf bank_mask:0xf bound_ctrl:1
	s_nop 1
	v_add_u32_dpp v12, v12, v12 row_ror:2 row_mask:0xf bank_mask:0xf bound_ctrl:1
	s_nop 1
	v_add_u32_dpp v12, v12, v12 row_ror:1 row_mask:0xf bank_mask:0xf bound_ctrl:1
	s_nop 0
	v_readlane_b32 s6, v12, 0
	v_readlane_b32 s7, v12, 16
	v_readlane_b32 s8, v12, 32
	v_readlane_b32 s9, v12, 48
	s_add_i32 s6, s6, s7
	s_add_i32 s8, s8, s9
	s_add_i32 s6, s6, s57
	s_add_i32 s8, s6, s8
	s_cmpk_eq_i32 s8, 0x100
	s_cbranch_scc1 .Lrdx_eq
	s_cmpk_lt_i32 s8, 0x100
	s_cselect_b32 s6, -1, 0
	s_cselect_b32 s57, s8, s57
	s_xor_b32 s59, s58, s6
	v_bitop3_b32 v7, v7, v126, s59 bitop3:0x60
	v_bitop3_b32 v6, v6, v123, s59 bitop3:0x60
	v_bitop3_b32 v5, v5, v53, s59 bitop3:0x60
	v_bitop3_b32 v4, v4, v48, s59 bitop3:0x60
	v_bitop3_b32 v3, v3, v8, s6 bitop3:0xf8
	v_bitop3_b32 v2, v2, v9, s6 bitop3:0xf8
	v_bitop3_b32 v1, v1, v10, s6 bitop3:0xf8
	v_bitop3_b32 v0, v0, v11, s6 bitop3:0xf8
	v_bitop3_b32 v8, v7, v124, s58 bitop3:0x60
	v_bitop3_b32 v9, v6, v121, s58 bitop3:0x60
	v_bcnt_u32_b32 v12, v8, 0
	v_bitop3_b32 v10, v5, v51, s58 bitop3:0x60
	v_bcnt_u32_b32 v12, v9, v12
	v_bitop3_b32 v11, v4, v46, s58 bitop3:0x60
	v_bcnt_u32_b32 v12, v10, v12
	v_bcnt_u32_b32 v12, v11, v12
	s_nop 1
	v_add_u32_dpp v12, v12, v12 row_ror:8 row_mask:0xf bank_mask:0xf bound_ctrl:1
	s_nop 1
	v_add_u32_dpp v12, v12, v12 row_ror:4 row_mask:0xf bank_mask:0xf bound_ctrl:1
	s_nop 1
	v_add_u32_dpp v12, v12, v12 row_ror:2 row_mask:0xf bank_mask:0xf bound_ctrl:1
	s_nop 1
	v_add_u32_dpp v12, v12, v12 row_ror:1 row_mask:0xf bank_mask:0xf bound_ctrl:1
	s_nop 0
	v_readlane_b32 s6, v12, 0
	v_readlane_b32 s7, v12, 16
	v_readlane_b32 s8, v12, 32
	v_readlane_b32 s9, v12, 48
	s_add_i32 s6, s6, s7
	s_add_i32 s8, s8, s9
	s_add_i32 s6, s6, s57
	s_add_i32 s8, s6, s8
	s_cmpk_eq_i32 s8, 0x100
	s_cbranch_scc1 .Lrdx_eq
	s_cmpk_lt_i32 s8, 0x100
	s_cselect_b32 s6, -1, 0
	s_cselect_b32 s57, s8, s57
	s_xor_b32 s59, s58, s6
	v_bitop3_b32 v7, v7, v124, s59 bitop3:0x60
	v_bitop3_b32 v6, v6, v121, s59 bitop3:0x60
	v_bitop3_b32 v5, v5, v51, s59 bitop3:0x60
	v_bitop3_b32 v4, v4, v46, s59 bitop3:0x60
	v_bitop3_b32 v3, v3, v8, s6 bitop3:0xf8
	v_bitop3_b32 v2, v2, v9, s6 bitop3:0xf8
	v_bitop3_b32 v1, v1, v10, s6 bitop3:0xf8
	v_bitop3_b32 v0, v0, v11, s6 bitop3:0xf8
	v_bitop3_b32 v8, v7, v122, s58 bitop3:0x60
	v_bitop3_b32 v9, v6, v119, s58 bitop3:0x60
	v_bcnt_u32_b32 v12, v8, 0
	v_bitop3_b32 v10, v5, v49, s58 bitop3:0x60
	v_bcnt_u32_b32 v12, v9, v12
	v_bitop3_b32 v11, v4, v44, s58 bitop3:0x60
	v_bcnt_u32_b32 v12, v10, v12
	v_bcnt_u32_b32 v12, v11, v12
	s_nop 1
	v_add_u32_dpp v12, v12, v12 row_ror:8 row_mask:0xf bank_mask:0xf bound_ctrl:1
	s_nop 1
	v_add_u32_dpp v12, v12, v12 row_ror:4 row_mask:0xf bank_mask:0xf bound_ctrl:1
	s_nop 1
	v_add_u32_dpp v12, v12, v12 row_ror:2 row_mask:0xf bank_mask:0xf bound_ctrl:1
	s_nop 1
	v_add_u32_dpp v12, v12, v12 row_ror:1 row_mask:0xf bank_mask:0xf bound_ctrl:1
	s_nop 0
	v_readlane_b32 s6, v12, 0
	v_readlane_b32 s7, v12, 16
	v_readlane_b32 s8, v12, 32
	v_readlane_b32 s9, v12, 48
	s_add_i32 s6, s6, s7
	s_add_i32 s8, s8, s9
	s_add_i32 s6, s6, s57
	s_add_i32 s8, s6, s8
	s_cmpk_eq_i32 s8, 0x100
	s_cbranch_scc1 .Lrdx_eq
	s_cmpk_lt_i32 s8, 0x100
	s_cselect_b32 s6, -1, 0
	s_cselect_b32 s57, s8, s57
	s_xor_b32 s59, s58, s6
	v_bitop3_b32 v7, v7, v122, s59 bitop3:0x60
	v_bitop3_b32 v6, v6, v119, s59 bitop3:0x60
	v_bitop3_b32 v5, v5, v49, s59 bitop3:0x60
	v_bitop3_b32 v4, v4, v44, s59 bitop3:0x60
	v_bitop3_b32 v3, v3, v8, s6 bitop3:0xf8
	v_bitop3_b32 v2, v2, v9, s6 bitop3:0xf8
	v_bitop3_b32 v1, v1, v10, s6 bitop3:0xf8
	v_bitop3_b32 v0, v0, v11, s6 bitop3:0xf8
	v_bitop3_b32 v8, v7, v120, s58 bitop3:0x60
	v_bitop3_b32 v9, v6, v117, s58 bitop3:0x60
	v_bcnt_u32_b32 v12, v8, 0
	v_bitop3_b32 v10, v5, v47, s58 bitop3:0x60
	v_bcnt_u32_b32 v12, v9, v12
	v_bitop3_b32 v11, v4, v43, s58 bitop3:0x60
	v_bcnt_u32_b32 v12, v10, v12
	v_bcnt_u32_b32 v12, v11, v12
	s_nop 1
	v_add_u32_dpp v12, v12, v12 row_ror:8 row_mask:0xf bank_mask:0xf bound_ctrl:1
	s_nop 1
	v_add_u32_dpp v12, v12, v12 row_ror:4 row_mask:0xf bank_mask:0xf bound_ctrl:1
	s_nop 1
	v_add_u32_dpp v12, v12, v12 row_ror:2 row_mask:0xf bank_mask:0xf bound_ctrl:1
	s_nop 1
	v_add_u32_dpp v12, v12, v12 row_ror:1 row_mask:0xf bank_mask:0xf bound_ctrl:1
	s_nop 0
	v_readlane_b32 s6, v12, 0
	v_readlane_b32 s7, v12, 16
	v_readlane_b32 s8, v12, 32
	v_readlane_b32 s9, v12, 48
	s_add_i32 s6, s6, s7
	s_add_i32 s8, s8, s9
	s_add_i32 s6, s6, s57
	s_add_i32 s8, s6, s8
	s_cmpk_eq_i32 s8, 0x100
	s_cbranch_scc1 .Lrdx_eq
	s_cmpk_lt_i32 s8, 0x100
	s_cselect_b32 s6, -1, 0
	s_cselect_b32 s57, s8, s57
	s_xor_b32 s59, s58, s6
	v_bitop3_b32 v7, v7, v120, s59 bitop3:0x60
	v_bitop3_b32 v6, v6, v117, s59 bitop3:0x60
	v_bitop3_b32 v5, v5, v47, s59 bitop3:0x60
	v_bitop3_b32 v4, v4, v43, s59 bitop3:0x60
	v_bitop3_b32 v3, v3, v8, s6 bitop3:0xf8
	v_bitop3_b32 v2, v2, v9, s6 bitop3:0xf8
	v_bitop3_b32 v1, v1, v10, s6 bitop3:0xf8
	v_bitop3_b32 v0, v0, v11, s6 bitop3:0xf8
	v_bitop3_b32 v8, v7, v118, s58 bitop3:0x60
	v_bitop3_b32 v9, v6, v115, s58 bitop3:0x60
	v_bcnt_u32_b32 v12, v8, 0
	v_bitop3_b32 v10, v5, v45, s58 bitop3:0x60
	v_bcnt_u32_b32 v12, v9, v12
	v_bitop3_b32 v11, v4, v41, s58 bitop3:0x60
	v_bcnt_u32_b32 v12, v10, v12
	v_bcnt_u32_b32 v12, v11, v12
	s_nop 1
	v_add_u32_dpp v12, v12, v12 row_ror:8 row_mask:0xf bank_mask:0xf bound_ctrl:1
	s_nop 1
	v_add_u32_dpp v12, v12, v12 row_ror:4 row_mask:0xf bank_mask:0xf bound_ctrl:1
	s_nop 1
	v_add_u32_dpp v12, v12, v12 row_ror:2 row_mask:0xf bank_mask:0xf bound_ctrl:1
	s_nop 1
	v_add_u32_dpp v12, v12, v12 row_ror:1 row_mask:0xf bank_mask:0xf bound_ctrl:1
	s_nop 0
	v_readlane_b32 s6, v12, 0
	v_readlane_b32 s7, v12, 16
	v_readlane_b32 s8, v12, 32
	v_readlane_b32 s9, v12, 48
	s_add_i32 s6, s6, s7
	s_add_i32 s8, s8, s9
	s_add_i32 s6, s6, s57
	s_add_i32 s8, s6, s8
	s_cmpk_eq_i32 s8, 0x100
	s_cbranch_scc1 .Lrdx_eq
	s_cmpk_lt_i32 s8, 0x100
	s_cselect_b32 s6, -1, 0
	s_cselect_b32 s57, s8, s57
	s_xor_b32 s59, s58, s6
	v_bitop3_b32 v7, v7, v118, s59 bitop3:0x60
	v_bitop3_b32 v6, v6, v115, s59 bitop3:0x60
	v_bitop3_b32 v5, v5, v45, s59 bitop3:0x60
	v_bitop3_b32 v4, v4, v41, s59 bitop3:0x60
	v_bitop3_b32 v3, v3, v8, s6 bitop3:0xf8
	v_bitop3_b32 v2, v2, v9, s6 bitop3:0xf8
	v_bitop3_b32 v1, v1, v10, s6 bitop3:0xf8
	v_bitop3_b32 v0, v0, v11, s6 bitop3:0xf8
	v_bitop3_b32 v8, v7, v116, s58 bitop3:0x60
	v_bitop3_b32 v9, v6, v113, s58 bitop3:0x60
	v_bcnt_u32_b32 v12, v8, 0
	v_bitop3_b32 v10, v5, v42, s58 bitop3:0x60
	v_bcnt_u32_b32 v12, v9, v12
	v_bitop3_b32 v11, v4, v39, s58 bitop3:0x60
	v_bcnt_u32_b32 v12, v10, v12
	v_bcnt_u32_b32 v12, v11, v12
	s_nop 1
	v_add_u32_dpp v12, v12, v12 row_ror:8 row_mask:0xf bank_mask:0xf bound_ctrl:1
	s_nop 1
	v_add_u32_dpp v12, v12, v12 row_ror:4 row_mask:0xf bank_mask:0xf bound_ctrl:1
	s_nop 1
	v_add_u32_dpp v12, v12, v12 row_ror:2 row_mask:0xf bank_mask:0xf bound_ctrl:1
	s_nop 1
	v_add_u32_dpp v12, v12, v12 row_ror:1 row_mask:0xf bank_mask:0xf bound_ctrl:1
	s_nop 0
	v_readlane_b32 s6, v12, 0
	v_readlane_b32 s7, v12, 16
	v_readlane_b32 s8, v12, 32
	v_readlane_b32 s9, v12, 48
	s_add_i32 s6, s6, s7
	s_add_i32 s8, s8, s9
	s_add_i32 s6, s6, s57
	s_add_i32 s8, s6, s8
	s_cmpk_eq_i32 s8, 0x100
	s_cbranch_scc1 .Lrdx_eq
	s_cmpk_lt_i32 s8, 0x100
	s_cselect_b32 s6, -1, 0
	s_cselect_b32 s57, s8, s57
	s_xor_b32 s59, s58, s6
	v_bitop3_b32 v7, v7, v116, s59 bitop3:0x60
	v_bitop3_b32 v6, v6, v113, s59 bitop3:0x60
	v_bitop3_b32 v5, v5, v42, s59 bitop3:0x60
	v_bitop3_b32 v4, v4, v39, s59 bitop3:0x60
	v_bitop3_b32 v3, v3, v8, s6 bitop3:0xf8
	v_bitop3_b32 v2, v2, v9, s6 bitop3:0xf8
	v_bitop3_b32 v1, v1, v10, s6 bitop3:0xf8
	v_bitop3_b32 v0, v0, v11, s6 bitop3:0xf8
	v_bitop3_b32 v8, v7, v114, s58 bitop3:0x60
	v_bitop3_b32 v9, v6, v111, s58 bitop3:0x60
	v_bcnt_u32_b32 v12, v8, 0
	v_bitop3_b32 v10, v5, v40, s58 bitop3:0x60
	v_bcnt_u32_b32 v12, v9, v12
	v_bitop3_b32 v11, v4, v37, s58 bitop3:0x60
	v_bcnt_u32_b32 v12, v10, v12
	v_bcnt_u32_b32 v12, v11, v12
	s_nop 1
	v_add_u32_dpp v12, v12, v12 row_ror:8 row_mask:0xf bank_mask:0xf bound_ctrl:1
	s_nop 1
	v_add_u32_dpp v12, v12, v12 row_ror:4 row_mask:0xf bank_mask:0xf bound_ctrl:1
	s_nop 1
	v_add_u32_dpp v12, v12, v12 row_ror:2 row_mask:0xf bank_mask:0xf bound_ctrl:1
	s_nop 1
	v_add_u32_dpp v12, v12, v12 row_ror:1 row_mask:0xf bank_mask:0xf bound_ctrl:1
	s_nop 0
	v_readlane_b32 s6, v12, 0
	v_readlane_b32 s7, v12, 16
	v_readlane_b32 s8, v12, 32
	v_readlane_b32 s9, v12, 48
	s_add_i32 s6, s6, s7
	s_add_i32 s8, s8, s9
	s_add_i32 s6, s6, s57
	s_add_i32 s8, s6, s8
	s_cmpk_eq_i32 s8, 0x100
	s_cbranch_scc1 .Lrdx_eq
	s_cmpk_lt_i32 s8, 0x100
	s_cselect_b32 s6, -1, 0
	s_cselect_b32 s57, s8, s57
	s_xor_b32 s59, s58, s6
	v_bitop3_b32 v7, v7, v114, s59 bitop3:0x60
	v_bitop3_b32 v6, v6, v111, s59 bitop3:0x60
	v_bitop3_b32 v5, v5, v40, s59 bitop3:0x60
	v_bitop3_b32 v4, v4, v37, s59 bitop3:0x60
	v_bitop3_b32 v3, v3, v8, s6 bitop3:0xf8
	v_bitop3_b32 v2, v2, v9, s6 bitop3:0xf8
	v_bitop3_b32 v1, v1, v10, s6 bitop3:0xf8
	v_bitop3_b32 v0, v0, v11, s6 bitop3:0xf8
	v_bitop3_b32 v8, v7, v112, s58 bitop3:0x60
	v_bitop3_b32 v9, v6, v109, s58 bitop3:0x60
	v_bcnt_u32_b32 v12, v8, 0
	v_bitop3_b32 v10, v5, v38, s58 bitop3:0x60
	v_bcnt_u32_b32 v12, v9, v12
	v_bitop3_b32 v11, v4, v35, s58 bitop3:0x60
	v_bcnt_u32_b32 v12, v10, v12
	v_bcnt_u32_b32 v12, v11, v12
	s_nop 1
	v_add_u32_dpp v12, v12, v12 row_ror:8 row_mask:0xf bank_mask:0xf bound_ctrl:1
	s_nop 1
	v_add_u32_dpp v12, v12, v12 row_ror:4 row_mask:0xf bank_mask:0xf bound_ctrl:1
	s_nop 1
	v_add_u32_dpp v12, v12, v12 row_ror:2 row_mask:0xf bank_mask:0xf bound_ctrl:1
	s_nop 1
	v_add_u32_dpp v12, v12, v12 row_ror:1 row_mask:0xf bank_mask:0xf bound_ctrl:1
	s_nop 0
	v_readlane_b32 s6, v12, 0
	v_readlane_b32 s7, v12, 16
	v_readlane_b32 s8, v12, 32
	v_readlane_b32 s9, v12, 48
	s_add_i32 s6, s6, s7
	s_add_i32 s8, s8, s9
	s_add_i32 s6, s6, s57
	s_add_i32 s8, s6, s8
	s_cmpk_eq_i32 s8, 0x100
	s_cbranch_scc1 .Lrdx_eq
	s_cmpk_lt_i32 s8, 0x100
	s_cselect_b32 s6, -1, 0
	s_cselect_b32 s57, s8, s57
	s_xor_b32 s59, s58, s6
	v_bitop3_b32 v7, v7, v112, s59 bitop3:0x60
	v_bitop3_b32 v6, v6, v109, s59 bitop3:0x60
	v_bitop3_b32 v5, v5, v38, s59 bitop3:0x60
	v_bitop3_b32 v4, v4, v35, s59 bitop3:0x60
	v_bitop3_b32 v3, v3, v8, s6 bitop3:0xf8
	v_bitop3_b32 v2, v2, v9, s6 bitop3:0xf8
	v_bitop3_b32 v1, v1, v10, s6 bitop3:0xf8
	v_bitop3_b32 v0, v0, v11, s6 bitop3:0xf8
	v_bitop3_b32 v8, v7, v110, s58 bitop3:0x60
	v_bitop3_b32 v9, v6, v107, s58 bitop3:0x60
	v_bcnt_u32_b32 v12, v8, 0
	v_bitop3_b32 v10, v5, v36, s58 bitop3:0x60
	v_bcnt_u32_b32 v12, v9, v12
	v_bitop3_b32 v11, v4, v33, s58 bitop3:0x60
	v_bcnt_u32_b32 v12, v10, v12
	v_bcnt_u32_b32 v12, v11, v12
	s_nop 1
	v_add_u32_dpp v12, v12, v12 row_ror:8 row_mask:0xf bank_mask:0xf bound_ctrl:1
	s_nop 1
	v_add_u32_dpp v12, v12, v12 row_ror:4 row_mask:0xf bank_mask:0xf bound_ctrl:1
	s_nop 1
	v_add_u32_dpp v12, v12, v12 row_ror:2 row_mask:0xf bank_mask:0xf bound_ctrl:1
	s_nop 1
	v_add_u32_dpp v12, v12, v12 row_ror:1 row_mask:0xf bank_mask:0xf bound_ctrl:1
	s_nop 0
	v_readlane_b32 s6, v12, 0
	v_readlane_b32 s7, v12, 16
	v_readlane_b32 s8, v12, 32
	v_readlane_b32 s9, v12, 48
	s_add_i32 s6, s6, s7
	s_add_i32 s8, s8, s9
	s_add_i32 s6, s6, s57
	s_add_i32 s8, s6, s8
	s_cmpk_eq_i32 s8, 0x100
	s_cbranch_scc1 .Lrdx_eq
	s_cmpk_lt_i32 s8, 0x100
	s_cselect_b32 s6, -1, 0
	s_cselect_b32 s57, s8, s57
	s_xor_b32 s59, s58, s6
	v_bitop3_b32 v7, v7, v110, s59 bitop3:0x60
	v_bitop3_b32 v6, v6, v107, s59 bitop3:0x60
	v_bitop3_b32 v5, v5, v36, s59 bitop3:0x60
	v_bitop3_b32 v4, v4, v33, s59 bitop3:0x60
	v_bitop3_b32 v3, v3, v8, s6 bitop3:0xf8
	v_bitop3_b32 v2, v2, v9, s6 bitop3:0xf8
	v_bitop3_b32 v1, v1, v10, s6 bitop3:0xf8
	v_bitop3_b32 v0, v0, v11, s6 bitop3:0xf8
	v_bitop3_b32 v8, v7, v108, s58 bitop3:0x60
	v_bitop3_b32 v9, v6, v106, s58 bitop3:0x60
	v_bcnt_u32_b32 v12, v8, 0
	v_bitop3_b32 v10, v5, v34, s58 bitop3:0x60
	v_bcnt_u32_b32 v12, v9, v12
	v_bitop3_b32 v11, v4, v32, s58 bitop3:0x60
	v_bcnt_u32_b32 v12, v10, v12
	v_bcnt_u32_b32 v12, v11, v12
	s_nop 1
	v_add_u32_dpp v12, v12, v12 row_ror:8 row_mask:0xf bank_mask:0xf bound_ctrl:1
	s_nop 1
	v_add_u32_dpp v12, v12, v12 row_ror:4 row_mask:0xf bank_mask:0xf bound_ctrl:1
	s_nop 1
	v_add_u32_dpp v12, v12, v12 row_ror:2 row_mask:0xf bank_mask:0xf bound_ctrl:1
	s_nop 1
	v_add_u32_dpp v12, v12, v12 row_ror:1 row_mask:0xf bank_mask:0xf bound_ctrl:1
	s_nop 0
	v_readlane_b32 s6, v12, 0
	v_readlane_b32 s7, v12, 16
	v_readlane_b32 s8, v12, 32
	v_readlane_b32 s9, v12, 48
	s_add_i32 s6, s6, s7
	s_add_i32 s8, s8, s9
	s_add_i32 s6, s6, s57
	s_add_i32 s8, s6, s8
	s_cmpk_eq_i32 s8, 0x100
	s_cbranch_scc1 .Lrdx_eq
	s_cmpk_lt_i32 s8, 0x100
	s_cselect_b32 s6, -1, 0
	s_cselect_b32 s57, s8, s57
	s_xor_b32 s59, s58, s6
	v_bitop3_b32 v7, v7, v108, s59 bitop3:0x60
	v_bitop3_b32 v6, v6, v106, s59 bitop3:0x60
	v_bitop3_b32 v5, v5, v34, s59 bitop3:0x60
	v_bitop3_b32 v4, v4, v32, s59 bitop3:0x60
	v_bitop3_b32 v3, v3, v8, s6 bitop3:0xf8
	v_bitop3_b32 v2, v2, v9, s6 bitop3:0xf8
	v_bitop3_b32 v1, v1, v10, s6 bitop3:0xf8
	v_bitop3_b32 v0, v0, v11, s6 bitop3:0xf8
	s_branch .LBB0_1099
